# LayerNorm phases: waves 4-7 start about 3 us after waves 0-3 so one half's stores overlap the other half's loads
# baseline (speedup 1.0000x reference)
.LBB0_27:
	s_cselect_b32 s99, 1, 0
	v_readfirstlane_b32 s98, v206
	s_nop 3
	s_bitcmp1_b32 s98, 8
	s_cbranch_scc0 .Lln_stg_27
	s_sleep 100
.Lln_stg_27:
	s_cmp_eq_u32 s99, 1
	v_add_u32_e32 v1, s38, v32
	v_add_u32_e32 v2, s35, v32
	v_cmp_lt_i32_e32 vcc, s6, v1
	v_add_u32_e32 v0, 0xfffff000, v32
	v_add_u32_e32 v3, s33, v32
	v_cndmask_b32_e32 v88, v1, v32, vcc
	v_cmp_lt_i32_e32 vcc, s6, v2
	v_ashrrev_i32_e32 v4, 10, v0
	v_add_u32_e32 v1, 1, v4
	v_cndmask_b32_e32 v46, v2, v32, vcc
	v_cmp_lt_i32_e32 vcc, s6, v3
	v_add_u32_e32 v6, 0xfffff000, v88
	v_ashrrev_i32_e32 v5, 10, v6
	v_cndmask_b32_e32 v44, v3, v32, vcc
	v_cmp_gt_i32_e32 vcc, s2, v32
	s_waitcnt lgkmcnt(0)
	v_mov_b32_e32 v12, s87
	v_mov_b32_e32 v13, s85
	v_cndmask_b32_e64 v4, v1, 0, vcc
	v_mov_b32_e32 v14, s86
	v_mov_b32_e32 v15, s84
	v_cndmask_b32_e32 v1, 0, v33, vcc
	v_cndmask_b32_e32 v0, v0, v32, vcc
	v_add_u32_e32 v10, 1, v5
	v_mul_hi_i32_i24_e32 v5, 0x9000, v4
	v_mul_i32_i24_e32 v4, 0x9000, v4
	v_cndmask_b32_e32 v3, v12, v13, vcc
	v_cndmask_b32_e32 v2, v14, v15, vcc
	v_lshlrev_b64 v[0:1], 12, v[0:1]
	v_lshl_add_u64 v[4:5], s[60:61], 0, v[4:5]
	v_lshl_add_u64 v[0:1], v[2:3], 0, v[0:1]
	v_lshl_add_u64 v[90:91], v[4:5], 0, s[30:31]
	v_lshl_add_u64 v[92:93], v[4:5], 0, v[152:153]
	v_lshl_add_u64 v[0:1], v[0:1], 0, v[152:153]
	v_lshl_add_u64 v[4:5], v[90:91], 0, v[152:153]
	global_load_dwordx4 v[154:157], v[92:93], off offset:1024
	global_load_dwordx4 v[158:161], v[92:93], off offset:2048
	global_load_dwordx4 v[162:165], v[92:93], off offset:3072
	flat_load_dwordx4 v[48:51], v[92:93]
	global_load_dwordx4 v[166:169], v[4:5], off offset:1024
	global_load_dwordx4 v[170:173], v[4:5], off offset:2048
	global_load_dwordx4 v[174:177], v[4:5], off offset:3072
	flat_load_dwordx4 v[52:55], v[4:5]
	global_load_dwordx4 v[56:59], v[0:1], off
	v_add_u32_e32 v16, 0xfffff000, v44
	v_add_u32_e32 v8, 0xfffff000, v46
	v_ashrrev_i32_e32 v9, 10, v16
	v_ashrrev_i32_e32 v89, 31, v88
	v_ashrrev_i32_e32 v47, 31, v46
	v_ashrrev_i32_e32 v7, 10, v8
	v_cmp_gt_i32_e32 vcc, s2, v46
	v_add_u32_e32 v9, 1, v9
	v_cmp_gt_i32_e64 s[8:9], s2, v44
	v_cmp_gt_i32_e64 s[10:11], s2, v88
	v_ashrrev_i32_e32 v45, 31, v44
	v_add_u32_e32 v7, 1, v7
	v_cndmask_b32_e64 v100, v9, 0, s[8:9]
	v_cndmask_b32_e64 v3, 0, v89, s[10:11]
	v_cndmask_b32_e64 v2, v6, v88, s[10:11]
	v_cndmask_b32_e32 v9, 0, v47, vcc
	v_cndmask_b32_e32 v8, v8, v46, vcc
	v_cndmask_b32_e64 v98, v10, 0, s[10:11]
	v_cndmask_b32_e64 v99, v7, 0, vcc
	v_cndmask_b32_e64 v7, v12, v13, s[10:11]
	v_cndmask_b32_e64 v6, v14, v15, s[10:11]
	v_cndmask_b32_e32 v11, v12, v13, vcc
	v_cndmask_b32_e32 v10, v14, v15, vcc
	v_cndmask_b32_e64 v5, 0, v45, s[8:9]
	v_cndmask_b32_e64 v4, v16, v44, s[8:9]
	v_lshlrev_b64 v[2:3], 12, v[2:3]
	v_lshlrev_b64 v[8:9], 12, v[8:9]
	v_cndmask_b32_e64 v13, v12, v13, s[8:9]
	v_cndmask_b32_e64 v12, v14, v15, s[8:9]
	v_lshlrev_b64 v[4:5], 12, v[4:5]
	global_load_dwordx4 v[60:63], v[0:1], off offset:1024
	global_load_dwordx4 v[64:67], v[0:1], off offset:2048
	global_load_dwordx4 v[68:71], v[0:1], off offset:3072
	v_lshl_add_u64 v[0:1], v[6:7], 0, v[2:3]
	v_lshl_add_u64 v[2:3], v[10:11], 0, v[8:9]
	v_mov_b32_e32 v39, v153
	v_lshl_add_u64 v[4:5], v[12:13], 0, v[4:5]
	v_lshl_add_u64 v[0:1], v[0:1], 0, v[152:153]
	v_lshl_add_u64 v[2:3], v[2:3], 0, v[152:153]
	v_lshl_add_u64 v[94:95], v[90:91], 0, v[38:39]
	v_lshl_add_u64 v[96:97], v[4:5], 0, v[152:153]
	global_load_dwordx4 v[72:75], v[0:1], off
	global_load_dwordx4 v[76:79], v[0:1], off offset:1024
	global_load_dwordx4 v[80:83], v[0:1], off offset:2048
	global_load_dwordx4 v[84:87], v[0:1], off offset:3072
	global_load_dwordx4 v[28:31], v[2:3], off
	global_load_dwordx4 v[24:27], v[2:3], off offset:1024
	global_load_dwordx4 v[20:23], v[2:3], off offset:2048
	global_load_dwordx4 v[16:19], v[2:3], off offset:3072
	global_load_dwordx4 v[12:15], v[96:97], off
	global_load_dwordx4 v[8:11], v[96:97], off offset:1024
	global_load_dwordx4 v[4:7], v[96:97], off offset:2048
	s_nop 0
	global_load_dwordx4 v[0:3], v[96:97], off offset:3072
	v_mov_b32_e32 v41, v153
	v_mov_b32_e32 v43, v153
	v_lshlrev_b64 v[46:47], 11, v[46:47]
	v_lshl_add_u64 v[32:33], v[32:33], 0, s[96:97]
	v_cmp_lt_i32_e32 vcc, s6, v32
	s_or_b64 s[16:17], vcc, s[16:17]
	s_waitcnt vmcnt(0) lgkmcnt(0)
	v_pk_add_f32 v[54:55], v[54:55], 1.0 op_sel_hi:[1,0]
	v_pk_add_f32 v[52:53], v[52:53], 1.0 op_sel_hi:[1,0]
	v_pk_fma_f32 v[50:51], v[58:59], v[54:55], v[50:51]
	v_pk_fma_f32 v[48:49], v[56:57], v[52:53], v[48:49]
	v_lshl_add_u64 v[56:57], v[90:91], 0, v[40:41]
	v_cvt_pk_bf16_f32 v48, v48, v49
	v_cvt_pk_bf16_f32 v49, v50, v51
	flat_store_dwordx2 v[36:37], v[48:49]
	v_mov_b64_e32 v[48:49], v[166:167]
	v_mov_b64_e32 v[50:51], v[168:169]
	s_nop 0
	v_mov_b64_e32 v[52:53], v[154:155]
	v_mov_b64_e32 v[54:55], v[156:157]
	v_pk_add_f32 v[50:51], v[50:51], 1.0 op_sel_hi:[1,0]
	v_pk_add_f32 v[48:49], v[48:49], 1.0 op_sel_hi:[1,0]
	v_pk_fma_f32 v[50:51], v[62:63], v[50:51], v[54:55]
	v_pk_fma_f32 v[48:49], v[60:61], v[48:49], v[52:53]
	s_nop 0
	v_cvt_pk_bf16_f32 v48, v48, v49
	v_cvt_pk_bf16_f32 v49, v50, v51
	flat_store_dwordx2 v[36:37], v[48:49] offset:512
	v_mov_b64_e32 v[48:49], v[170:171]
	v_mov_b64_e32 v[50:51], v[172:173]
	s_nop 0
	v_mov_b64_e32 v[52:53], v[158:159]
	v_mov_b64_e32 v[54:55], v[160:161]
	v_lshl_add_u64 v[56:57], v[90:91], 0, v[42:43]
	v_pk_add_f32 v[50:51], v[50:51], 1.0 op_sel_hi:[1,0]
	v_pk_add_f32 v[48:49], v[48:49], 1.0 op_sel_hi:[1,0]
	v_pk_fma_f32 v[50:51], v[66:67], v[50:51], v[54:55]
	v_pk_fma_f32 v[48:49], v[64:65], v[48:49], v[52:53]
	s_nop 0
	v_cvt_pk_bf16_f32 v48, v48, v49
	v_cvt_pk_bf16_f32 v49, v50, v51
	flat_store_dwordx2 v[36:37], v[48:49] offset:1024
	v_mov_b64_e32 v[48:49], v[174:175]
	v_mov_b64_e32 v[50:51], v[176:177]
	s_nop 0
	v_mov_b64_e32 v[52:53], v[162:163]
	v_mov_b64_e32 v[54:55], v[164:165]
	v_mul_hi_i32_i24_e32 v57, 0x9000, v98
	v_mul_i32_i24_e32 v56, 0x9000, v98
	v_lshl_add_u64 v[56:57], s[60:61], 0, v[56:57]
	v_lshl_add_u64 v[58:59], v[56:57], 0, s[30:31]
	v_lshl_add_u64 v[60:61], v[58:59], 0, v[152:153]
	v_lshl_add_u64 v[56:57], v[56:57], 0, v[152:153]
	v_lshl_add_u64 v[62:63], v[58:59], 0, v[38:39]
	v_pk_add_f32 v[50:51], v[50:51], 1.0 op_sel_hi:[1,0]
	v_pk_add_f32 v[48:49], v[48:49], 1.0 op_sel_hi:[1,0]
	v_pk_fma_f32 v[50:51], v[70:71], v[50:51], v[54:55]
	v_pk_fma_f32 v[48:49], v[68:69], v[48:49], v[52:53]
	s_nop 0
	v_cvt_pk_bf16_f32 v48, v48, v49
	v_cvt_pk_bf16_f32 v49, v50, v51
	flat_store_dwordx2 v[36:37], v[48:49] offset:1536
	global_load_dwordx4 v[154:157], v[60:61], off offset:1024
	global_load_dwordx4 v[158:161], v[60:61], off offset:2048
	global_load_dwordx4 v[162:165], v[60:61], off offset:3072
	flat_load_dwordx4 v[48:51], v[60:61]
	s_nop 0
	global_load_dwordx4 v[166:169], v[56:57], off offset:1024
	global_load_dwordx4 v[170:173], v[56:57], off offset:2048
	global_load_dwordx4 v[174:177], v[56:57], off offset:3072
	flat_load_dwordx4 v[52:55], v[56:57]
	v_lshlrev_b64 v[60:61], 11, v[88:89]
	v_lshl_add_u64 v[60:61], v[34:35], 0, v[60:61]
	v_lshl_add_u64 v[36:37], v[36:37], 0, s[22:23]
	s_waitcnt vmcnt(0) lgkmcnt(0)
	v_pk_add_f32 v[50:51], v[50:51], 1.0 op_sel_hi:[1,0]
	v_pk_add_f32 v[48:49], v[48:49], 1.0 op_sel_hi:[1,0]
	v_pk_fma_f32 v[50:51], v[74:75], v[50:51], v[54:55]
	v_pk_fma_f32 v[48:49], v[72:73], v[48:49], v[52:53]
	s_nop 0
	v_cvt_pk_bf16_f32 v48, v48, v49
	v_cvt_pk_bf16_f32 v49, v50, v51
	flat_store_dwordx2 v[60:61], v[48:49]
	v_mov_b64_e32 v[48:49], v[154:155]
	v_mov_b64_e32 v[50:51], v[156:157]
	s_nop 0
	v_mov_b64_e32 v[52:53], v[166:167]
	v_mov_b64_e32 v[54:55], v[168:169]
	v_lshl_add_u64 v[62:63], v[58:59], 0, v[40:41]
	v_lshl_add_u64 v[58:59], v[58:59], 0, v[42:43]
	v_pk_add_f32 v[50:51], v[50:51], 1.0 op_sel_hi:[1,0]
	v_pk_add_f32 v[48:49], v[48:49], 1.0 op_sel_hi:[1,0]
	v_pk_fma_f32 v[50:51], v[78:79], v[50:51], v[54:55]
	v_pk_fma_f32 v[48:49], v[76:77], v[48:49], v[52:53]
	s_nop 0
	v_cvt_pk_bf16_f32 v48, v48, v49
	v_cvt_pk_bf16_f32 v49, v50, v51
	flat_store_dwordx2 v[60:61], v[48:49] offset:512
	v_mov_b64_e32 v[48:49], v[158:159]
	v_mov_b64_e32 v[50:51], v[160:161]
	s_nop 0
	v_mov_b64_e32 v[52:53], v[170:171]
	v_mov_b64_e32 v[54:55], v[172:173]
	v_pk_add_f32 v[50:51], v[50:51], 1.0 op_sel_hi:[1,0]
	v_pk_add_f32 v[48:49], v[48:49], 1.0 op_sel_hi:[1,0]
	v_pk_fma_f32 v[50:51], v[82:83], v[50:51], v[54:55]
	v_pk_fma_f32 v[48:49], v[80:81], v[48:49], v[52:53]
	s_nop 0
	v_cvt_pk_bf16_f32 v48, v48, v49
	v_cvt_pk_bf16_f32 v49, v50, v51
	flat_store_dwordx2 v[60:61], v[48:49] offset:1024
	v_mov_b64_e32 v[48:49], v[162:163]
	v_mov_b64_e32 v[50:51], v[164:165]
	s_nop 0
	v_mov_b64_e32 v[52:53], v[174:175]
	v_mov_b64_e32 v[54:55], v[176:177]
	v_mul_hi_i32_i24_e32 v57, 0x9000, v99
	v_mul_i32_i24_e32 v56, 0x9000, v99
	v_lshl_add_u64 v[56:57], s[60:61], 0, v[56:57]
	v_lshl_add_u64 v[58:59], v[56:57], 0, s[30:31]
	v_lshl_add_u64 v[62:63], v[58:59], 0, v[152:153]
	v_lshl_add_u64 v[56:57], v[56:57], 0, v[152:153]
	v_pk_add_f32 v[50:51], v[50:51], 1.0 op_sel_hi:[1,0]
	v_pk_add_f32 v[48:49], v[48:49], 1.0 op_sel_hi:[1,0]
	v_pk_fma_f32 v[50:51], v[86:87], v[50:51], v[54:55]
	v_pk_fma_f32 v[48:49], v[84:85], v[48:49], v[52:53]
	s_nop 0
	v_cvt_pk_bf16_f32 v48, v48, v49
	v_cvt_pk_bf16_f32 v49, v50, v51
	flat_store_dwordx2 v[60:61], v[48:49] offset:1536
	global_load_dwordx4 v[154:157], v[62:63], off offset:1024
	global_load_dwordx4 v[158:161], v[62:63], off offset:2048
	global_load_dwordx4 v[162:165], v[62:63], off offset:3072
	flat_load_dwordx4 v[48:51], v[62:63]
	s_nop 0
	global_load_dwordx4 v[166:169], v[56:57], off offset:1024
	global_load_dwordx4 v[170:173], v[56:57], off offset:2048
	global_load_dwordx4 v[174:177], v[56:57], off offset:3072
	flat_load_dwordx4 v[52:55], v[56:57]
	v_lshl_add_u64 v[60:61], v[34:35], 0, v[46:47]
	v_lshl_add_u64 v[46:47], v[58:59], 0, v[38:39]
	s_waitcnt vmcnt(0) lgkmcnt(0)
	v_pk_add_f32 v[50:51], v[50:51], 1.0 op_sel_hi:[1,0]
	v_pk_add_f32 v[48:49], v[48:49], 1.0 op_sel_hi:[1,0]
	v_pk_fma_f32 v[30:31], v[30:31], v[50:51], v[54:55]
	v_pk_fma_f32 v[28:29], v[28:29], v[48:49], v[52:53]
	v_lshl_add_u64 v[50:51], v[58:59], 0, v[40:41]
	v_cvt_pk_bf16_f32 v28, v28, v29
	v_cvt_pk_bf16_f32 v29, v30, v31
	flat_store_dwordx2 v[60:61], v[28:29]
	v_mov_b64_e32 v[28:29], v[154:155]
	v_mov_b64_e32 v[30:31], v[156:157]
	s_nop 0
	v_mov_b64_e32 v[46:47], v[166:167]
	v_mov_b64_e32 v[48:49], v[168:169]
	v_pk_add_f32 v[30:31], v[30:31], 1.0 op_sel_hi:[1,0]
	v_pk_add_f32 v[28:29], v[28:29], 1.0 op_sel_hi:[1,0]
	v_pk_fma_f32 v[26:27], v[26:27], v[30:31], v[48:49]
	v_pk_fma_f32 v[24:25], v[24:25], v[28:29], v[46:47]
	v_lshl_add_u64 v[46:47], v[58:59], 0, v[42:43]
	v_cvt_pk_bf16_f32 v24, v24, v25
	v_cvt_pk_bf16_f32 v25, v26, v27
	flat_store_dwordx2 v[60:61], v[24:25] offset:512
	v_mov_b64_e32 v[24:25], v[158:159]
	v_mov_b64_e32 v[26:27], v[160:161]
	s_nop 0
	v_mov_b64_e32 v[28:29], v[170:171]
	v_mov_b64_e32 v[30:31], v[172:173]
	v_pk_add_f32 v[26:27], v[26:27], 1.0 op_sel_hi:[1,0]
	v_pk_add_f32 v[24:25], v[24:25], 1.0 op_sel_hi:[1,0]
	v_pk_fma_f32 v[22:23], v[22:23], v[26:27], v[30:31]
	v_pk_fma_f32 v[20:21], v[20:21], v[24:25], v[28:29]
	v_mul_hi_i32_i24_e32 v29, 0x9000, v100
	v_cvt_pk_bf16_f32 v20, v20, v21
	v_cvt_pk_bf16_f32 v21, v22, v23
	flat_store_dwordx2 v[60:61], v[20:21] offset:1024
	v_mov_b64_e32 v[20:21], v[162:163]
	v_mov_b64_e32 v[22:23], v[164:165]
	s_nop 0
	v_mov_b64_e32 v[24:25], v[174:175]
	v_mov_b64_e32 v[26:27], v[176:177]
	v_mul_i32_i24_e32 v28, 0x9000, v100
	v_lshl_add_u64 v[28:29], s[60:61], 0, v[28:29]
	v_lshl_add_u64 v[30:31], v[28:29], 0, s[30:31]
	v_lshl_add_u64 v[46:47], v[30:31], 0, v[152:153]
	v_lshl_add_u64 v[28:29], v[28:29], 0, v[152:153]
	v_pk_add_f32 v[22:23], v[22:23], 1.0 op_sel_hi:[1,0]
	v_pk_add_f32 v[20:21], v[20:21], 1.0 op_sel_hi:[1,0]
	v_pk_fma_f32 v[18:19], v[18:19], v[22:23], v[26:27]
	v_pk_fma_f32 v[16:17], v[16:17], v[20:21], v[24:25]
	v_lshlrev_b64 v[24:25], 11, v[44:45]
	v_cvt_pk_bf16_f32 v16, v16, v17
	v_cvt_pk_bf16_f32 v17, v18, v19
	flat_store_dwordx2 v[60:61], v[16:17] offset:1536
	global_load_dwordx4 v[154:157], v[46:47], off offset:1024
	global_load_dwordx4 v[158:161], v[46:47], off offset:2048
	global_load_dwordx4 v[162:165], v[46:47], off offset:3072
	flat_load_dwordx4 v[16:19], v[46:47]
	s_nop 0
	global_load_dwordx4 v[166:169], v[28:29], off offset:1024
	global_load_dwordx4 v[170:173], v[28:29], off offset:2048
	global_load_dwordx4 v[174:177], v[28:29], off offset:3072
	flat_load_dwordx4 v[20:23], v[28:29]
	v_lshl_add_u64 v[24:25], v[34:35], 0, v[24:25]
	v_lshl_add_u64 v[26:27], v[30:31], 0, v[38:39]
	s_waitcnt vmcnt(0) lgkmcnt(0)
	v_pk_add_f32 v[18:19], v[18:19], 1.0 op_sel_hi:[1,0]
	v_pk_add_f32 v[16:17], v[16:17], 1.0 op_sel_hi:[1,0]
	v_pk_fma_f32 v[14:15], v[14:15], v[18:19], v[22:23]
	v_pk_fma_f32 v[12:13], v[12:13], v[16:17], v[20:21]
	v_lshl_add_u64 v[20:21], v[30:31], 0, v[40:41]
	v_cvt_pk_bf16_f32 v12, v12, v13
	v_cvt_pk_bf16_f32 v13, v14, v15
	flat_store_dwordx2 v[24:25], v[12:13]
	v_mov_b64_e32 v[12:13], v[154:155]
	v_mov_b64_e32 v[14:15], v[156:157]
	s_nop 0
	v_mov_b64_e32 v[16:17], v[166:167]
	v_mov_b64_e32 v[18:19], v[168:169]
	v_pk_add_f32 v[14:15], v[14:15], 1.0 op_sel_hi:[1,0]
	v_pk_add_f32 v[12:13], v[12:13], 1.0 op_sel_hi:[1,0]
	v_pk_fma_f32 v[10:11], v[10:11], v[14:15], v[18:19]
	v_pk_fma_f32 v[8:9], v[8:9], v[12:13], v[16:17]
	v_lshl_add_u64 v[16:17], v[30:31], 0, v[42:43]
	v_cvt_pk_bf16_f32 v8, v8, v9
	v_cvt_pk_bf16_f32 v9, v10, v11
	flat_store_dwordx2 v[24:25], v[8:9] offset:512
	v_mov_b64_e32 v[8:9], v[158:159]
	v_mov_b64_e32 v[10:11], v[160:161]
	s_nop 0
	v_mov_b64_e32 v[12:13], v[170:171]
	v_mov_b64_e32 v[14:15], v[172:173]
	v_pk_add_f32 v[10:11], v[10:11], 1.0 op_sel_hi:[1,0]
	v_pk_add_f32 v[8:9], v[8:9], 1.0 op_sel_hi:[1,0]
	v_pk_fma_f32 v[6:7], v[6:7], v[10:11], v[14:15]
	v_pk_fma_f32 v[4:5], v[4:5], v[8:9], v[12:13]
	s_nop 0
	v_cvt_pk_bf16_f32 v4, v4, v5
	v_cvt_pk_bf16_f32 v5, v6, v7
	flat_store_dwordx2 v[24:25], v[4:5] offset:1024
	v_mov_b64_e32 v[4:5], v[162:163]
	v_mov_b64_e32 v[6:7], v[164:165]
	s_nop 0
	v_mov_b64_e32 v[8:9], v[174:175]
	v_mov_b64_e32 v[10:11], v[176:177]
	v_pk_add_f32 v[6:7], v[6:7], 1.0 op_sel_hi:[1,0]
	v_pk_add_f32 v[4:5], v[4:5], 1.0 op_sel_hi:[1,0]
	v_pk_fma_f32 v[2:3], v[2:3], v[6:7], v[10:11]
	v_pk_fma_f32 v[0:1], v[0:1], v[4:5], v[8:9]
	s_nop 0
	v_cvt_pk_bf16_f32 v0, v0, v1
	v_cvt_pk_bf16_f32 v1, v2, v3
	flat_store_dwordx2 v[24:25], v[0:1] offset:1536
	s_andn2_b64 exec, exec, s[16:17]
	s_cbranch_execnz .LBB0_27

.Lln_stg_51:
	s_cmp_eq_u32 s99, 1
	global_load_dwordx4 v[154:157], v[74:75], off
	global_load_dwordx4 v[158:161], v[76:77], off
	global_load_dwordx4 v[162:165], v[74:75], off offset:1024
	global_load_dwordx4 v[166:169], v[76:77], off offset:1024
	global_load_dwordx4 v[170:173], v[74:75], off offset:2048
	global_load_dwordx4 v[174:177], v[76:77], off offset:2048
	global_load_dwordx4 v[178:181], v[74:75], off offset:3072
	global_load_dwordx4 v[182:185], v[76:77], off offset:3072
	v_add_u32_e32 v0, 0xfffff000, v64
	v_ashrrev_i32_e32 v0, 10, v0
	v_add_u32_e32 v0, 1, v0
	v_cmp_lt_i32_e32 vcc, s33, v64
	s_mov_b32 s2, 0x1000000
	global_load_dwordx4 v[186:189], v[86:87], off offset:1024
	global_load_dwordx4 v[190:193], v[86:87], off offset:2048
	global_load_dwordx4 v[194:197], v[86:87], off offset:3072
	flat_load_dwordx4 v[8:11], v[86:87]
	v_cndmask_b32_e32 v4, 0, v0, vcc
	v_add_u32_e32 v0, s38, v64
	v_cmp_lt_i32_e32 vcc, s6, v0
	v_ashrrev_i32_e32 v5, 31, v4
	v_lshl_add_u64 v[88:89], v[4:5], 0, s[28:29]
	v_cndmask_b32_e32 v0, v0, v64, vcc
	v_add_u32_e32 v1, 0xfffff000, v0
	v_ashrrev_i32_e32 v1, 10, v1
	v_add_u32_e32 v1, 1, v1
	v_cmp_lt_i32_e32 vcc, s33, v0
	v_mad_u64_u32 v[4:5], s[4:5], v88, s7, v[78:79]
	s_nop 0
	v_cndmask_b32_e32 v2, 0, v1, vcc
	v_add_u32_e32 v1, s35, v64
	v_cmp_lt_i32_e32 vcc, s6, v1
	v_mad_i32_i24 v5, v89, s7, v5
	global_load_dwordx4 v[198:201], v[4:5], off offset:1024
	global_load_dwordx4 v[202:205], v[4:5], off offset:2048
	global_load_dwordx4 v[224:227], v[4:5], off offset:3072
	flat_load_dwordx4 v[12:15], v[4:5]
	v_cndmask_b32_e32 v40, v1, v64, vcc
	v_add_u32_e32 v1, 0xfffff000, v40
	v_ashrrev_i32_e32 v1, 10, v1
	v_add_u32_e32 v1, 1, v1
	v_cmp_lt_i32_e32 vcc, s33, v40
	v_ashrrev_i32_e32 v3, 31, v2
	v_lshl_add_u64 v[92:93], v[2:3], 0, s[28:29]
	v_cndmask_b32_e32 v42, 0, v1, vcc
	v_add_u32_e32 v1, s26, v64
	v_cmp_lt_i32_e32 vcc, s6, v1
	s_mov_b64 s[8:9], 0x1000000
	v_mad_u64_u32 v[48:49], s[4:5], v92, s7, v[78:79]
	v_cndmask_b32_e32 v20, v1, v64, vcc
	v_add_u32_e32 v1, 0xfffff000, v20
	v_ashrrev_i32_e32 v1, 10, v1
	v_add_u32_e32 v1, 1, v1
	v_cmp_lt_i32_e32 vcc, s33, v20
	v_lshlrev_b32_e32 v152, 1, v66
	v_mad_i32_i24 v49, v93, s7, v49
	v_cndmask_b32_e32 v22, 0, v1, vcc
	v_add_co_u32_e32 v6, vcc, s2, v84
	s_brev_b32 s2, 64
	s_nop 0
	v_addc_co_u32_e32 v7, vcc, 0, v85, vcc
	v_add_co_u32_e32 v24, vcc, s2, v84
	global_load_dwordx2 v[228:229], v[6:7], off offset:512
	global_load_dwordx2 v[230:231], v[6:7], off offset:1024
	global_load_dwordx2 v[232:233], v[6:7], off offset:1536
	flat_load_dwordx2 v[16:17], v[6:7]
	s_nop 0
	v_addc_co_u32_e32 v25, vcc, 0, v85, vcc
	global_load_dwordx2 v[234:235], v[24:25], off offset:512
	global_load_dwordx2 v[236:237], v[24:25], off offset:1024
	global_load_dwordx2 v[238:239], v[24:25], off offset:1536
	flat_load_dwordx2 v[26:27], v[24:25]
	v_lshlrev_b32_e32 v104, 1, v68
	v_mov_b32_e32 v105, v153
	v_lshlrev_b32_e32 v106, 1, v70
	v_mov_b32_e32 v107, v153
	v_lshlrev_b32_e32 v120, 1, v72
	v_mov_b32_e32 v121, v153
	v_ashrrev_i32_e32 v41, 31, v40
	v_ashrrev_i32_e32 v43, 31, v42
	v_lshlrev_b64 v[96:97], 11, v[40:41]
	v_lshl_add_u64 v[98:99], v[42:43], 0, s[28:29]
	v_lshl_add_u64 v[42:43], s[56:57], 0, v[96:97]
	v_ashrrev_i32_e32 v21, 31, v20
	v_ashrrev_i32_e32 v23, 31, v22
	s_mov_b32 s2, 0x3727c5ac
	s_waitcnt vmcnt(0) lgkmcnt(0)
	v_lshlrev_b32_e32 v18, 16, v16
	v_and_b32_e32 v19, 0xffff0000, v16
	v_lshlrev_b32_e32 v16, 16, v17
	v_and_b32_e32 v17, 0xffff0000, v17
	v_lshlrev_b32_e32 v28, 16, v26
	v_and_b32_e32 v29, 0xffff0000, v26
	v_lshlrev_b32_e32 v26, 16, v27
	v_and_b32_e32 v27, 0xffff0000, v27
	v_pk_add_f32 v[18:19], v[18:19], v[28:29]
	v_pk_add_f32 v[16:17], v[16:17], v[26:27]
	v_pk_mul_f32 v[12:13], v[12:13], v[18:19]
	v_pk_mul_f32 v[14:15], v[14:15], v[16:17]
	v_pk_fma_f32 v[8:9], v[8:9], s[42:43], v[12:13] op_sel_hi:[1,0,1]
	v_pk_fma_f32 v[10:11], v[10:11], s[42:43], v[14:15] op_sel_hi:[1,0,1]
	v_mov_b32_e32 v14, v8
	v_pk_mov_b32 v[12:13], v[8:9], v[10:11] op_sel:[1,0]
	v_mov_b32_e32 v15, v11
	v_pk_add_f32 v[12:13], v[12:13], v[14:15]
	s_nop 0
	v_add_f32_e32 v1, v12, v13
	v_mov_b64_e32 v[12:13], v[186:187]
	v_mov_b64_e32 v[14:15], v[188:189]
	v_mov_b64_e32 v[16:17], v[198:199]
	v_mov_b64_e32 v[18:19], v[200:201]
	v_mov_b64_e32 v[26:27], v[228:229]
	v_mov_b64_e32 v[32:33], v[234:235]
	v_add_f32_e32 v28, 0, v1
	v_ashrrev_i32_e32 v1, 31, v0
	v_lshlrev_b64 v[90:91], 11, v[0:1]
	v_lshlrev_b64 v[2:3], 12, v[0:1]
	v_lshlrev_b32_e32 v30, 16, v26
	v_and_b32_e32 v31, 0xffff0000, v26
	v_lshlrev_b32_e32 v26, 16, v27
	v_and_b32_e32 v27, 0xffff0000, v27
	v_lshlrev_b32_e32 v34, 16, v32
	v_and_b32_e32 v35, 0xffff0000, v32
	v_lshlrev_b32_e32 v32, 16, v33
	v_and_b32_e32 v33, 0xffff0000, v33
	v_pk_add_f32 v[30:31], v[30:31], v[34:35]
	v_pk_add_f32 v[26:27], v[26:27], v[32:33]
	v_pk_mul_f32 v[16:17], v[16:17], v[30:31]
	v_pk_mul_f32 v[18:19], v[18:19], v[26:27]
	v_pk_fma_f32 v[12:13], v[12:13], s[42:43], v[16:17] op_sel_hi:[1,0,1]
	v_pk_fma_f32 v[14:15], v[14:15], s[42:43], v[18:19] op_sel_hi:[1,0,1]
	v_mov_b32_e32 v18, v12
	v_pk_mov_b32 v[16:17], v[12:13], v[14:15] op_sel:[1,0]
	v_mov_b32_e32 v19, v15
	v_pk_add_f32 v[16:17], v[16:17], v[18:19]
	s_nop 0
	v_pk_add_f32 v[30:31], v[16:17], v[16:17] op_sel:[0,1] op_sel_hi:[1,0]
	v_mov_b64_e32 v[16:17], v[190:191]
	v_mov_b64_e32 v[18:19], v[192:193]
	v_mov_b64_e32 v[32:33], v[202:203]
	v_mov_b64_e32 v[34:35], v[204:205]
	v_mov_b64_e32 v[26:27], v[230:231]
	v_mov_b64_e32 v[38:39], v[236:237]
	v_lshlrev_b32_e32 v36, 16, v26
	v_and_b32_e32 v37, 0xffff0000, v26
	v_lshlrev_b32_e32 v44, 16, v38
	v_and_b32_e32 v45, 0xffff0000, v38
	v_lshlrev_b32_e32 v26, 16, v27
	v_and_b32_e32 v27, 0xffff0000, v27
	v_lshlrev_b32_e32 v38, 16, v39
	v_and_b32_e32 v39, 0xffff0000, v39
	v_pk_add_f32 v[36:37], v[36:37], v[44:45]
	v_pk_add_f32 v[26:27], v[26:27], v[38:39]
	v_pk_mul_f32 v[32:33], v[32:33], v[36:37]
	v_pk_mul_f32 v[26:27], v[34:35], v[26:27]
	v_pk_fma_f32 v[16:17], v[16:17], s[42:43], v[32:33] op_sel_hi:[1,0,1]
	v_mov_b64_e32 v[32:33], v[194:195]
	v_mov_b64_e32 v[34:35], v[196:197]
	v_mov_b64_e32 v[36:37], v[224:225]
	v_mov_b64_e32 v[38:39], v[226:227]
	s_nop 0
	v_mov_b64_e32 v[4:5], v[232:233]
	v_pk_fma_f32 v[18:19], v[18:19], s[42:43], v[26:27] op_sel_hi:[1,0,1]
	v_mov_b64_e32 v[24:25], v[238:239]
	v_add_f32_e32 v44, v16, v17
	v_add_f32_e32 v46, v18, v19
	v_lshlrev_b32_e32 v6, 16, v4
	v_and_b32_e32 v7, 0xffff0000, v4
	v_lshlrev_b32_e32 v26, 16, v24
	v_and_b32_e32 v27, 0xffff0000, v24
	v_lshlrev_b32_e32 v4, 16, v5
	v_and_b32_e32 v5, 0xffff0000, v5
	v_lshlrev_b32_e32 v24, 16, v25
	v_and_b32_e32 v25, 0xffff0000, v25
	v_pk_add_f32 v[6:7], v[6:7], v[26:27]
	v_pk_add_f32 v[4:5], v[4:5], v[24:25]
	v_pk_mul_f32 v[6:7], v[36:37], v[6:7]
	v_pk_mul_f32 v[4:5], v[38:39], v[4:5]
	v_pk_fma_f32 v[24:25], v[32:33], s[42:43], v[6:7] op_sel_hi:[1,0,1]
	v_pk_fma_f32 v[26:27], v[34:35], s[42:43], v[4:5] op_sel_hi:[1,0,1]
	v_mov_b32_e32 v29, v24
	v_mov_b32_e32 v31, v25
	v_pk_add_f32 v[4:5], v[28:29], v[30:31]
	v_mov_b32_e32 v45, v26
	v_mov_b32_e32 v47, v27
	v_lshl_add_u64 v[28:29], s[56:57], 0, v[90:91]
	v_pk_add_f32 v[6:7], v[44:45], v[46:47]
	v_lshl_add_u64 v[44:45], v[28:29], 0, s[8:9]
	v_pk_add_f32 v[4:5], v[4:5], v[6:7]
	v_lshl_add_u64 v[52:53], v[28:29], 0, v[152:153]
	v_lshl_add_u64 v[34:35], v[44:45], 0, v[152:153]
	v_add_f32_e32 v122, v4, v5
	global_load_dwordx4 v[186:189], v[48:49], off offset:1024
	global_load_dwordx4 v[190:193], v[48:49], off offset:2048
	global_load_dwordx4 v[194:197], v[48:49], off offset:3072
	flat_load_dwordx4 v[4:7], v[48:49]
	global_load_dwordx2 v[228:229], v[52:53], off offset:512
	global_load_dwordx2 v[230:231], v[52:53], off offset:1024
	global_load_dwordx2 v[232:233], v[52:53], off offset:1536
	flat_load_dwordx2 v[28:29], v[52:53]
	v_lshl_add_u64 v[32:33], v[80:81], 0, v[2:3]
	global_load_dwordx2 v[234:235], v[34:35], off offset:512
	global_load_dwordx2 v[236:237], v[34:35], off offset:1024
	global_load_dwordx2 v[238:239], v[34:35], off offset:1536
	flat_load_dwordx2 v[34:35], v[34:35]
	v_lshl_add_u64 v[38:39], v[44:45], 0, v[104:105]
	global_load_dwordx4 v[198:201], v[32:33], off offset:1024
	global_load_dwordx4 v[202:205], v[32:33], off offset:2048
	global_load_dwordx4 v[224:227], v[32:33], off offset:3072
	flat_load_dwordx4 v[0:3], v[32:33]
	v_lshl_add_u64 v[54:55], v[44:45], 0, v[106:107]
	v_lshl_add_u64 v[44:45], v[44:45], 0, v[120:121]
	s_waitcnt vmcnt(0) lgkmcnt(0)
	v_lshlrev_b32_e32 v30, 16, v28
	v_and_b32_e32 v31, 0xffff0000, v28
	v_lshlrev_b32_e32 v28, 16, v29
	v_and_b32_e32 v29, 0xffff0000, v29
	v_lshlrev_b32_e32 v36, 16, v34
	v_and_b32_e32 v37, 0xffff0000, v34
	v_lshlrev_b32_e32 v34, 16, v35
	v_and_b32_e32 v35, 0xffff0000, v35
	v_pk_add_f32 v[30:31], v[30:31], v[36:37]
	v_pk_add_f32 v[28:29], v[28:29], v[34:35]
	v_pk_mul_f32 v[4:5], v[4:5], v[30:31]
	v_pk_mul_f32 v[6:7], v[6:7], v[28:29]
	v_pk_fma_f32 v[28:29], v[0:1], s[42:43], v[4:5] op_sel_hi:[1,0,1]
	v_pk_fma_f32 v[30:31], v[2:3], s[42:43], v[6:7] op_sel_hi:[1,0,1]
	v_mov_b32_e32 v2, v28
	v_pk_mov_b32 v[0:1], v[28:29], v[30:31] op_sel:[1,0]
	v_mov_b32_e32 v3, v31
	v_pk_add_f32 v[0:1], v[0:1], v[2:3]
	s_nop 0
	v_add_f32_e32 v0, v0, v1
	v_add_f32_e32 v46, 0, v0
	v_mov_b64_e32 v[0:1], v[198:199]
	v_mov_b64_e32 v[2:3], v[200:201]
	v_mov_b64_e32 v[4:5], v[186:187]
	v_mov_b64_e32 v[6:7], v[188:189]
	v_mov_b64_e32 v[34:35], v[228:229]
	v_lshlrev_b32_e32 v36, 16, v34
	v_mov_b64_e32 v[38:39], v[234:235]
	v_and_b32_e32 v37, 0xffff0000, v34
	v_lshlrev_b32_e32 v34, 16, v35
	v_and_b32_e32 v35, 0xffff0000, v35
	v_lshlrev_b32_e32 v50, 16, v38
	v_and_b32_e32 v51, 0xffff0000, v38
	v_lshlrev_b32_e32 v38, 16, v39
	v_and_b32_e32 v39, 0xffff0000, v39
	v_pk_add_f32 v[36:37], v[36:37], v[50:51]
	v_pk_add_f32 v[34:35], v[34:35], v[38:39]
	v_pk_mul_f32 v[4:5], v[4:5], v[36:37]
	v_pk_mul_f32 v[6:7], v[6:7], v[34:35]
	v_pk_fma_f32 v[38:39], v[0:1], s[42:43], v[4:5] op_sel_hi:[1,0,1]
	v_pk_fma_f32 v[60:61], v[2:3], s[42:43], v[6:7] op_sel_hi:[1,0,1]
	v_mov_b32_e32 v2, v38
	v_pk_mov_b32 v[0:1], v[38:39], v[60:61] op_sel:[1,0]
	v_mov_b32_e32 v3, v61
	v_pk_add_f32 v[0:1], v[0:1], v[2:3]
	s_nop 0
	v_pk_add_f32 v[50:51], v[0:1], v[0:1] op_sel:[0,1] op_sel_hi:[1,0]
	v_mov_b64_e32 v[0:1], v[202:203]
	v_mov_b64_e32 v[2:3], v[204:205]
	v_mov_b64_e32 v[4:5], v[190:191]
	v_mov_b64_e32 v[6:7], v[192:193]
	v_mov_b64_e32 v[34:35], v[230:231]
	v_lshlrev_b32_e32 v36, 16, v34
	v_mov_b64_e32 v[54:55], v[236:237]
	v_and_b32_e32 v37, 0xffff0000, v34
	v_lshlrev_b32_e32 v34, 16, v35
	v_and_b32_e32 v35, 0xffff0000, v35
	v_lshlrev_b32_e32 v56, 16, v54
	v_and_b32_e32 v57, 0xffff0000, v54
	v_lshlrev_b32_e32 v54, 16, v55
	v_and_b32_e32 v55, 0xffff0000, v55
	v_pk_add_f32 v[34:35], v[34:35], v[54:55]
	v_pk_add_f32 v[36:37], v[36:37], v[56:57]
	v_pk_mul_f32 v[6:7], v[6:7], v[34:35]
	v_pk_mul_f32 v[4:5], v[4:5], v[36:37]
	v_pk_fma_f32 v[36:37], v[2:3], s[42:43], v[6:7] op_sel_hi:[1,0,1]
	v_pk_fma_f32 v[34:35], v[0:1], s[42:43], v[4:5] op_sel_hi:[1,0,1]
	v_mov_b64_e32 v[0:1], v[224:225]
	v_mov_b64_e32 v[2:3], v[226:227]
	v_mov_b64_e32 v[4:5], v[194:195]
	v_mov_b64_e32 v[6:7], v[196:197]
	s_nop 0
	v_mov_b64_e32 v[52:53], v[232:233]
	v_add_f32_e32 v54, v34, v35
	v_mov_b64_e32 v[44:45], v[238:239]
	v_add_f32_e32 v56, v36, v37
	v_lshlrev_b32_e32 v48, 16, v52
	v_and_b32_e32 v49, 0xffff0000, v52
	v_lshlrev_b32_e32 v58, 16, v44
	v_and_b32_e32 v59, 0xffff0000, v44
	v_lshlrev_b32_e32 v52, 16, v53
	v_and_b32_e32 v53, 0xffff0000, v53
	v_lshlrev_b32_e32 v44, 16, v45
	v_and_b32_e32 v45, 0xffff0000, v45
	v_pk_add_f32 v[48:49], v[48:49], v[58:59]
	v_pk_add_f32 v[44:45], v[52:53], v[44:45]
	v_pk_mul_f32 v[4:5], v[4:5], v[48:49]
	v_pk_mul_f32 v[6:7], v[6:7], v[44:45]
	v_pk_fma_f32 v[62:63], v[0:1], s[42:43], v[4:5] op_sel_hi:[1,0,1]
	v_pk_fma_f32 v[118:119], v[2:3], s[42:43], v[6:7] op_sel_hi:[1,0,1]
	v_mov_b32_e32 v47, v62
	v_mov_b32_e32 v51, v63
	v_pk_add_f32 v[0:1], v[46:47], v[50:51]
	v_mov_b32_e32 v55, v118
	v_mov_b32_e32 v57, v119
	v_lshl_add_u64 v[44:45], v[42:43], 0, s[8:9]
	v_mad_u64_u32 v[46:47], s[4:5], v98, s7, v[78:79]
	v_pk_add_f32 v[2:3], v[54:55], v[56:57]
	v_mad_i32_i24 v47, v99, s7, v47
	v_lshl_add_u64 v[42:43], v[42:43], 0, v[152:153]
	v_lshl_add_u64 v[52:53], v[44:45], 0, v[152:153]
	v_pk_add_f32 v[0:1], v[0:1], v[2:3]
	global_load_dwordx4 v[186:189], v[46:47], off offset:1024
	global_load_dwordx4 v[190:193], v[46:47], off offset:2048
	global_load_dwordx4 v[194:197], v[46:47], off offset:3072
	flat_load_dwordx4 v[4:7], v[46:47]
	global_load_dwordx2 v[228:229], v[42:43], off offset:512
	global_load_dwordx2 v[230:231], v[42:43], off offset:1024
	global_load_dwordx2 v[232:233], v[42:43], off offset:1536
	flat_load_dwordx2 v[48:49], v[42:43]
	v_add_f32_e32 v126, v0, v1
	global_load_dwordx2 v[234:235], v[52:53], off offset:512
	global_load_dwordx2 v[236:237], v[52:53], off offset:1024
	global_load_dwordx2 v[238:239], v[52:53], off offset:1536
	flat_load_dwordx2 v[52:53], v[52:53]
	v_lshlrev_b64 v[0:1], 12, v[40:41]
	v_lshl_add_u64 v[40:41], v[80:81], 0, v[0:1]
	global_load_dwordx4 v[198:201], v[40:41], off offset:1024
	global_load_dwordx4 v[202:205], v[40:41], off offset:2048
	global_load_dwordx4 v[224:227], v[40:41], off offset:3072
	flat_load_dwordx4 v[0:3], v[40:41]
	v_lshl_add_u64 v[56:57], v[44:45], 0, v[104:105]
	v_lshl_add_u64 v[102:103], v[44:45], 0, v[106:107]
	v_lshl_add_u64 v[44:45], v[44:45], 0, v[120:121]
	s_waitcnt vmcnt(0) lgkmcnt(0)
	v_lshlrev_b32_e32 v50, 16, v48
	v_and_b32_e32 v51, 0xffff0000, v48
	v_lshlrev_b32_e32 v48, 16, v49
	v_and_b32_e32 v49, 0xffff0000, v49
	v_lshlrev_b32_e32 v54, 16, v52
	v_and_b32_e32 v55, 0xffff0000, v52
	v_lshlrev_b32_e32 v52, 16, v53
	v_and_b32_e32 v53, 0xffff0000, v53
	v_pk_add_f32 v[50:51], v[50:51], v[54:55]
	v_pk_add_f32 v[48:49], v[48:49], v[52:53]
	v_pk_mul_f32 v[4:5], v[4:5], v[50:51]
	v_pk_mul_f32 v[6:7], v[6:7], v[48:49]
	v_pk_fma_f32 v[50:51], v[0:1], s[42:43], v[4:5] op_sel_hi:[1,0,1]
	v_pk_fma_f32 v[52:53], v[2:3], s[42:43], v[6:7] op_sel_hi:[1,0,1]
	v_mov_b32_e32 v2, v50
	v_pk_mov_b32 v[0:1], v[50:51], v[52:53] op_sel:[1,0]
	v_mov_b32_e32 v3, v53
	v_pk_add_f32 v[0:1], v[0:1], v[2:3]
	s_nop 0
	v_add_f32_e32 v0, v0, v1
	v_add_f32_e32 v94, 0, v0
	v_mov_b64_e32 v[0:1], v[198:199]
	v_mov_b64_e32 v[2:3], v[200:201]
	v_mov_b64_e32 v[4:5], v[186:187]
	v_mov_b64_e32 v[6:7], v[188:189]
	v_mov_b64_e32 v[48:49], v[228:229]
	v_lshlrev_b32_e32 v54, 16, v48
	v_mov_b64_e32 v[56:57], v[234:235]
	v_and_b32_e32 v55, 0xffff0000, v48
	v_lshlrev_b32_e32 v48, 16, v49
	v_and_b32_e32 v49, 0xffff0000, v49
	v_lshlrev_b32_e32 v58, 16, v56
	v_and_b32_e32 v59, 0xffff0000, v56
	v_lshlrev_b32_e32 v56, 16, v57
	v_and_b32_e32 v57, 0xffff0000, v57
	v_pk_add_f32 v[54:55], v[54:55], v[58:59]
	v_pk_add_f32 v[48:49], v[48:49], v[56:57]
	v_pk_mul_f32 v[4:5], v[4:5], v[54:55]
	v_pk_mul_f32 v[6:7], v[6:7], v[48:49]
	v_pk_fma_f32 v[56:57], v[0:1], s[42:43], v[4:5] op_sel_hi:[1,0,1]
	v_pk_fma_f32 v[58:59], v[2:3], s[42:43], v[6:7] op_sel_hi:[1,0,1]
	v_mov_b32_e32 v2, v56
	v_pk_mov_b32 v[0:1], v[56:57], v[58:59] op_sel:[1,0]
	v_mov_b32_e32 v3, v59
	v_pk_add_f32 v[0:1], v[0:1], v[2:3]
	s_nop 0
	v_pk_add_f32 v[100:101], v[0:1], v[0:1] op_sel:[0,1] op_sel_hi:[1,0]
	v_mov_b64_e32 v[0:1], v[202:203]
	v_mov_b64_e32 v[2:3], v[204:205]
	v_mov_b64_e32 v[4:5], v[190:191]
	v_mov_b64_e32 v[6:7], v[192:193]
	v_mov_b64_e32 v[48:49], v[230:231]
	v_lshlrev_b32_e32 v54, 16, v48
	v_mov_b64_e32 v[102:103], v[236:237]
	v_and_b32_e32 v55, 0xffff0000, v48
	v_lshlrev_b32_e32 v48, 16, v49
	v_and_b32_e32 v49, 0xffff0000, v49
	v_lshlrev_b32_e32 v108, 16, v102
	v_and_b32_e32 v109, 0xffff0000, v102
	v_lshlrev_b32_e32 v102, 16, v103
	v_and_b32_e32 v103, 0xffff0000, v103
	v_pk_add_f32 v[48:49], v[48:49], v[102:103]
	v_pk_add_f32 v[54:55], v[54:55], v[108:109]
	v_pk_mul_f32 v[6:7], v[6:7], v[48:49]
	v_pk_mul_f32 v[4:5], v[4:5], v[54:55]
	v_pk_fma_f32 v[116:117], v[2:3], s[42:43], v[6:7] op_sel_hi:[1,0,1]
	v_pk_fma_f32 v[54:55], v[0:1], s[42:43], v[4:5] op_sel_hi:[1,0,1]
	v_mov_b64_e32 v[0:1], v[224:225]
	v_mov_b64_e32 v[2:3], v[226:227]
	v_mov_b64_e32 v[4:5], v[194:195]
	v_mov_b64_e32 v[6:7], v[196:197]
	s_nop 0
	v_mov_b64_e32 v[42:43], v[232:233]
	v_add_f32_e32 v102, v54, v55
	v_mov_b64_e32 v[44:45], v[238:239]
	v_add_f32_e32 v108, v116, v117
	v_lshlrev_b32_e32 v46, 16, v42
	v_and_b32_e32 v47, 0xffff0000, v42
	v_lshlrev_b32_e32 v42, 16, v43
	v_and_b32_e32 v43, 0xffff0000, v43
	v_lshlrev_b32_e32 v48, 16, v44
	v_and_b32_e32 v49, 0xffff0000, v44
	v_lshlrev_b32_e32 v44, 16, v45
	v_and_b32_e32 v45, 0xffff0000, v45
	v_pk_add_f32 v[42:43], v[42:43], v[44:45]
	v_pk_add_f32 v[44:45], v[46:47], v[48:49]
	v_pk_mul_f32 v[6:7], v[6:7], v[42:43]
	v_pk_mul_f32 v[4:5], v[4:5], v[44:45]
	v_pk_fma_f32 v[48:49], v[2:3], s[42:43], v[6:7] op_sel_hi:[1,0,1]
	v_pk_fma_f32 v[46:47], v[0:1], s[42:43], v[4:5] op_sel_hi:[1,0,1]
	v_mov_b32_e32 v103, v48
	v_mov_b32_e32 v95, v46
	v_mov_b32_e32 v101, v47
	v_mov_b32_e32 v109, v49
	v_pk_add_f32 v[0:1], v[94:95], v[100:101]
	v_pk_add_f32 v[2:3], v[102:103], v[108:109]
	v_lshlrev_b64 v[94:95], 11, v[20:21]
	v_pk_add_f32 v[0:1], v[0:1], v[2:3]
	v_lshl_add_u64 v[100:101], v[22:23], 0, s[28:29]
	v_add_f32_e32 v125, v0, v1
	v_lshlrev_b64 v[0:1], 12, v[20:21]
	v_lshl_add_u64 v[20:21], s[56:57], 0, v[94:95]
	v_lshl_add_u64 v[22:23], v[20:21], 0, s[8:9]
	v_mad_u64_u32 v[128:129], s[4:5], v100, s7, v[78:79]
	v_mad_i32_i24 v129, v101, s7, v129
	v_lshl_add_u64 v[20:21], v[20:21], 0, v[152:153]
	v_lshl_add_u64 v[108:109], v[22:23], 0, v[152:153]
	global_load_dwordx4 v[186:189], v[128:129], off offset:1024
	global_load_dwordx4 v[190:193], v[128:129], off offset:2048
	global_load_dwordx4 v[194:197], v[128:129], off offset:3072
	flat_load_dwordx4 v[4:7], v[128:129]
	global_load_dwordx2 v[228:229], v[20:21], off offset:512
	global_load_dwordx2 v[230:231], v[20:21], off offset:1024
	global_load_dwordx2 v[232:233], v[20:21], off offset:1536
	flat_load_dwordx2 v[42:43], v[20:21]
	v_lshl_add_u64 v[102:103], v[80:81], 0, v[0:1]
	global_load_dwordx2 v[234:235], v[108:109], off offset:512
	global_load_dwordx2 v[236:237], v[108:109], off offset:1024
	global_load_dwordx2 v[238:239], v[108:109], off offset:1536
	flat_load_dwordx2 v[108:109], v[108:109]
	v_lshl_add_u64 v[104:105], v[22:23], 0, v[104:105]
	global_load_dwordx4 v[198:201], v[102:103], off offset:1024
	global_load_dwordx4 v[202:205], v[102:103], off offset:2048
	global_load_dwordx4 v[224:227], v[102:103], off offset:3072
	flat_load_dwordx4 v[0:3], v[102:103]
	v_lshl_add_u64 v[106:107], v[22:23], 0, v[106:107]
	v_lshl_add_u64 v[22:23], v[22:23], 0, v[120:121]
	v_readlane_b32 s4, v254, 33
	v_readlane_b32 s5, v254, 34
	s_waitcnt vmcnt(0) lgkmcnt(0)
	v_lshlrev_b32_e32 v44, 16, v42
	v_and_b32_e32 v45, 0xffff0000, v42
	v_lshlrev_b32_e32 v42, 16, v43
	v_and_b32_e32 v43, 0xffff0000, v43
	v_lshlrev_b32_e32 v110, 16, v108
	v_and_b32_e32 v111, 0xffff0000, v108
	v_lshlrev_b32_e32 v108, 16, v109
	v_and_b32_e32 v109, 0xffff0000, v109
	v_pk_add_f32 v[44:45], v[44:45], v[110:111]
	v_pk_add_f32 v[42:43], v[42:43], v[108:109]
	v_pk_mul_f32 v[4:5], v[4:5], v[44:45]
	v_pk_mul_f32 v[6:7], v[6:7], v[42:43]
	v_pk_fma_f32 v[44:45], v[0:1], s[42:43], v[4:5] op_sel_hi:[1,0,1]
	v_pk_fma_f32 v[114:115], v[2:3], s[42:43], v[6:7] op_sel_hi:[1,0,1]
	v_mov_b32_e32 v2, v44
	v_pk_mov_b32 v[0:1], v[44:45], v[114:115] op_sel:[1,0]
	v_mov_b32_e32 v3, v115
	v_pk_add_f32 v[0:1], v[0:1], v[2:3]
	s_nop 0
	v_add_f32_e32 v0, v0, v1
	v_add_f32_e32 v130, 0, v0
	v_mov_b64_e32 v[0:1], v[198:199]
	v_mov_b64_e32 v[2:3], v[200:201]
	v_mov_b64_e32 v[4:5], v[186:187]
	v_mov_b64_e32 v[6:7], v[188:189]
	v_mov_b64_e32 v[42:43], v[228:229]
	v_lshlrev_b32_e32 v108, 16, v42
	v_mov_b64_e32 v[104:105], v[234:235]
	v_and_b32_e32 v109, 0xffff0000, v42
	v_lshlrev_b32_e32 v42, 16, v43
	v_and_b32_e32 v43, 0xffff0000, v43
	v_lshlrev_b32_e32 v110, 16, v104
	v_and_b32_e32 v111, 0xffff0000, v104
	v_lshlrev_b32_e32 v104, 16, v105
	v_and_b32_e32 v105, 0xffff0000, v105
	v_pk_add_f32 v[108:109], v[108:109], v[110:111]
	v_pk_add_f32 v[42:43], v[42:43], v[104:105]
	v_pk_mul_f32 v[4:5], v[4:5], v[108:109]
	v_pk_mul_f32 v[6:7], v[6:7], v[42:43]
	v_pk_fma_f32 v[42:43], v[0:1], s[42:43], v[4:5] op_sel_hi:[1,0,1]
	v_pk_fma_f32 v[112:113], v[2:3], s[42:43], v[6:7] op_sel_hi:[1,0,1]
	v_mov_b32_e32 v2, v42
	v_pk_mov_b32 v[0:1], v[42:43], v[112:113] op_sel:[1,0]
	v_mov_b32_e32 v3, v113
	v_pk_add_f32 v[0:1], v[0:1], v[2:3]
	s_nop 0
	v_pk_add_f32 v[132:133], v[0:1], v[0:1] op_sel:[0,1] op_sel_hi:[1,0]
	v_mov_b64_e32 v[0:1], v[202:203]
	v_mov_b64_e32 v[2:3], v[204:205]
	v_mov_b64_e32 v[4:5], v[190:191]
	v_mov_b64_e32 v[6:7], v[192:193]
	v_mov_b64_e32 v[104:105], v[230:231]
	v_lshlrev_b32_e32 v108, 16, v104
	v_mov_b64_e32 v[106:107], v[236:237]
	v_and_b32_e32 v109, 0xffff0000, v104
	v_lshlrev_b32_e32 v104, 16, v105
	v_and_b32_e32 v105, 0xffff0000, v105
	v_lshlrev_b32_e32 v110, 16, v106
	v_and_b32_e32 v111, 0xffff0000, v106
	v_lshlrev_b32_e32 v106, 16, v107
	v_and_b32_e32 v107, 0xffff0000, v107
	v_pk_add_f32 v[104:105], v[104:105], v[106:107]
	v_pk_add_f32 v[106:107], v[108:109], v[110:111]
	v_pk_mul_f32 v[6:7], v[6:7], v[104:105]
	v_pk_mul_f32 v[4:5], v[4:5], v[106:107]
	v_pk_fma_f32 v[110:111], v[2:3], s[42:43], v[6:7] op_sel_hi:[1,0,1]
	v_pk_fma_f32 v[108:109], v[0:1], s[42:43], v[4:5] op_sel_hi:[1,0,1]
	v_mov_b64_e32 v[0:1], v[224:225]
	v_mov_b64_e32 v[2:3], v[226:227]
	v_mov_b64_e32 v[4:5], v[194:195]
	v_mov_b64_e32 v[6:7], v[196:197]
	s_nop 0
	v_mov_b64_e32 v[20:21], v[232:233]
	v_add_f32_e32 v134, v108, v109
	v_mov_b64_e32 v[22:23], v[238:239]
	v_add_f32_e32 v136, v110, v111
	v_lshlrev_b32_e32 v104, 16, v20
	v_and_b32_e32 v105, 0xffff0000, v20
	v_lshlrev_b32_e32 v20, 16, v21
	v_and_b32_e32 v21, 0xffff0000, v21
	v_lshlrev_b32_e32 v106, 16, v22
	v_and_b32_e32 v107, 0xffff0000, v22
	v_lshlrev_b32_e32 v22, 16, v23
	v_and_b32_e32 v23, 0xffff0000, v23
	v_pk_add_f32 v[20:21], v[20:21], v[22:23]
	v_pk_add_f32 v[22:23], v[104:105], v[106:107]
	v_pk_mul_f32 v[6:7], v[6:7], v[20:21]
	v_pk_mul_f32 v[4:5], v[4:5], v[22:23]
	v_pk_fma_f32 v[106:107], v[2:3], s[42:43], v[6:7] op_sel_hi:[1,0,1]
	v_pk_fma_f32 v[104:105], v[0:1], s[42:43], v[4:5] op_sel_hi:[1,0,1]
	v_mov_b32_e32 v135, v106
	v_mov_b32_e32 v131, v104
	v_mov_b32_e32 v133, v105
	v_mov_b32_e32 v137, v107
	v_pk_add_f32 v[0:1], v[130:131], v[132:133]
	v_pk_add_f32 v[2:3], v[134:135], v[136:137]
	ds_bpermute_b32 v22, v67, v126
	v_pk_add_f32 v[0:1], v[0:1], v[2:3]
	s_waitcnt lgkmcnt(0)
	v_add_f32_e32 v22, v126, v22
	v_add_f32_e32 v65, v0, v1
	ds_bpermute_b32 v0, v67, v122
	ds_bpermute_b32 v23, v69, v22
	s_waitcnt lgkmcnt(1)
	v_add_f32_e32 v0, v122, v0
	ds_bpermute_b32 v1, v69, v0
	s_waitcnt lgkmcnt(1)
	v_add_f32_e32 v22, v22, v23
	ds_bpermute_b32 v23, v71, v22
	s_waitcnt lgkmcnt(1)
	v_add_f32_e32 v0, v0, v1
	ds_bpermute_b32 v1, v71, v0
	s_waitcnt lgkmcnt(1)
	v_add_f32_e32 v22, v22, v23
	ds_bpermute_b32 v23, v73, v22
	s_waitcnt lgkmcnt(1)
	v_add_f32_e32 v0, v0, v1
	ds_bpermute_b32 v1, v73, v0
	s_waitcnt lgkmcnt(1)
	v_add_f32_e32 v22, v22, v23
	ds_bpermute_b32 v23, v123, v22
	s_waitcnt lgkmcnt(1)
	v_add_f32_e32 v0, v0, v1
	ds_bpermute_b32 v1, v123, v0
	s_waitcnt lgkmcnt(1)
	v_add_f32_e32 v22, v22, v23
	ds_bpermute_b32 v23, v124, v22
	s_waitcnt lgkmcnt(1)
	v_add_f32_e32 v0, v0, v1
	ds_bpermute_b32 v1, v124, v0
	s_waitcnt lgkmcnt(1)
	v_add_f32_e32 v122, v22, v23
	v_fmamk_f32 v29, v122, 0xba800000, v29
	v_fmac_f32_e32 v28, 0xba800000, v122
	v_fmamk_f32 v31, v122, 0xba800000, v31
	s_waitcnt lgkmcnt(0)
	v_add_f32_e32 v20, v0, v1
	v_fmamk_f32 v9, v20, 0xba800000, v9
	v_fmac_f32_e32 v8, 0xba800000, v20
	v_fmamk_f32 v11, v20, 0xba800000, v11
	v_fmac_f32_e32 v10, 0xba800000, v20
	v_pk_mul_f32 v[0:1], v[10:11], v[10:11]
	v_pk_mul_f32 v[2:3], v[8:9], v[8:9]
	v_fmamk_f32 v13, v20, 0xba800000, v13
	v_pk_mov_b32 v[4:5], v[2:3], v[0:1] op_sel:[1,0]
	v_mov_b32_e32 v3, v1
	v_pk_add_f32 v[0:1], v[4:5], v[2:3]
	v_fmac_f32_e32 v12, 0xba800000, v20
	v_fmamk_f32 v15, v20, 0xba800000, v15
	v_fmac_f32_e32 v14, 0xba800000, v20
	v_pk_add_f32 v[0:1], v[0:1], v[0:1] op_sel_hi:[0,1]
	v_pk_mul_f32 v[2:3], v[14:15], v[14:15]
	v_pk_mul_f32 v[4:5], v[12:13], v[12:13]
	v_fmac_f32_e32 v16, 0xba800000, v20
	v_pk_mov_b32 v[6:7], v[4:5], v[2:3] op_sel:[1,0]
	v_mov_b32_e32 v5, v3
	v_fmamk_f32 v17, v20, 0xba800000, v17
	v_fmac_f32_e32 v18, 0xba800000, v20
	v_mul_f32_e32 v0, v16, v16
	v_pk_add_f32 v[2:3], v[6:7], v[4:5]
	v_fmamk_f32 v19, v20, 0xba800000, v19
	v_pk_fma_f32 v[4:5], v[16:17], v[16:17], v[0:1] op_sel_hi:[1,1,0]
	v_mul_f32_e32 v0, v18, v18
	v_pk_add_f32 v[2:3], v[2:3], v[2:3] op_sel_hi:[0,1]
	v_pk_fma_f32 v[6:7], v[18:19], v[18:19], v[0:1] op_sel_hi:[1,1,0]
	v_fmamk_f32 v27, v20, 0xba800000, v27
	v_fmac_f32_e32 v26, 0xba800000, v20
	v_fmamk_f32 v25, v20, 0xba800000, v25
	v_fmac_f32_e32 v24, 0xba800000, v20
	v_mul_f32_e32 v4, v24, v24
	v_mul_f32_e32 v6, v25, v25
	v_mul_f32_e32 v0, v26, v26
	v_mul_f32_e32 v2, v27, v27
	v_pk_add_f32 v[4:5], v[4:5], v[6:7]
	v_pk_add_f32 v[0:1], v[0:1], v[2:3]
	v_fmac_f32_e32 v30, 0xba800000, v122
	v_pk_add_f32 v[20:21], v[4:5], v[0:1]
	v_mov_b64_e32 v[0:1], v[154:155]
	v_mov_b64_e32 v[2:3], v[156:157]
	v_mov_b64_e32 v[4:5], v[158:159]
	v_mov_b64_e32 v[6:7], v[160:161]
	v_pk_mul_f32 v[22:23], v[30:31], v[30:31]
	v_pk_mul_f32 v[120:121], v[28:29], v[28:29]
	v_fmamk_f32 v39, v122, 0xba800000, v39
	v_pk_mov_b32 v[126:127], v[120:121], v[22:23] op_sel:[1,0]
	v_mov_b32_e32 v121, v23
	v_pk_add_f32 v[22:23], v[126:127], v[120:121]
	v_fmac_f32_e32 v38, 0xba800000, v122
	v_fmamk_f32 v61, v122, 0xba800000, v61
	v_fmac_f32_e32 v60, 0xba800000, v122
	v_pk_add_f32 v[22:23], v[22:23], v[22:23] op_sel_hi:[0,1]
	v_pk_mul_f32 v[120:121], v[60:61], v[60:61]
	v_pk_mul_f32 v[126:127], v[38:39], v[38:39]
	v_fmac_f32_e32 v34, 0xba800000, v122
	v_pk_mov_b32 v[128:129], v[126:127], v[120:121] op_sel:[1,0]
	v_mov_b32_e32 v127, v121
	v_fmamk_f32 v35, v122, 0xba800000, v35
	v_fmac_f32_e32 v36, 0xba800000, v122
	v_mul_f32_e32 v22, v34, v34
	v_pk_add_f32 v[120:121], v[128:129], v[126:127]
	v_fmamk_f32 v37, v122, 0xba800000, v37
	v_pk_fma_f32 v[126:127], v[34:35], v[34:35], v[22:23] op_sel_hi:[1,1,0]
	v_mul_f32_e32 v22, v36, v36
	v_pk_add_f32 v[120:121], v[120:121], v[120:121] op_sel_hi:[0,1]
	v_pk_fma_f32 v[128:129], v[36:37], v[36:37], v[22:23] op_sel_hi:[1,1,0]
	v_fmamk_f32 v119, v122, 0xba800000, v119
	v_fmac_f32_e32 v118, 0xba800000, v122
	v_fmamk_f32 v63, v122, 0xba800000, v63
	v_fmac_f32_e32 v62, 0xba800000, v122
	v_mul_f32_e32 v126, v62, v62
	v_mul_f32_e32 v128, v63, v63
	v_mul_f32_e32 v22, v118, v118
	v_mul_f32_e32 v120, v119, v119
	v_pk_add_f32 v[126:127], v[126:127], v[128:129]
	v_pk_add_f32 v[22:23], v[22:23], v[120:121]
	v_mov_b32_e32 v121, v20
	v_pk_add_f32 v[22:23], v[126:127], v[22:23]
	s_nop 0
	v_mov_b32_e32 v120, v22
	v_mov_b32_e32 v20, v23
	v_pk_add_f32 v[20:21], v[120:121], v[20:21]
	ds_bpermute_b32 v23, v67, v21
	ds_bpermute_b32 v22, v67, v20
	v_mov_b64_e32 v[120:121], s[2:3]
	s_mov_b32 s2, 0x3a800000
	s_waitcnt lgkmcnt(0)
	v_pk_add_f32 v[20:21], v[20:21], v[22:23]
	ds_bpermute_b32 v23, v69, v21
	ds_bpermute_b32 v22, v69, v20
	s_waitcnt lgkmcnt(0)
	v_pk_add_f32 v[20:21], v[20:21], v[22:23]
	ds_bpermute_b32 v23, v71, v21
	ds_bpermute_b32 v22, v71, v20
	s_waitcnt lgkmcnt(0)
	v_pk_add_f32 v[20:21], v[20:21], v[22:23]
	ds_bpermute_b32 v23, v73, v21
	ds_bpermute_b32 v22, v73, v20
	s_waitcnt lgkmcnt(0)
	v_pk_add_f32 v[20:21], v[20:21], v[22:23]
	ds_bpermute_b32 v23, v123, v21
	ds_bpermute_b32 v22, v123, v20
	s_waitcnt lgkmcnt(0)
	v_pk_add_f32 v[20:21], v[20:21], v[22:23]
	ds_bpermute_b32 v23, v124, v21
	ds_bpermute_b32 v22, v124, v20
	s_waitcnt lgkmcnt(0)
	v_pk_add_f32 v[20:21], v[20:21], v[22:23]
	s_nop 0
	v_pk_fma_f32 v[126:127], v[20:21], s[2:3], v[120:121] op_sel_hi:[1,0,0]
	s_nop 0
	v_mul_f32_e32 v20, 0x4b800000, v127
	v_cmp_gt_f32_e64 s[8:9], s68, v127
	v_cmp_gt_f32_e32 vcc, s68, v126
	s_nop 0
	v_cndmask_b32_e64 v20, v127, v20, s[8:9]
	v_rsq_f32_e32 v20, v20
	s_nop 0
	v_mul_f32_e32 v21, 0x45800000, v20
	v_cndmask_b32_e64 v122, v20, v21, s[8:9]
	v_pk_mul_f32 v[8:9], v[8:9], v[122:123] op_sel_hi:[1,0]
	v_pk_mul_f32 v[10:11], v[10:11], v[122:123] op_sel_hi:[1,0]
	v_pk_fma_f32 v[20:21], v[0:1], v[8:9], v[4:5]
	v_pk_fma_f32 v[22:23], v[2:3], v[10:11], v[6:7]
	flat_store_dwordx4 v[86:87], v[20:23]
	v_mov_b64_e32 v[0:1], v[162:163]
	v_mov_b64_e32 v[2:3], v[164:165]
	v_mov_b64_e32 v[4:5], v[166:167]
	v_mov_b64_e32 v[6:7], v[168:169]
	v_pk_mul_f32 v[8:9], v[14:15], v[122:123] op_sel_hi:[1,0]
	v_pk_mul_f32 v[10:11], v[12:13], v[122:123] op_sel_hi:[1,0]
	v_pk_fma_f32 v[14:15], v[2:3], v[8:9], v[6:7]
	v_pk_fma_f32 v[12:13], v[0:1], v[10:11], v[4:5]
	flat_store_dwordx4 v[86:87], v[12:15] offset:1024
	v_mov_b64_e32 v[0:1], v[170:171]
	v_mov_b64_e32 v[2:3], v[172:173]
	v_mov_b64_e32 v[4:5], v[174:175]
	v_mov_b64_e32 v[6:7], v[176:177]
	v_pk_mul_f32 v[8:9], v[18:19], v[122:123] op_sel_hi:[1,0]
	v_pk_mul_f32 v[10:11], v[16:17], v[122:123] op_sel_hi:[1,0]
	v_pk_mul_f32 v[18:19], v[24:25], v[122:123] op_sel_hi:[1,0]
	v_pk_mul_f32 v[16:17], v[26:27], v[122:123] op_sel_hi:[1,0]
	v_pk_fma_f32 v[4:5], v[0:1], v[10:11], v[4:5]
	v_pk_fma_f32 v[6:7], v[2:3], v[8:9], v[6:7]
	flat_store_dwordx4 v[86:87], v[4:7] offset:2048
	v_mov_b64_e32 v[0:1], v[178:179]
	v_mov_b64_e32 v[2:3], v[180:181]
	v_mov_b64_e32 v[8:9], v[182:183]
	v_mov_b64_e32 v[10:11], v[184:185]
	v_pk_fma_f32 v[0:1], v[0:1], v[18:19], v[8:9]
	v_mul_f32_e32 v8, 0x4b800000, v126
	v_cndmask_b32_e32 v8, v126, v8, vcc
	v_rsq_f32_e32 v8, v8
	v_pk_fma_f32 v[2:3], v[2:3], v[16:17], v[10:11]
	flat_store_dwordx4 v[86:87], v[0:3] offset:3072
	v_mul_f32_e32 v9, 0x45800000, v8
	v_cndmask_b32_e32 v122, v8, v9, vcc
	v_mov_b64_e32 v[8:9], v[154:155]
	v_mov_b64_e32 v[10:11], v[156:157]
	v_mov_b64_e32 v[16:17], v[158:159]
	v_mov_b64_e32 v[18:19], v[160:161]
	v_pk_mul_f32 v[24:25], v[30:31], v[122:123] op_sel_hi:[1,0]
	v_pk_mul_f32 v[26:27], v[28:29], v[122:123] op_sel_hi:[1,0]
	v_pk_mul_f32 v[30:31], v[60:61], v[122:123] op_sel_hi:[1,0]
	v_pk_mul_f32 v[28:29], v[38:39], v[122:123] op_sel_hi:[1,0]
	v_pk_mul_f32 v[36:37], v[36:37], v[122:123] op_sel_hi:[1,0]
	v_pk_mul_f32 v[34:35], v[34:35], v[122:123] op_sel_hi:[1,0]
	v_pk_mul_f32 v[38:39], v[118:119], v[122:123] op_sel_hi:[1,0]
	v_pk_mul_f32 v[60:61], v[62:63], v[122:123] op_sel_hi:[1,0]
	ds_bpermute_b32 v62, v67, v65
	s_waitcnt lgkmcnt(0)
	v_add_f32_e32 v62, v65, v62
	ds_bpermute_b32 v63, v69, v62
	s_waitcnt lgkmcnt(0)
	v_add_f32_e32 v62, v62, v63
	ds_bpermute_b32 v63, v71, v62
	s_waitcnt lgkmcnt(0)
	v_add_f32_e32 v62, v62, v63
	ds_bpermute_b32 v63, v73, v62
	s_waitcnt lgkmcnt(0)
	v_add_f32_e32 v62, v62, v63
	ds_bpermute_b32 v63, v123, v62
	s_waitcnt lgkmcnt(0)
	v_add_f32_e32 v62, v62, v63
	ds_bpermute_b32 v63, v124, v62
	s_waitcnt lgkmcnt(0)
	v_add_f32_e32 v65, v62, v63
	v_fmamk_f32 v45, v65, 0xba800000, v45
	v_fmac_f32_e32 v44, 0xba800000, v65
	v_fmamk_f32 v115, v65, 0xba800000, v115
	v_fmac_f32_e32 v114, 0xba800000, v65
	v_pk_mul_f32 v[62:63], v[114:115], v[114:115]
	v_pk_mul_f32 v[118:119], v[44:45], v[44:45]
	v_fmamk_f32 v43, v65, 0xba800000, v43
	v_pk_mov_b32 v[126:127], v[118:119], v[62:63] op_sel:[1,0]
	v_mov_b32_e32 v119, v63
	v_pk_add_f32 v[62:63], v[126:127], v[118:119]
	v_fmac_f32_e32 v42, 0xba800000, v65
	v_fmamk_f32 v113, v65, 0xba800000, v113
	v_fmac_f32_e32 v112, 0xba800000, v65
	v_pk_add_f32 v[62:63], v[62:63], v[62:63] op_sel_hi:[0,1]
	v_pk_mul_f32 v[118:119], v[112:113], v[112:113]
	v_pk_mul_f32 v[126:127], v[42:43], v[42:43]
	v_fmac_f32_e32 v108, 0xba800000, v65
	v_pk_mov_b32 v[128:129], v[126:127], v[118:119] op_sel:[1,0]
	v_mov_b32_e32 v127, v119
	v_fmamk_f32 v109, v65, 0xba800000, v109
	v_fmac_f32_e32 v110, 0xba800000, v65
	v_mul_f32_e32 v62, v108, v108
	v_pk_add_f32 v[118:119], v[128:129], v[126:127]
	v_fmamk_f32 v111, v65, 0xba800000, v111
	v_pk_fma_f32 v[126:127], v[108:109], v[108:109], v[62:63] op_sel_hi:[1,1,0]
	v_mul_f32_e32 v62, v110, v110
	v_pk_add_f32 v[118:119], v[118:119], v[118:119] op_sel_hi:[0,1]
	v_pk_fma_f32 v[128:129], v[110:111], v[110:111], v[62:63] op_sel_hi:[1,1,0]
	v_fmamk_f32 v107, v65, 0xba800000, v107
	v_fmac_f32_e32 v106, 0xba800000, v65
	v_fmamk_f32 v105, v65, 0xba800000, v105
	v_fmac_f32_e32 v104, 0xba800000, v65
	v_mul_f32_e32 v126, v104, v104
	v_mul_f32_e32 v128, v105, v105
	v_mul_f32_e32 v62, v106, v106
	v_pk_fma_f32 v[8:9], v[8:9], v[26:27], v[16:17]
	v_pk_fma_f32 v[10:11], v[10:11], v[24:25], v[18:19]
	flat_store_dwordx4 v[32:33], v[8:11]
	v_mov_b64_e32 v[16:17], v[162:163]
	v_mov_b64_e32 v[18:19], v[164:165]
	v_mov_b64_e32 v[24:25], v[166:167]
	v_mov_b64_e32 v[26:27], v[168:169]
	v_mul_f32_e32 v118, v107, v107
	v_pk_add_f32 v[126:127], v[126:127], v[128:129]
	v_pk_add_f32 v[62:63], v[62:63], v[118:119]
	v_pk_fma_f32 v[28:29], v[16:17], v[28:29], v[24:25]
	v_pk_fma_f32 v[30:31], v[18:19], v[30:31], v[26:27]
	flat_store_dwordx4 v[32:33], v[28:31] offset:1024
	v_mov_b64_e32 v[16:17], v[170:171]
	v_mov_b64_e32 v[18:19], v[172:173]
	v_mov_b64_e32 v[24:25], v[174:175]
	v_mov_b64_e32 v[26:27], v[176:177]
	v_pk_add_f32 v[62:63], v[126:127], v[62:63]
	v_pk_fma_f32 v[24:25], v[16:17], v[34:35], v[24:25]
	v_pk_fma_f32 v[26:27], v[18:19], v[36:37], v[26:27]
	flat_store_dwordx4 v[32:33], v[24:27] offset:2048
	v_mov_b64_e32 v[16:17], v[178:179]
	v_mov_b64_e32 v[18:19], v[180:181]
	v_mov_b64_e32 v[34:35], v[182:183]
	v_mov_b64_e32 v[36:37], v[184:185]
	v_mov_b32_e32 v118, v62
	v_pk_fma_f32 v[16:17], v[16:17], v[60:61], v[34:35]
	v_pk_fma_f32 v[18:19], v[18:19], v[38:39], v[36:37]
	flat_store_dwordx4 v[32:33], v[16:19] offset:3072
	ds_bpermute_b32 v32, v67, v125
	s_waitcnt lgkmcnt(0)
	v_add_f32_e32 v32, v125, v32
	ds_bpermute_b32 v33, v69, v32
	s_waitcnt lgkmcnt(0)
	v_add_f32_e32 v32, v32, v33
	ds_bpermute_b32 v33, v71, v32
	s_waitcnt lgkmcnt(0)
	v_add_f32_e32 v32, v32, v33
	ds_bpermute_b32 v33, v73, v32
	s_waitcnt lgkmcnt(0)
	v_add_f32_e32 v32, v32, v33
	ds_bpermute_b32 v33, v123, v32
	s_waitcnt lgkmcnt(0)
	v_add_f32_e32 v32, v32, v33
	ds_bpermute_b32 v33, v124, v32
	s_waitcnt lgkmcnt(0)
	v_add_f32_e32 v60, v32, v33
	v_fmamk_f32 v51, v60, 0xba800000, v51
	v_fmac_f32_e32 v50, 0xba800000, v60
	v_fmamk_f32 v53, v60, 0xba800000, v53
	v_fmac_f32_e32 v52, 0xba800000, v60
	v_pk_mul_f32 v[32:33], v[52:53], v[52:53]
	v_pk_mul_f32 v[34:35], v[50:51], v[50:51]
	v_fmamk_f32 v57, v60, 0xba800000, v57
	v_pk_mov_b32 v[36:37], v[34:35], v[32:33] op_sel:[1,0]
	v_mov_b32_e32 v35, v33
	v_pk_add_f32 v[32:33], v[36:37], v[34:35]
	v_fmac_f32_e32 v56, 0xba800000, v60
	v_fmamk_f32 v59, v60, 0xba800000, v59
	v_fmac_f32_e32 v58, 0xba800000, v60
	v_pk_add_f32 v[32:33], v[32:33], v[32:33] op_sel_hi:[0,1]
	v_pk_mul_f32 v[34:35], v[58:59], v[58:59]
	v_pk_mul_f32 v[36:37], v[56:57], v[56:57]
	v_fmac_f32_e32 v54, 0xba800000, v60
	v_pk_mov_b32 v[38:39], v[36:37], v[34:35] op_sel:[1,0]
	v_mov_b32_e32 v37, v35
	v_fmamk_f32 v55, v60, 0xba800000, v55
	v_fmac_f32_e32 v116, 0xba800000, v60
	v_mul_f32_e32 v32, v54, v54
	v_pk_add_f32 v[34:35], v[38:39], v[36:37]
	v_fmamk_f32 v117, v60, 0xba800000, v117
	v_pk_fma_f32 v[36:37], v[54:55], v[54:55], v[32:33] op_sel_hi:[1,1,0]
	v_mul_f32_e32 v32, v116, v116
	v_pk_add_f32 v[34:35], v[34:35], v[34:35] op_sel_hi:[0,1]
	v_pk_fma_f32 v[38:39], v[116:117], v[116:117], v[32:33] op_sel_hi:[1,1,0]
	v_fmamk_f32 v49, v60, 0xba800000, v49
	v_fmac_f32_e32 v48, 0xba800000, v60
	v_fmamk_f32 v47, v60, 0xba800000, v47
	v_fmac_f32_e32 v46, 0xba800000, v60
	v_mul_f32_e32 v36, v46, v46
	v_mul_f32_e32 v38, v47, v47
	v_mul_f32_e32 v32, v48, v48
	v_mul_f32_e32 v34, v49, v49
	v_pk_add_f32 v[36:37], v[36:37], v[38:39]
	v_pk_add_f32 v[32:33], v[32:33], v[34:35]
	s_nop 0
	v_pk_add_f32 v[60:61], v[36:37], v[32:33]
	v_mov_b64_e32 v[32:33], v[154:155]
	v_mov_b64_e32 v[34:35], v[156:157]
	v_mov_b64_e32 v[36:37], v[158:159]
	v_mov_b64_e32 v[38:39], v[160:161]
	v_mov_b32_e32 v119, v60
	v_mov_b32_e32 v60, v63
	v_pk_add_f32 v[60:61], v[118:119], v[60:61]
	ds_bpermute_b32 v63, v67, v61
	ds_bpermute_b32 v62, v67, v60
	s_waitcnt lgkmcnt(0)
	v_pk_add_f32 v[60:61], v[60:61], v[62:63]
	ds_bpermute_b32 v63, v69, v61
	ds_bpermute_b32 v62, v69, v60
	s_waitcnt lgkmcnt(0)
	v_pk_add_f32 v[60:61], v[60:61], v[62:63]
	ds_bpermute_b32 v63, v71, v61
	ds_bpermute_b32 v62, v71, v60
	s_waitcnt lgkmcnt(0)
	v_pk_add_f32 v[60:61], v[60:61], v[62:63]
	ds_bpermute_b32 v63, v73, v61
	ds_bpermute_b32 v62, v73, v60
	s_waitcnt lgkmcnt(0)
	v_pk_add_f32 v[60:61], v[60:61], v[62:63]
	ds_bpermute_b32 v63, v123, v61
	ds_bpermute_b32 v62, v123, v60
	s_waitcnt lgkmcnt(0)
	v_pk_add_f32 v[60:61], v[60:61], v[62:63]
	ds_bpermute_b32 v63, v124, v61
	ds_bpermute_b32 v62, v124, v60
	s_waitcnt lgkmcnt(0)
	v_pk_add_f32 v[60:61], v[60:61], v[62:63]
	s_nop 0
	v_pk_fma_f32 v[118:119], v[60:61], s[2:3], v[120:121] op_sel_hi:[1,0,0]
	s_nop 0
	v_mul_f32_e32 v60, 0x4b800000, v119
	v_cmp_gt_f32_e64 s[8:9], s68, v119
	v_cmp_gt_f32_e32 vcc, s68, v118
	s_nop 0
	v_cndmask_b32_e64 v60, v119, v60, s[8:9]
	v_rsq_f32_e32 v60, v60
	s_nop 0
	v_mul_f32_e32 v61, 0x45800000, v60
	v_cndmask_b32_e64 v120, v60, v61, s[8:9]
	v_pk_mul_f32 v[52:53], v[52:53], v[120:121] op_sel_hi:[1,0]
	v_pk_mul_f32 v[50:51], v[50:51], v[120:121] op_sel_hi:[1,0]
	v_pk_mul_f32 v[46:47], v[46:47], v[120:121] op_sel_hi:[1,0]
	v_pk_fma_f32 v[60:61], v[32:33], v[50:51], v[36:37]
	v_pk_fma_f32 v[62:63], v[34:35], v[52:53], v[38:39]
	flat_store_dwordx4 v[40:41], v[60:63]
	v_mov_b64_e32 v[32:33], v[162:163]
	v_mov_b64_e32 v[34:35], v[164:165]
	v_mov_b64_e32 v[36:37], v[166:167]
	v_mov_b64_e32 v[38:39], v[168:169]
	v_pk_mul_f32 v[50:51], v[58:59], v[120:121] op_sel_hi:[1,0]
	v_pk_mul_f32 v[52:53], v[56:57], v[120:121] op_sel_hi:[1,0]
	v_pk_fma_f32 v[58:59], v[34:35], v[50:51], v[38:39]
	v_pk_fma_f32 v[56:57], v[32:33], v[52:53], v[36:37]
	flat_store_dwordx4 v[40:41], v[56:59] offset:1024
	v_mov_b64_e32 v[32:33], v[170:171]
	v_mov_b64_e32 v[34:35], v[172:173]
	v_mov_b64_e32 v[36:37], v[174:175]
	v_mov_b64_e32 v[38:39], v[176:177]
	v_pk_mul_f32 v[50:51], v[116:117], v[120:121] op_sel_hi:[1,0]
	v_pk_mul_f32 v[52:53], v[54:55], v[120:121] op_sel_hi:[1,0]
	v_pk_fma_f32 v[54:55], v[34:35], v[50:51], v[38:39]
	v_pk_fma_f32 v[52:53], v[32:33], v[52:53], v[36:37]
	flat_store_dwordx4 v[40:41], v[52:55] offset:2048
	v_mov_b64_e32 v[32:33], v[178:179]
	v_mov_b64_e32 v[34:35], v[180:181]
	v_mov_b64_e32 v[36:37], v[182:183]
	v_mov_b64_e32 v[38:39], v[184:185]
	v_pk_mul_f32 v[50:51], v[48:49], v[120:121] op_sel_hi:[1,0]
	v_pk_fma_f32 v[48:49], v[32:33], v[46:47], v[36:37]
	v_mul_f32_e32 v32, 0x4b800000, v118
	v_cndmask_b32_e32 v32, v118, v32, vcc
	v_rsq_f32_e32 v32, v32
	v_pk_fma_f32 v[50:51], v[34:35], v[50:51], v[38:39]
	flat_store_dwordx4 v[40:41], v[48:51] offset:3072
	v_mul_f32_e32 v33, 0x45800000, v32
	v_cndmask_b32_e32 v116, v32, v33, vcc
	v_mov_b64_e32 v[32:33], v[154:155]
	v_mov_b64_e32 v[34:35], v[156:157]
	v_mov_b64_e32 v[36:37], v[158:159]
	v_mov_b64_e32 v[38:39], v[160:161]
	v_pk_mul_f32 v[40:41], v[114:115], v[116:117] op_sel_hi:[1,0]
	v_pk_mul_f32 v[44:45], v[44:45], v[116:117] op_sel_hi:[1,0]
	v_pk_mul_f32 v[112:113], v[112:113], v[116:117] op_sel_hi:[1,0]
	v_pk_mul_f32 v[110:111], v[110:111], v[116:117] op_sel_hi:[1,0]
	v_pk_mul_f32 v[108:109], v[108:109], v[116:117] op_sel_hi:[1,0]
	s_andn2_b64 vcc, exec, s[4:5]
	v_pk_fma_f32 v[44:45], v[32:33], v[44:45], v[36:37]
	v_pk_fma_f32 v[46:47], v[34:35], v[40:41], v[38:39]
	flat_store_dwordx4 v[102:103], v[44:47]
	v_mov_b64_e32 v[32:33], v[162:163]
	v_mov_b64_e32 v[34:35], v[164:165]
	v_mov_b64_e32 v[36:37], v[166:167]
	v_mov_b64_e32 v[38:39], v[168:169]
	v_pk_mul_f32 v[40:41], v[42:43], v[116:117] op_sel_hi:[1,0]
	v_pk_fma_f32 v[42:43], v[34:35], v[112:113], v[38:39]
	v_pk_fma_f32 v[40:41], v[32:33], v[40:41], v[36:37]
	flat_store_dwordx4 v[102:103], v[40:43] offset:1024
	v_mov_b64_e32 v[32:33], v[170:171]
	v_mov_b64_e32 v[34:35], v[172:173]
	v_mov_b64_e32 v[36:37], v[174:175]
	v_mov_b64_e32 v[38:39], v[176:177]
	v_pk_fma_f32 v[36:37], v[32:33], v[108:109], v[36:37]
	v_pk_fma_f32 v[38:39], v[34:35], v[110:111], v[38:39]
	flat_store_dwordx4 v[102:103], v[36:39] offset:2048
	v_pk_mul_f32 v[108:109], v[106:107], v[116:117] op_sel_hi:[1,0]
	v_pk_mul_f32 v[110:111], v[104:105], v[116:117] op_sel_hi:[1,0]
	v_mov_b64_e32 v[32:33], v[178:179]
	v_mov_b64_e32 v[34:35], v[180:181]
	v_mov_b64_e32 v[104:105], v[182:183]
	v_mov_b64_e32 v[106:107], v[184:185]
	v_pk_fma_f32 v[32:33], v[32:33], v[110:111], v[104:105]
	v_pk_fma_f32 v[34:35], v[34:35], v[108:109], v[106:107]
	flat_store_dwordx4 v[102:103], v[32:35] offset:3072
	s_cbranch_vccnz .LBB0_50
	v_mad_u64_u32 v[104:105], s[4:5], v88, s7, 0
	v_mad_u64_u32 v[102:103], s[4:5], v92, s7, 0
	v_mad_i32_i24 v105, v89, s7, v105
	v_mad_i32_i24 v103, v93, s7, v103
	v_mad_u64_u32 v[92:93], s[4:5], v98, s7, 0
	v_mad_u64_u32 v[88:89], s[4:5], v100, s7, 0
	v_mad_i32_i24 v93, v99, s7, v93
	v_lshl_add_u64 v[98:99], s[60:61], 0, v[104:105]
	s_mov_b64 s[4:5], 0x6000
	s_mov_b64 s[8:9], 0x7000
	v_mad_i32_i24 v89, v101, s7, v89
	v_lshl_add_u64 v[100:101], v[98:99], 0, s[4:5]
	v_lshl_add_u64 v[98:99], v[98:99], 0, s[8:9]
	v_lshlrev_b32_e32 v152, 2, v66
	v_lshl_add_u64 v[104:105], v[100:101], 0, v[152:153]
	v_lshl_add_u64 v[108:109], v[98:99], 0, v[152:153]
	global_load_dwordx4 v[186:189], v[104:105], off offset:1024
	global_load_dwordx4 v[190:193], v[104:105], off offset:2048
	global_load_dwordx4 v[194:197], v[104:105], off offset:3072
	flat_load_dwordx4 v[104:107], v[104:105]
	s_nop 0
	global_load_dwordx4 v[198:201], v[108:109], off offset:1024
	global_load_dwordx4 v[202:205], v[108:109], off offset:2048
	global_load_dwordx4 v[224:227], v[108:109], off offset:3072
	flat_load_dwordx4 v[108:111], v[108:109]
	s_waitcnt vmcnt(0) lgkmcnt(0)
	v_pk_add_f32 v[110:111], v[110:111], 1.0 op_sel_hi:[1,0]
	v_pk_add_f32 v[108:109], v[108:109], 1.0 op_sel_hi:[1,0]
	v_pk_fma_f32 v[22:23], v[22:23], v[110:111], v[106:107]
	v_pk_fma_f32 v[20:21], v[20:21], v[108:109], v[104:105]
	s_nop 0
	v_cvt_pk_bf16_f32 v20, v20, v21
	v_cvt_pk_bf16_f32 v21, v22, v23
	flat_store_dwordx2 v[84:85], v[20:21]
	v_lshlrev_b32_e32 v20, 2, v68
	v_mov_b32_e32 v21, v153
	v_lshl_add_u64 v[22:23], v[100:101], 0, v[20:21]
	v_mov_b64_e32 v[104:105], v[186:187]
	v_mov_b64_e32 v[106:107], v[188:189]
	v_lshl_add_u64 v[22:23], v[98:99], 0, v[20:21]
	v_mov_b64_e32 v[108:109], v[198:199]
	v_mov_b64_e32 v[110:111], v[200:201]
	v_pk_add_f32 v[22:23], v[110:111], 1.0 op_sel_hi:[1,0]
	v_pk_add_f32 v[108:109], v[108:109], 1.0 op_sel_hi:[1,0]
	v_pk_fma_f32 v[14:15], v[14:15], v[22:23], v[106:107]
	v_pk_fma_f32 v[12:13], v[12:13], v[108:109], v[104:105]
	s_nop 0
	v_cvt_pk_bf16_f32 v12, v12, v13
	v_cvt_pk_bf16_f32 v13, v14, v15
	flat_store_dwordx2 v[84:85], v[12:13] offset:512
	v_lshlrev_b32_e32 v12, 2, v70
	v_mov_b32_e32 v13, v153
	v_lshl_add_u64 v[14:15], v[100:101], 0, v[12:13]
	v_mov_b64_e32 v[104:105], v[190:191]
	v_mov_b64_e32 v[106:107], v[192:193]
	v_lshl_add_u64 v[14:15], v[98:99], 0, v[12:13]
	v_mov_b64_e32 v[108:109], v[202:203]
	v_mov_b64_e32 v[110:111], v[204:205]
	v_pk_add_f32 v[14:15], v[110:111], 1.0 op_sel_hi:[1,0]
	v_pk_add_f32 v[22:23], v[108:109], 1.0 op_sel_hi:[1,0]
	v_pk_fma_f32 v[6:7], v[6:7], v[14:15], v[106:107]
	v_pk_fma_f32 v[4:5], v[4:5], v[22:23], v[104:105]
	s_nop 0
	v_cvt_pk_bf16_f32 v4, v4, v5
	v_cvt_pk_bf16_f32 v5, v6, v7
	flat_store_dwordx2 v[84:85], v[4:5] offset:1024
	v_lshlrev_b32_e32 v4, 2, v72
	v_mov_b32_e32 v5, v153
	v_lshl_add_u64 v[6:7], v[100:101], 0, v[4:5]
	v_mov_b64_e32 v[104:105], v[194:195]
	v_mov_b64_e32 v[106:107], v[196:197]
	v_lshl_add_u64 v[6:7], v[98:99], 0, v[4:5]
	v_mov_b64_e32 v[98:99], v[224:225]
	v_mov_b64_e32 v[100:101], v[226:227]
	v_pk_add_f32 v[6:7], v[100:101], 1.0 op_sel_hi:[1,0]
	v_pk_add_f32 v[14:15], v[98:99], 1.0 op_sel_hi:[1,0]
	v_pk_fma_f32 v[2:3], v[2:3], v[6:7], v[106:107]
	v_pk_fma_f32 v[0:1], v[0:1], v[14:15], v[104:105]
	s_nop 0
	v_cvt_pk_bf16_f32 v0, v0, v1
	v_cvt_pk_bf16_f32 v1, v2, v3
	flat_store_dwordx2 v[84:85], v[0:1] offset:1536
	v_lshl_add_u64 v[0:1], s[60:61], 0, v[102:103]
	v_lshl_add_u64 v[2:3], v[0:1], 0, s[4:5]
	v_lshl_add_u64 v[0:1], v[0:1], 0, s[8:9]
	v_lshl_add_u64 v[6:7], v[2:3], 0, v[152:153]
	global_load_dwordx4 v[186:189], v[6:7], off offset:1024
	global_load_dwordx4 v[190:193], v[6:7], off offset:2048
	global_load_dwordx4 v[194:197], v[6:7], off offset:3072
	flat_load_dwordx4 v[98:101], v[6:7]
	v_lshl_add_u64 v[6:7], v[0:1], 0, v[152:153]
	global_load_dwordx4 v[198:201], v[6:7], off offset:1024
	global_load_dwordx4 v[202:205], v[6:7], off offset:2048
	global_load_dwordx4 v[224:227], v[6:7], off offset:3072
	flat_load_dwordx4 v[102:105], v[6:7]
	s_waitcnt vmcnt(0) lgkmcnt(0)
	v_pk_add_f32 v[6:7], v[104:105], 1.0 op_sel_hi:[1,0]
	v_pk_add_f32 v[14:15], v[102:103], 1.0 op_sel_hi:[1,0]
	v_pk_fma_f32 v[6:7], v[10:11], v[6:7], v[100:101]
	v_pk_fma_f32 v[8:9], v[8:9], v[14:15], v[98:99]
	v_lshl_add_u64 v[10:11], v[82:83], 0, v[90:91]
	v_cvt_pk_bf16_f32 v8, v8, v9
	v_cvt_pk_bf16_f32 v9, v6, v7
	flat_store_dwordx2 v[10:11], v[8:9]
	v_lshl_add_u64 v[6:7], v[2:3], 0, v[20:21]
	v_lshl_add_u64 v[14:15], v[0:1], 0, v[20:21]
	v_mov_b64_e32 v[6:7], v[186:187]
	v_mov_b64_e32 v[8:9], v[188:189]
	s_nop 0
	v_mov_b64_e32 v[98:99], v[198:199]
	v_mov_b64_e32 v[100:101], v[200:201]
	v_pk_add_f32 v[14:15], v[100:101], 1.0 op_sel_hi:[1,0]
	v_pk_add_f32 v[22:23], v[98:99], 1.0 op_sel_hi:[1,0]
	v_pk_fma_f32 v[8:9], v[30:31], v[14:15], v[8:9]
	v_pk_fma_f32 v[6:7], v[28:29], v[22:23], v[6:7]
	v_lshl_add_u64 v[14:15], v[0:1], 0, v[12:13]
	v_cvt_pk_bf16_f32 v6, v6, v7
	v_cvt_pk_bf16_f32 v7, v8, v9
	flat_store_dwordx2 v[10:11], v[6:7] offset:512
	v_lshl_add_u64 v[6:7], v[2:3], 0, v[12:13]
	v_mov_b64_e32 v[6:7], v[190:191]
	v_mov_b64_e32 v[8:9], v[192:193]
	v_lshl_add_u64 v[2:3], v[2:3], 0, v[4:5]
	v_mov_b64_e32 v[28:29], v[202:203]
	v_mov_b64_e32 v[30:31], v[204:205]
	v_lshl_add_u64 v[0:1], v[0:1], 0, v[4:5]
	v_pk_add_f32 v[14:15], v[30:31], 1.0 op_sel_hi:[1,0]
	v_pk_add_f32 v[22:23], v[28:29], 1.0 op_sel_hi:[1,0]
	v_pk_fma_f32 v[8:9], v[26:27], v[14:15], v[8:9]
	v_pk_fma_f32 v[6:7], v[24:25], v[22:23], v[6:7]
	s_nop 0
	v_cvt_pk_bf16_f32 v6, v6, v7
	v_cvt_pk_bf16_f32 v7, v8, v9
	flat_store_dwordx2 v[10:11], v[6:7] offset:1024
	v_mov_b64_e32 v[6:7], v[194:195]
	v_mov_b64_e32 v[8:9], v[196:197]
	s_nop 0
	v_mov_b64_e32 v[0:1], v[224:225]
	v_mov_b64_e32 v[2:3], v[226:227]
	v_pk_add_f32 v[2:3], v[2:3], 1.0 op_sel_hi:[1,0]
	v_pk_add_f32 v[0:1], v[0:1], 1.0 op_sel_hi:[1,0]
	v_pk_fma_f32 v[2:3], v[18:19], v[2:3], v[8:9]
	v_pk_fma_f32 v[0:1], v[16:17], v[0:1], v[6:7]
	v_lshl_add_u64 v[18:19], v[82:83], 0, v[94:95]
	v_cvt_pk_bf16_f32 v0, v0, v1
	v_cvt_pk_bf16_f32 v1, v2, v3
	flat_store_dwordx2 v[10:11], v[0:1] offset:1536
	v_lshl_add_u64 v[0:1], s[60:61], 0, v[92:93]
	v_lshl_add_u64 v[2:3], v[0:1], 0, s[4:5]
	v_lshl_add_u64 v[0:1], v[0:1], 0, s[8:9]
	v_lshl_add_u64 v[6:7], v[2:3], 0, v[152:153]
	v_lshl_add_u64 v[10:11], v[0:1], 0, v[152:153]
	global_load_dwordx4 v[186:189], v[6:7], off offset:1024
	global_load_dwordx4 v[190:193], v[6:7], off offset:2048
	global_load_dwordx4 v[194:197], v[6:7], off offset:3072
	flat_load_dwordx4 v[6:9], v[6:7]
	s_nop 0
	global_load_dwordx4 v[198:201], v[10:11], off offset:1024
	global_load_dwordx4 v[202:205], v[10:11], off offset:2048
	global_load_dwordx4 v[224:227], v[10:11], off offset:3072
	flat_load_dwordx4 v[14:17], v[10:11]
	s_waitcnt vmcnt(0) lgkmcnt(0)
	v_pk_add_f32 v[10:11], v[16:17], 1.0 op_sel_hi:[1,0]
	v_pk_add_f32 v[14:15], v[14:15], 1.0 op_sel_hi:[1,0]
	v_pk_fma_f32 v[8:9], v[62:63], v[10:11], v[8:9]
	v_pk_fma_f32 v[6:7], v[60:61], v[14:15], v[6:7]
	v_lshl_add_u64 v[10:11], v[82:83], 0, v[96:97]
	v_cvt_pk_bf16_f32 v6, v6, v7
	v_cvt_pk_bf16_f32 v7, v8, v9
	flat_store_dwordx2 v[10:11], v[6:7]
	v_lshl_add_u64 v[6:7], v[2:3], 0, v[20:21]
	v_lshl_add_u64 v[14:15], v[0:1], 0, v[20:21]
	v_mov_b64_e32 v[6:7], v[186:187]
	v_mov_b64_e32 v[8:9], v[188:189]
	s_nop 0
	v_mov_b64_e32 v[14:15], v[198:199]
	v_mov_b64_e32 v[16:17], v[200:201]
	v_pk_add_f32 v[16:17], v[16:17], 1.0 op_sel_hi:[1,0]
	v_pk_add_f32 v[14:15], v[14:15], 1.0 op_sel_hi:[1,0]
	v_pk_fma_f32 v[8:9], v[58:59], v[16:17], v[8:9]
	v_pk_fma_f32 v[6:7], v[56:57], v[14:15], v[6:7]
	v_lshl_add_u64 v[14:15], v[0:1], 0, v[12:13]
	v_cvt_pk_bf16_f32 v6, v6, v7
	v_cvt_pk_bf16_f32 v7, v8, v9
	flat_store_dwordx2 v[10:11], v[6:7] offset:512
	v_lshl_add_u64 v[6:7], v[2:3], 0, v[12:13]
	v_mov_b64_e32 v[6:7], v[190:191]
	v_mov_b64_e32 v[8:9], v[192:193]
	v_lshl_add_u64 v[2:3], v[2:3], 0, v[4:5]
	v_mov_b64_e32 v[14:15], v[202:203]
	v_mov_b64_e32 v[16:17], v[204:205]
	v_lshl_add_u64 v[0:1], v[0:1], 0, v[4:5]
	v_pk_add_f32 v[16:17], v[16:17], 1.0 op_sel_hi:[1,0]
	v_pk_add_f32 v[14:15], v[14:15], 1.0 op_sel_hi:[1,0]
	v_pk_fma_f32 v[8:9], v[54:55], v[16:17], v[8:9]
	v_pk_fma_f32 v[6:7], v[52:53], v[14:15], v[6:7]
	s_nop 0
	v_cvt_pk_bf16_f32 v6, v6, v7
	v_cvt_pk_bf16_f32 v7, v8, v9
	flat_store_dwordx2 v[10:11], v[6:7] offset:1024
	v_mov_b64_e32 v[6:7], v[194:195]
	v_mov_b64_e32 v[8:9], v[196:197]
	s_nop 0
	v_mov_b64_e32 v[0:1], v[224:225]
	v_mov_b64_e32 v[2:3], v[226:227]
	v_pk_add_f32 v[2:3], v[2:3], 1.0 op_sel_hi:[1,0]
	v_pk_add_f32 v[0:1], v[0:1], 1.0 op_sel_hi:[1,0]
	v_pk_fma_f32 v[2:3], v[50:51], v[2:3], v[8:9]
	v_pk_fma_f32 v[0:1], v[48:49], v[0:1], v[6:7]
	s_nop 0
	v_cvt_pk_bf16_f32 v0, v0, v1
	v_cvt_pk_bf16_f32 v1, v2, v3
	flat_store_dwordx2 v[10:11], v[0:1] offset:1536
	v_lshl_add_u64 v[0:1], s[60:61], 0, v[88:89]
	v_lshl_add_u64 v[2:3], v[0:1], 0, s[4:5]
	v_lshl_add_u64 v[0:1], v[0:1], 0, s[8:9]
	v_lshl_add_u64 v[6:7], v[2:3], 0, v[152:153]
	v_lshl_add_u64 v[10:11], v[0:1], 0, v[152:153]
	global_load_dwordx4 v[186:189], v[6:7], off offset:1024
	global_load_dwordx4 v[190:193], v[6:7], off offset:2048
	global_load_dwordx4 v[194:197], v[6:7], off offset:3072
	flat_load_dwordx4 v[6:9], v[6:7]
	s_nop 0
	global_load_dwordx4 v[198:201], v[10:11], off offset:1024
	global_load_dwordx4 v[202:205], v[10:11], off offset:2048
	global_load_dwordx4 v[224:227], v[10:11], off offset:3072
	flat_load_dwordx4 v[14:17], v[10:11]
	s_waitcnt vmcnt(0) lgkmcnt(0)
	v_pk_add_f32 v[10:11], v[16:17], 1.0 op_sel_hi:[1,0]
	v_pk_add_f32 v[14:15], v[14:15], 1.0 op_sel_hi:[1,0]
	v_pk_fma_f32 v[8:9], v[46:47], v[10:11], v[8:9]
	v_pk_fma_f32 v[6:7], v[44:45], v[14:15], v[6:7]
	v_lshl_add_u64 v[10:11], v[0:1], 0, v[20:21]
	v_cvt_pk_bf16_f32 v6, v6, v7
	v_cvt_pk_bf16_f32 v7, v8, v9
	flat_store_dwordx2 v[18:19], v[6:7]
	v_lshl_add_u64 v[6:7], v[2:3], 0, v[20:21]
	v_mov_b64_e32 v[6:7], v[186:187]
	v_mov_b64_e32 v[8:9], v[188:189]
	s_nop 0
	v_mov_b64_e32 v[14:15], v[198:199]
	v_mov_b64_e32 v[16:17], v[200:201]
	v_pk_add_f32 v[10:11], v[16:17], 1.0 op_sel_hi:[1,0]
	v_pk_add_f32 v[14:15], v[14:15], 1.0 op_sel_hi:[1,0]
	v_pk_fma_f32 v[8:9], v[42:43], v[10:11], v[8:9]
	v_pk_fma_f32 v[6:7], v[40:41], v[14:15], v[6:7]
	v_lshl_add_u64 v[10:11], v[0:1], 0, v[12:13]
	v_cvt_pk_bf16_f32 v6, v6, v7
	v_cvt_pk_bf16_f32 v7, v8, v9
	flat_store_dwordx2 v[18:19], v[6:7] offset:512
	v_lshl_add_u64 v[6:7], v[2:3], 0, v[12:13]
	v_mov_b64_e32 v[6:7], v[190:191]
	v_mov_b64_e32 v[8:9], v[192:193]
	v_lshl_add_u64 v[2:3], v[2:3], 0, v[4:5]
	v_mov_b64_e32 v[10:11], v[202:203]
	v_mov_b64_e32 v[12:13], v[204:205]
	v_lshl_add_u64 v[0:1], v[0:1], 0, v[4:5]
	v_pk_add_f32 v[12:13], v[12:13], 1.0 op_sel_hi:[1,0]
	v_pk_add_f32 v[10:11], v[10:11], 1.0 op_sel_hi:[1,0]
	v_pk_fma_f32 v[8:9], v[38:39], v[12:13], v[8:9]
	v_pk_fma_f32 v[6:7], v[36:37], v[10:11], v[6:7]
	s_nop 0
	v_cvt_pk_bf16_f32 v6, v6, v7
	v_cvt_pk_bf16_f32 v7, v8, v9
	flat_store_dwordx2 v[18:19], v[6:7] offset:1024
	v_mov_b64_e32 v[6:7], v[194:195]
	v_mov_b64_e32 v[8:9], v[196:197]
	s_nop 0
	v_mov_b64_e32 v[0:1], v[224:225]
	v_mov_b64_e32 v[2:3], v[226:227]
	v_pk_add_f32 v[2:3], v[2:3], 1.0 op_sel_hi:[1,0]
	v_pk_add_f32 v[0:1], v[0:1], 1.0 op_sel_hi:[1,0]
	v_pk_fma_f32 v[2:3], v[34:35], v[2:3], v[8:9]
	v_pk_fma_f32 v[0:1], v[32:33], v[0:1], v[6:7]
	s_nop 0
	v_cvt_pk_bf16_f32 v0, v0, v1
	v_cvt_pk_bf16_f32 v1, v2, v3
	flat_store_dwordx2 v[18:19], v[0:1] offset:1536
	s_branch .LBB0_50

.Lln_stg_180:
	s_cmp_eq_u32 s99, 1
	v_and_b32_e32 v210, 63, v206
	v_lshlrev_b32_e32 v210, 4, v210
	v_and_b32_e32 v211, 0x1c0, v206
	v_lshl_add_u32 v210, v211, 7, v210
	global_load_dwordx4 v[214:217], v[106:107], off
	global_load_dwordx4 v[218:221], v[108:109], off
	global_load_dwordx4 v[236:239], v[106:107], off offset:1024
	global_load_dwordx4 v[240:243], v[108:109], off offset:1024
	s_waitcnt vmcnt(0)
	ds_write_b128 v210, v[214:217]
	ds_write_b128 v210, v[218:221] offset:4096
	ds_write_b128 v210, v[236:239] offset:1024
	ds_write_b128 v210, v[240:243] offset:5120
	s_waitcnt lgkmcnt(0)
	global_load_dwordx4 v[214:217], v[106:107], off offset:2048
	global_load_dwordx4 v[218:221], v[108:109], off offset:2048
	global_load_dwordx4 v[236:239], v[106:107], off offset:3072
	global_load_dwordx4 v[240:243], v[108:109], off offset:3072
	s_waitcnt vmcnt(0)
	ds_write_b128 v210, v[214:217] offset:2048
	ds_write_b128 v210, v[218:221] offset:6144
	ds_write_b128 v210, v[236:239] offset:3072
	ds_write_b128 v210, v[240:243] offset:7168
	s_waitcnt lgkmcnt(0)
	v_readlane_b32 s4, v254, 27
	v_readlane_b32 s5, v254, 28
	v_cmp_gt_i32_e64 s[8:9], s27, v96
	v_cmp_lt_i32_e64 s[10:11], s33, v96
	s_mov_b64 s[12:13], -1
	s_and_b64 vcc, exec, s[4:5]
	s_cbranch_vccz .LBB0_182
	v_readlane_b32 s4, v254, 18
	v_readlane_b32 s5, v254, 19
	v_ashrrev_i32_e32 v139, 31, v96
	v_mov_b32_e32 v138, v96
	v_lshl_add_u64 v[0:1], s[4:5], 0, v[116:117]
	s_mov_b64 s[12:13], 0

.Lln_stg_225:
	s_cmp_eq_u32 s99, 1
	global_load_dwordx4 v[154:157], v[74:75], off
	global_load_dwordx4 v[158:161], v[76:77], off
	global_load_dwordx4 v[162:165], v[74:75], off offset:1024
	global_load_dwordx4 v[166:169], v[76:77], off offset:1024
	global_load_dwordx4 v[170:173], v[74:75], off offset:2048
	global_load_dwordx4 v[174:177], v[76:77], off offset:2048
	global_load_dwordx4 v[178:181], v[74:75], off offset:3072
	global_load_dwordx4 v[182:185], v[76:77], off offset:3072
	v_add_u32_e32 v0, 0xfffff000, v64
	v_ashrrev_i32_e32 v0, 10, v0
	v_add_u32_e32 v0, 1, v0
	v_cmp_lt_i32_e32 vcc, s33, v64
	global_load_dwordx4 v[186:189], v[86:87], off offset:1024
	global_load_dwordx4 v[190:193], v[86:87], off offset:2048
	global_load_dwordx4 v[194:197], v[86:87], off offset:3072
	flat_load_dwordx4 v[8:11], v[86:87]
	s_mov_b64 s[8:9], 0x1000000
	v_cndmask_b32_e32 v94, 0, v0, vcc
	v_add_u32_e32 v0, s38, v64
	v_cmp_lt_i32_e32 vcc, s6, v0
	v_ashrrev_i32_e32 v95, 31, v94
	v_lshl_add_u64 v[4:5], v[94:95], 0, s[28:29]
	v_cndmask_b32_e32 v0, v0, v64, vcc
	v_add_u32_e32 v1, 0xfffff000, v0
	v_ashrrev_i32_e32 v1, 10, v1
	v_add_u32_e32 v1, 1, v1
	v_cmp_lt_i32_e32 vcc, s33, v0
	v_mad_u64_u32 v[2:3], s[4:5], v4, s7, v[78:79]
	s_nop 0
	v_cndmask_b32_e32 v92, 0, v1, vcc
	v_add_u32_e32 v1, s35, v64
	v_cmp_lt_i32_e32 vcc, s6, v1
	s_mov_b32 s4, 0x1000000
	v_mad_i32_i24 v3, v5, s7, v3
	v_cndmask_b32_e32 v18, v1, v64, vcc
	v_add_u32_e32 v1, 0xfffff000, v18
	v_ashrrev_i32_e32 v1, 10, v1
	v_add_u32_e32 v1, 1, v1
	v_cmp_lt_i32_e32 vcc, s33, v18
	global_load_dwordx4 v[198:201], v[2:3], off offset:1024
	global_load_dwordx4 v[202:205], v[2:3], off offset:2048
	global_load_dwordx4 v[224:227], v[2:3], off offset:3072
	flat_load_dwordx4 v[12:15], v[2:3]
	v_ashrrev_i32_e32 v93, 31, v92
	v_cndmask_b32_e32 v90, 0, v1, vcc
	v_add_u32_e32 v1, s26, v64
	v_cmp_lt_i32_e32 vcc, s6, v1
	v_lshlrev_b32_e32 v152, 1, v66
	v_lshlrev_b32_e32 v42, 1, v68
	v_cndmask_b32_e32 v16, v1, v64, vcc
	v_add_u32_e32 v1, 0xfffff000, v16
	v_ashrrev_i32_e32 v1, 10, v1
	v_add_u32_e32 v1, 1, v1
	v_cmp_lt_i32_e32 vcc, s33, v16
	v_mov_b32_e32 v43, v153
	v_lshlrev_b32_e32 v104, 1, v70
	v_cndmask_b32_e32 v88, 0, v1, vcc
	v_add_co_u32_e32 v4, vcc, s4, v84
	s_brev_b32 s4, 64
	s_nop 0
	v_addc_co_u32_e32 v5, vcc, 0, v85, vcc
	global_load_dwordx2 v[228:229], v[4:5], off offset:512
	global_load_dwordx2 v[230:231], v[4:5], off offset:1024
	global_load_dwordx2 v[232:233], v[4:5], off offset:1536
	flat_load_dwordx2 v[6:7], v[4:5]
	v_mov_b32_e32 v105, v153
	v_lshlrev_b32_e32 v106, 1, v72
	v_mov_b32_e32 v107, v153
	v_ashrrev_i32_e32 v19, 31, v18
	v_ashrrev_i32_e32 v91, 31, v90
	v_lshlrev_b64 v[100:101], 11, v[18:19]
	v_ashrrev_i32_e32 v17, 31, v16
	v_ashrrev_i32_e32 v89, 31, v88
	s_waitcnt vmcnt(0) lgkmcnt(0)
	v_pk_mul_f32 v[14:15], v[14:15], 0.5 op_sel_hi:[1,0]
	v_pk_mul_f32 v[12:13], v[12:13], 0.5 op_sel_hi:[1,0]
	v_lshlrev_b32_e32 v20, 16, v6
	v_and_b32_e32 v21, 0xffff0000, v6
	v_add_co_u32_e32 v6, vcc, s4, v84
	v_lshlrev_b32_e32 v22, 16, v7
	v_and_b32_e32 v23, 0xffff0000, v7
	v_addc_co_u32_e32 v7, vcc, 0, v85, vcc
	global_load_dwordx2 v[234:235], v[6:7], off offset:512
	global_load_dwordx2 v[236:237], v[6:7], off offset:1024
	global_load_dwordx2 v[238:239], v[6:7], off offset:1536
	flat_load_dwordx2 v[24:25], v[6:7]
	s_waitcnt vmcnt(0) lgkmcnt(0)
	v_lshlrev_b32_e32 v26, 16, v24
	v_and_b32_e32 v27, 0xffff0000, v24
	v_lshlrev_b32_e32 v24, 16, v25
	v_and_b32_e32 v25, 0xffff0000, v25
	v_pk_add_f32 v[20:21], v[20:21], v[26:27]
	v_pk_add_f32 v[22:23], v[22:23], v[24:25]
	v_pk_mul_f32 v[12:13], v[12:13], v[20:21]
	v_pk_mul_f32 v[14:15], v[14:15], v[22:23]
	v_pk_fma_f32 v[8:9], v[8:9], s[42:43], v[12:13] op_sel_hi:[1,0,1]
	v_pk_fma_f32 v[10:11], v[10:11], s[42:43], v[14:15] op_sel_hi:[1,0,1]
	v_mov_b32_e32 v14, v8
	v_pk_mov_b32 v[12:13], v[8:9], v[10:11] op_sel:[1,0]
	v_mov_b32_e32 v15, v11
	v_pk_add_f32 v[12:13], v[12:13], v[14:15]
	s_nop 0
	v_add_f32_e32 v1, v12, v13
	v_mov_b64_e32 v[12:13], v[186:187]
	v_mov_b64_e32 v[14:15], v[188:189]
	v_mov_b64_e32 v[20:21], v[198:199]
	v_mov_b64_e32 v[22:23], v[200:201]
	v_mov_b64_e32 v[24:25], v[228:229]
	v_mov_b64_e32 v[30:31], v[234:235]
	v_add_f32_e32 v28, 0, v1
	v_ashrrev_i32_e32 v1, 31, v0
	v_lshlrev_b64 v[96:97], 11, v[0:1]
	v_pk_mul_f32 v[22:23], v[22:23], 0.5 op_sel_hi:[1,0]
	v_lshlrev_b32_e32 v26, 16, v24
	v_and_b32_e32 v27, 0xffff0000, v24
	v_lshlrev_b32_e32 v24, 16, v25
	v_and_b32_e32 v25, 0xffff0000, v25
	v_lshlrev_b32_e32 v32, 16, v30
	v_and_b32_e32 v33, 0xffff0000, v30
	v_lshlrev_b32_e32 v30, 16, v31
	v_and_b32_e32 v31, 0xffff0000, v31
	v_pk_mul_f32 v[20:21], v[20:21], 0.5 op_sel_hi:[1,0]
	v_pk_add_f32 v[26:27], v[26:27], v[32:33]
	v_pk_add_f32 v[24:25], v[24:25], v[30:31]
	v_pk_mul_f32 v[20:21], v[20:21], v[26:27]
	v_pk_mul_f32 v[22:23], v[22:23], v[24:25]
	v_pk_fma_f32 v[12:13], v[12:13], s[42:43], v[20:21] op_sel_hi:[1,0,1]
	v_pk_fma_f32 v[14:15], v[14:15], s[42:43], v[22:23] op_sel_hi:[1,0,1]
	v_mov_b32_e32 v22, v12
	v_pk_mov_b32 v[20:21], v[12:13], v[14:15] op_sel:[1,0]
	v_mov_b32_e32 v23, v15
	v_pk_add_f32 v[20:21], v[20:21], v[22:23]
	s_nop 0
	v_pk_add_f32 v[30:31], v[20:21], v[20:21] op_sel:[0,1] op_sel_hi:[1,0]
	v_mov_b64_e32 v[20:21], v[190:191]
	v_mov_b64_e32 v[22:23], v[192:193]
	v_mov_b64_e32 v[24:25], v[202:203]
	v_mov_b64_e32 v[26:27], v[204:205]
	v_mov_b64_e32 v[32:33], v[230:231]
	v_mov_b64_e32 v[36:37], v[236:237]
	v_pk_mul_f32 v[26:27], v[26:27], 0.5 op_sel_hi:[1,0]
	v_lshlrev_b32_e32 v34, 16, v32
	v_and_b32_e32 v35, 0xffff0000, v32
	v_lshlrev_b32_e32 v32, 16, v33
	v_and_b32_e32 v33, 0xffff0000, v33
	v_lshlrev_b32_e32 v38, 16, v36
	v_and_b32_e32 v39, 0xffff0000, v36
	v_lshlrev_b32_e32 v36, 16, v37
	v_and_b32_e32 v37, 0xffff0000, v37
	v_pk_mul_f32 v[24:25], v[24:25], 0.5 op_sel_hi:[1,0]
	v_pk_add_f32 v[32:33], v[32:33], v[36:37]
	v_pk_add_f32 v[34:35], v[34:35], v[38:39]
	v_pk_mul_f32 v[26:27], v[26:27], v[32:33]
	v_pk_mul_f32 v[24:25], v[24:25], v[34:35]
	v_pk_fma_f32 v[22:23], v[22:23], s[42:43], v[26:27] op_sel_hi:[1,0,1]
	v_pk_fma_f32 v[20:21], v[20:21], s[42:43], v[24:25] op_sel_hi:[1,0,1]
	v_mov_b64_e32 v[24:25], v[194:195]
	v_mov_b64_e32 v[26:27], v[196:197]
	v_mov_b64_e32 v[32:33], v[224:225]
	v_mov_b64_e32 v[34:35], v[226:227]
	s_nop 0
	v_mov_b64_e32 v[2:3], v[232:233]
	v_add_f32_e32 v36, v20, v21
	v_mov_b64_e32 v[6:7], v[238:239]
	v_add_f32_e32 v38, v22, v23
	v_pk_mul_f32 v[34:35], v[34:35], 0.5 op_sel_hi:[1,0]
	v_lshlrev_b32_e32 v4, 16, v2
	v_and_b32_e32 v5, 0xffff0000, v2
	v_lshlrev_b32_e32 v2, 16, v3
	v_and_b32_e32 v3, 0xffff0000, v3
	v_lshlrev_b32_e32 v40, 16, v6
	v_and_b32_e32 v41, 0xffff0000, v6
	v_lshlrev_b32_e32 v6, 16, v7
	v_and_b32_e32 v7, 0xffff0000, v7
	v_pk_mul_f32 v[32:33], v[32:33], 0.5 op_sel_hi:[1,0]
	v_pk_add_f32 v[2:3], v[2:3], v[6:7]
	v_pk_add_f32 v[4:5], v[4:5], v[40:41]
	v_pk_mul_f32 v[2:3], v[34:35], v[2:3]
	v_pk_mul_f32 v[4:5], v[32:33], v[4:5]
	v_pk_fma_f32 v[26:27], v[26:27], s[42:43], v[2:3] op_sel_hi:[1,0,1]
	v_pk_fma_f32 v[24:25], v[24:25], s[42:43], v[4:5] op_sel_hi:[1,0,1]
	v_mov_b32_e32 v37, v26
	v_mov_b32_e32 v29, v24
	v_mov_b32_e32 v31, v25
	v_mov_b32_e32 v39, v27
	v_lshl_add_u64 v[34:35], s[56:57], 0, v[96:97]
	v_pk_add_f32 v[2:3], v[28:29], v[30:31]
	v_pk_add_f32 v[4:5], v[36:37], v[38:39]
	v_lshl_add_u64 v[6:7], v[92:93], 0, s[28:29]
	v_lshl_add_u64 v[46:47], v[34:35], 0, s[8:9]
	v_pk_add_f32 v[2:3], v[2:3], v[4:5]
	v_mad_u64_u32 v[4:5], s[4:5], v6, s7, v[78:79]
	v_lshl_add_u64 v[48:49], v[34:35], 0, v[152:153]
	v_lshl_add_u64 v[36:37], v[46:47], 0, v[152:153]
	v_mad_i32_i24 v5, v7, s7, v5
	global_load_dwordx2 v[228:229], v[48:49], off offset:512
	global_load_dwordx2 v[230:231], v[48:49], off offset:1024
	global_load_dwordx2 v[232:233], v[48:49], off offset:1536
	flat_load_dwordx2 v[6:7], v[48:49]
	v_add_f32_e32 v120, v2, v3
	global_load_dwordx2 v[234:235], v[36:37], off offset:512
	global_load_dwordx2 v[236:237], v[36:37], off offset:1024
	global_load_dwordx2 v[238:239], v[36:37], off offset:1536
	flat_load_dwordx2 v[36:37], v[36:37]
	v_lshlrev_b64 v[2:3], 12, v[0:1]
	global_load_dwordx4 v[186:189], v[4:5], off offset:1024
	global_load_dwordx4 v[190:193], v[4:5], off offset:2048
	global_load_dwordx4 v[194:197], v[4:5], off offset:3072
	flat_load_dwordx4 v[28:31], v[4:5]
	v_lshl_add_u64 v[32:33], v[80:81], 0, v[2:3]
	global_load_dwordx4 v[198:201], v[32:33], off offset:1024
	global_load_dwordx4 v[202:205], v[32:33], off offset:2048
	global_load_dwordx4 v[224:227], v[32:33], off offset:3072
	flat_load_dwordx4 v[0:3], v[32:33]
	v_lshl_add_u64 v[44:45], v[46:47], 0, v[42:43]
	v_lshl_add_u64 v[52:53], v[46:47], 0, v[104:105]
	v_lshl_add_u64 v[46:47], v[46:47], 0, v[106:107]
	s_waitcnt vmcnt(0) lgkmcnt(0)
	v_lshlrev_b32_e32 v34, 16, v6
	v_and_b32_e32 v35, 0xffff0000, v6
	v_lshlrev_b32_e32 v6, 16, v7
	v_and_b32_e32 v7, 0xffff0000, v7
	v_lshlrev_b32_e32 v38, 16, v36
	v_and_b32_e32 v39, 0xffff0000, v36
	v_lshlrev_b32_e32 v36, 16, v37
	v_and_b32_e32 v37, 0xffff0000, v37
	v_pk_mul_f32 v[30:31], v[30:31], 0.5 op_sel_hi:[1,0]
	v_pk_mul_f32 v[28:29], v[28:29], 0.5 op_sel_hi:[1,0]
	v_pk_add_f32 v[34:35], v[34:35], v[38:39]
	v_pk_add_f32 v[6:7], v[6:7], v[36:37]
	v_pk_mul_f32 v[28:29], v[28:29], v[34:35]
	v_pk_mul_f32 v[6:7], v[30:31], v[6:7]
	v_pk_fma_f32 v[34:35], v[0:1], s[42:43], v[28:29] op_sel_hi:[1,0,1]
	v_pk_fma_f32 v[36:37], v[2:3], s[42:43], v[6:7] op_sel_hi:[1,0,1]
	v_mov_b32_e32 v2, v34
	v_pk_mov_b32 v[0:1], v[34:35], v[36:37] op_sel:[1,0]
	v_mov_b32_e32 v3, v37
	v_pk_add_f32 v[0:1], v[0:1], v[2:3]
	s_nop 0
	v_add_f32_e32 v0, v0, v1
	v_add_f32_e32 v40, 0, v0
	v_mov_b64_e32 v[0:1], v[198:199]
	v_mov_b64_e32 v[2:3], v[200:201]
	v_mov_b64_e32 v[28:29], v[186:187]
	v_mov_b64_e32 v[30:31], v[188:189]
	v_mov_b64_e32 v[6:7], v[228:229]
	v_pk_mul_f32 v[30:31], v[30:31], 0.5 op_sel_hi:[1,0]
	v_mov_b64_e32 v[44:45], v[234:235]
	v_lshlrev_b32_e32 v38, 16, v6
	v_and_b32_e32 v39, 0xffff0000, v6
	v_lshlrev_b32_e32 v6, 16, v7
	v_and_b32_e32 v7, 0xffff0000, v7
	v_pk_mul_f32 v[28:29], v[28:29], 0.5 op_sel_hi:[1,0]
	v_lshlrev_b32_e32 v50, 16, v44
	v_and_b32_e32 v51, 0xffff0000, v44
	v_lshlrev_b32_e32 v44, 16, v45
	v_and_b32_e32 v45, 0xffff0000, v45
	v_pk_add_f32 v[38:39], v[38:39], v[50:51]
	v_pk_add_f32 v[6:7], v[6:7], v[44:45]
	v_pk_mul_f32 v[28:29], v[28:29], v[38:39]
	v_pk_mul_f32 v[6:7], v[30:31], v[6:7]
	v_pk_fma_f32 v[38:39], v[0:1], s[42:43], v[28:29] op_sel_hi:[1,0,1]
	v_pk_fma_f32 v[60:61], v[2:3], s[42:43], v[6:7] op_sel_hi:[1,0,1]
	v_mov_b32_e32 v2, v38
	v_pk_mov_b32 v[0:1], v[38:39], v[60:61] op_sel:[1,0]
	v_mov_b32_e32 v3, v61
	v_pk_add_f32 v[0:1], v[0:1], v[2:3]
	s_nop 0
	v_pk_add_f32 v[44:45], v[0:1], v[0:1] op_sel:[0,1] op_sel_hi:[1,0]
	v_mov_b64_e32 v[0:1], v[202:203]
	v_mov_b64_e32 v[2:3], v[204:205]
	v_mov_b64_e32 v[28:29], v[190:191]
	v_mov_b64_e32 v[30:31], v[192:193]
	v_mov_b64_e32 v[6:7], v[230:231]
	v_pk_mul_f32 v[30:31], v[30:31], 0.5 op_sel_hi:[1,0]
	v_mov_b64_e32 v[52:53], v[236:237]
	v_lshlrev_b32_e32 v50, 16, v6
	v_and_b32_e32 v51, 0xffff0000, v6
	v_lshlrev_b32_e32 v6, 16, v7
	v_and_b32_e32 v7, 0xffff0000, v7
	v_pk_mul_f32 v[28:29], v[28:29], 0.5 op_sel_hi:[1,0]
	v_lshlrev_b32_e32 v54, 16, v52
	v_and_b32_e32 v55, 0xffff0000, v52
	v_lshlrev_b32_e32 v52, 16, v53
	v_and_b32_e32 v53, 0xffff0000, v53
	v_pk_add_f32 v[6:7], v[6:7], v[52:53]
	v_pk_add_f32 v[50:51], v[50:51], v[54:55]
	v_pk_mul_f32 v[6:7], v[30:31], v[6:7]
	v_pk_mul_f32 v[28:29], v[28:29], v[50:51]
	v_pk_fma_f32 v[30:31], v[2:3], s[42:43], v[6:7] op_sel_hi:[1,0,1]
	v_pk_fma_f32 v[28:29], v[0:1], s[42:43], v[28:29] op_sel_hi:[1,0,1]
	v_mov_b64_e32 v[0:1], v[224:225]
	v_mov_b64_e32 v[2:3], v[226:227]
	s_nop 0
	v_mov_b64_e32 v[4:5], v[194:195]
	v_mov_b64_e32 v[6:7], v[196:197]
	s_nop 0
	v_mov_b64_e32 v[54:55], v[232:233]
	v_add_f32_e32 v50, v28, v29
	v_mov_b64_e32 v[46:47], v[238:239]
	v_add_f32_e32 v52, v30, v31
	v_pk_mul_f32 v[6:7], v[6:7], 0.5 op_sel_hi:[1,0]
	v_lshlrev_b32_e32 v48, 16, v54
	v_and_b32_e32 v49, 0xffff0000, v54
	v_lshlrev_b32_e32 v54, 16, v55
	v_and_b32_e32 v55, 0xffff0000, v55
	v_lshlrev_b32_e32 v56, 16, v46
	v_and_b32_e32 v57, 0xffff0000, v46
	v_lshlrev_b32_e32 v46, 16, v47
	v_and_b32_e32 v47, 0xffff0000, v47
	v_pk_mul_f32 v[4:5], v[4:5], 0.5 op_sel_hi:[1,0]
	v_pk_add_f32 v[46:47], v[54:55], v[46:47]
	v_pk_add_f32 v[48:49], v[48:49], v[56:57]
	v_pk_mul_f32 v[6:7], v[6:7], v[46:47]
	v_pk_mul_f32 v[4:5], v[4:5], v[48:49]
	v_pk_fma_f32 v[118:119], v[2:3], s[42:43], v[6:7] op_sel_hi:[1,0,1]
	v_pk_fma_f32 v[62:63], v[0:1], s[42:43], v[4:5] op_sel_hi:[1,0,1]
	v_mov_b32_e32 v51, v118
	v_mov_b32_e32 v41, v62
	v_mov_b32_e32 v45, v63
	v_mov_b32_e32 v53, v119
	v_pk_add_f32 v[0:1], v[40:41], v[44:45]
	v_pk_add_f32 v[2:3], v[50:51], v[52:53]
	v_lshl_add_u64 v[4:5], v[90:91], 0, s[28:29]
	v_pk_add_f32 v[0:1], v[0:1], v[2:3]
	v_mad_u64_u32 v[48:49], s[4:5], v4, s7, v[78:79]
	v_add_f32_e32 v121, v0, v1
	v_lshlrev_b64 v[0:1], 12, v[18:19]
	v_lshl_add_u64 v[18:19], s[56:57], 0, v[100:101]
	v_lshl_add_u64 v[46:47], v[18:19], 0, s[8:9]
	v_mad_i32_i24 v49, v5, s7, v49
	v_lshl_add_u64 v[18:19], v[18:19], 0, v[152:153]
	v_lshl_add_u64 v[52:53], v[46:47], 0, v[152:153]
	global_load_dwordx4 v[186:189], v[48:49], off offset:1024
	global_load_dwordx4 v[190:193], v[48:49], off offset:2048
	global_load_dwordx4 v[194:197], v[48:49], off offset:3072
	flat_load_dwordx4 v[4:7], v[48:49]
	global_load_dwordx2 v[228:229], v[18:19], off offset:512
	global_load_dwordx2 v[230:231], v[18:19], off offset:1024
	global_load_dwordx2 v[232:233], v[18:19], off offset:1536
	flat_load_dwordx2 v[44:45], v[18:19]
	v_lshl_add_u64 v[40:41], v[80:81], 0, v[0:1]
	global_load_dwordx2 v[234:235], v[52:53], off offset:512
	global_load_dwordx2 v[236:237], v[52:53], off offset:1024
	global_load_dwordx2 v[238:239], v[52:53], off offset:1536
	flat_load_dwordx2 v[52:53], v[52:53]
	v_lshl_add_u64 v[56:57], v[46:47], 0, v[42:43]
	global_load_dwordx4 v[198:201], v[40:41], off offset:1024
	global_load_dwordx4 v[202:205], v[40:41], off offset:2048
	global_load_dwordx4 v[224:227], v[40:41], off offset:3072
	flat_load_dwordx4 v[0:3], v[40:41]
	v_lshl_add_u64 v[108:109], v[46:47], 0, v[104:105]
	v_lshl_add_u64 v[46:47], v[46:47], 0, v[106:107]
	s_waitcnt vmcnt(0) lgkmcnt(0)
	v_pk_mul_f32 v[6:7], v[6:7], 0.5 op_sel_hi:[1,0]
	v_lshlrev_b32_e32 v50, 16, v44
	v_and_b32_e32 v51, 0xffff0000, v44
	v_lshlrev_b32_e32 v44, 16, v45
	v_and_b32_e32 v45, 0xffff0000, v45
	v_lshlrev_b32_e32 v54, 16, v52
	v_and_b32_e32 v55, 0xffff0000, v52
	v_lshlrev_b32_e32 v52, 16, v53
	v_and_b32_e32 v53, 0xffff0000, v53
	v_pk_mul_f32 v[4:5], v[4:5], 0.5 op_sel_hi:[1,0]
	v_pk_add_f32 v[50:51], v[50:51], v[54:55]
	v_pk_add_f32 v[44:45], v[44:45], v[52:53]
	v_pk_mul_f32 v[4:5], v[4:5], v[50:51]
	v_pk_mul_f32 v[6:7], v[6:7], v[44:45]
	v_pk_fma_f32 v[44:45], v[0:1], s[42:43], v[4:5] op_sel_hi:[1,0,1]
	v_pk_fma_f32 v[50:51], v[2:3], s[42:43], v[6:7] op_sel_hi:[1,0,1]
	v_mov_b32_e32 v2, v44
	v_pk_mov_b32 v[0:1], v[44:45], v[50:51] op_sel:[1,0]
	v_mov_b32_e32 v3, v51
	v_pk_add_f32 v[0:1], v[0:1], v[2:3]
	s_nop 0
	v_add_f32_e32 v0, v0, v1
	v_add_f32_e32 v98, 0, v0
	v_mov_b64_e32 v[0:1], v[198:199]
	v_mov_b64_e32 v[2:3], v[200:201]
	v_mov_b64_e32 v[4:5], v[186:187]
	v_mov_b64_e32 v[6:7], v[188:189]
	v_mov_b64_e32 v[52:53], v[228:229]
	v_pk_mul_f32 v[6:7], v[6:7], 0.5 op_sel_hi:[1,0]
	v_mov_b64_e32 v[56:57], v[234:235]
	v_lshlrev_b32_e32 v54, 16, v52
	v_and_b32_e32 v55, 0xffff0000, v52
	v_lshlrev_b32_e32 v52, 16, v53
	v_and_b32_e32 v53, 0xffff0000, v53
	v_pk_mul_f32 v[4:5], v[4:5], 0.5 op_sel_hi:[1,0]
	v_lshlrev_b32_e32 v58, 16, v56
	v_and_b32_e32 v59, 0xffff0000, v56
	v_lshlrev_b32_e32 v56, 16, v57
	v_and_b32_e32 v57, 0xffff0000, v57
	v_pk_add_f32 v[54:55], v[54:55], v[58:59]
	v_pk_add_f32 v[52:53], v[52:53], v[56:57]
	v_pk_mul_f32 v[4:5], v[4:5], v[54:55]
	v_pk_mul_f32 v[6:7], v[6:7], v[52:53]
	v_pk_fma_f32 v[56:57], v[0:1], s[42:43], v[4:5] op_sel_hi:[1,0,1]
	v_pk_fma_f32 v[58:59], v[2:3], s[42:43], v[6:7] op_sel_hi:[1,0,1]
	v_mov_b32_e32 v2, v56
	v_pk_mov_b32 v[0:1], v[56:57], v[58:59] op_sel:[1,0]
	v_mov_b32_e32 v3, v59
	v_pk_add_f32 v[0:1], v[0:1], v[2:3]
	s_nop 0
	v_pk_add_f32 v[102:103], v[0:1], v[0:1] op_sel:[0,1] op_sel_hi:[1,0]
	v_mov_b64_e32 v[0:1], v[202:203]
	v_mov_b64_e32 v[2:3], v[204:205]
	v_mov_b64_e32 v[4:5], v[190:191]
	v_mov_b64_e32 v[6:7], v[192:193]
	v_mov_b64_e32 v[52:53], v[230:231]
	v_pk_mul_f32 v[6:7], v[6:7], 0.5 op_sel_hi:[1,0]
	v_mov_b64_e32 v[108:109], v[236:237]
	v_lshlrev_b32_e32 v54, 16, v52
	v_and_b32_e32 v55, 0xffff0000, v52
	v_lshlrev_b32_e32 v52, 16, v53
	v_and_b32_e32 v53, 0xffff0000, v53
	v_pk_mul_f32 v[4:5], v[4:5], 0.5 op_sel_hi:[1,0]
	v_lshlrev_b32_e32 v110, 16, v108
	v_and_b32_e32 v111, 0xffff0000, v108
	v_lshlrev_b32_e32 v108, 16, v109
	v_and_b32_e32 v109, 0xffff0000, v109
	v_pk_add_f32 v[52:53], v[52:53], v[108:109]
	v_pk_add_f32 v[54:55], v[54:55], v[110:111]
	v_pk_mul_f32 v[6:7], v[6:7], v[52:53]
	v_pk_mul_f32 v[4:5], v[4:5], v[54:55]
	v_pk_fma_f32 v[54:55], v[2:3], s[42:43], v[6:7] op_sel_hi:[1,0,1]
	v_pk_fma_f32 v[52:53], v[0:1], s[42:43], v[4:5] op_sel_hi:[1,0,1]
	v_mov_b64_e32 v[0:1], v[224:225]
	v_mov_b64_e32 v[2:3], v[226:227]
	v_mov_b64_e32 v[4:5], v[194:195]
	v_mov_b64_e32 v[6:7], v[196:197]
	s_nop 0
	v_mov_b64_e32 v[18:19], v[232:233]
	v_add_f32_e32 v108, v52, v53
	v_mov_b64_e32 v[46:47], v[238:239]
	v_add_f32_e32 v110, v54, v55
	v_pk_mul_f32 v[6:7], v[6:7], 0.5 op_sel_hi:[1,0]
	v_lshlrev_b32_e32 v48, 16, v18
	v_and_b32_e32 v49, 0xffff0000, v18
	v_lshlrev_b32_e32 v18, 16, v19
	v_and_b32_e32 v19, 0xffff0000, v19
	v_lshlrev_b32_e32 v112, 16, v46
	v_and_b32_e32 v113, 0xffff0000, v46
	v_lshlrev_b32_e32 v46, 16, v47
	v_and_b32_e32 v47, 0xffff0000, v47
	v_pk_mul_f32 v[4:5], v[4:5], 0.5 op_sel_hi:[1,0]
	v_pk_add_f32 v[18:19], v[18:19], v[46:47]
	v_pk_add_f32 v[46:47], v[48:49], v[112:113]
	v_pk_mul_f32 v[6:7], v[6:7], v[18:19]
	v_pk_mul_f32 v[4:5], v[4:5], v[46:47]
	v_pk_fma_f32 v[48:49], v[2:3], s[42:43], v[6:7] op_sel_hi:[1,0,1]
	v_pk_fma_f32 v[46:47], v[0:1], s[42:43], v[4:5] op_sel_hi:[1,0,1]
	v_mov_b32_e32 v109, v48
	v_mov_b32_e32 v99, v46
	v_mov_b32_e32 v103, v47
	v_mov_b32_e32 v111, v49
	v_pk_add_f32 v[0:1], v[98:99], v[102:103]
	v_pk_add_f32 v[2:3], v[108:109], v[110:111]
	v_lshlrev_b64 v[98:99], 11, v[16:17]
	v_pk_add_f32 v[0:1], v[0:1], v[2:3]
	v_lshl_add_u64 v[4:5], v[88:89], 0, s[28:29]
	v_add_f32_e32 v125, v0, v1
	v_lshlrev_b64 v[0:1], 12, v[16:17]
	v_lshl_add_u64 v[16:17], s[56:57], 0, v[98:99]
	v_lshl_add_u64 v[18:19], v[16:17], 0, s[8:9]
	v_mad_u64_u32 v[126:127], s[4:5], v4, s7, v[78:79]
	v_mad_i32_i24 v127, v5, s7, v127
	v_lshl_add_u64 v[16:17], v[16:17], 0, v[152:153]
	v_lshl_add_u64 v[112:113], v[18:19], 0, v[152:153]
	global_load_dwordx4 v[186:189], v[126:127], off offset:1024
	global_load_dwordx4 v[190:193], v[126:127], off offset:2048
	global_load_dwordx4 v[194:197], v[126:127], off offset:3072
	flat_load_dwordx4 v[4:7], v[126:127]
	global_load_dwordx2 v[228:229], v[16:17], off offset:512
	global_load_dwordx2 v[230:231], v[16:17], off offset:1024
	global_load_dwordx2 v[232:233], v[16:17], off offset:1536
	flat_load_dwordx2 v[108:109], v[16:17]
	v_lshl_add_u64 v[102:103], v[80:81], 0, v[0:1]
	global_load_dwordx2 v[234:235], v[112:113], off offset:512
	global_load_dwordx2 v[236:237], v[112:113], off offset:1024
	global_load_dwordx2 v[238:239], v[112:113], off offset:1536
	flat_load_dwordx2 v[112:113], v[112:113]
	v_lshl_add_u64 v[42:43], v[18:19], 0, v[42:43]
	global_load_dwordx4 v[198:201], v[102:103], off offset:1024
	global_load_dwordx4 v[202:205], v[102:103], off offset:2048
	global_load_dwordx4 v[224:227], v[102:103], off offset:3072
	flat_load_dwordx4 v[0:3], v[102:103]
	v_lshl_add_u64 v[104:105], v[18:19], 0, v[104:105]
	v_lshl_add_u64 v[18:19], v[18:19], 0, v[106:107]
	s_mov_b32 s4, 0x3727c5ac
	s_waitcnt vmcnt(0) lgkmcnt(0)
	v_pk_mul_f32 v[6:7], v[6:7], 0.5 op_sel_hi:[1,0]
	v_lshlrev_b32_e32 v110, 16, v108
	v_and_b32_e32 v111, 0xffff0000, v108
	v_lshlrev_b32_e32 v108, 16, v109
	v_and_b32_e32 v109, 0xffff0000, v109
	v_lshlrev_b32_e32 v114, 16, v112
	v_and_b32_e32 v115, 0xffff0000, v112
	v_lshlrev_b32_e32 v112, 16, v113
	v_and_b32_e32 v113, 0xffff0000, v113
	v_pk_mul_f32 v[4:5], v[4:5], 0.5 op_sel_hi:[1,0]
	v_pk_add_f32 v[110:111], v[110:111], v[114:115]
	v_pk_add_f32 v[108:109], v[108:109], v[112:113]
	v_pk_mul_f32 v[4:5], v[4:5], v[110:111]
	v_pk_mul_f32 v[6:7], v[6:7], v[108:109]
	v_pk_fma_f32 v[114:115], v[0:1], s[42:43], v[4:5] op_sel_hi:[1,0,1]
	v_pk_fma_f32 v[116:117], v[2:3], s[42:43], v[6:7] op_sel_hi:[1,0,1]
	v_mov_b32_e32 v2, v114
	v_pk_mov_b32 v[0:1], v[114:115], v[116:117] op_sel:[1,0]
	v_mov_b32_e32 v3, v117
	v_pk_add_f32 v[0:1], v[0:1], v[2:3]
	s_nop 0
	v_add_f32_e32 v0, v0, v1
	v_add_f32_e32 v128, 0, v0
	v_mov_b64_e32 v[0:1], v[198:199]
	v_mov_b64_e32 v[2:3], v[200:201]
	v_mov_b64_e32 v[4:5], v[186:187]
	v_mov_b64_e32 v[6:7], v[188:189]
	v_mov_b64_e32 v[108:109], v[228:229]
	v_pk_mul_f32 v[6:7], v[6:7], 0.5 op_sel_hi:[1,0]
	v_mov_b64_e32 v[42:43], v[234:235]
	v_lshlrev_b32_e32 v110, 16, v108
	v_and_b32_e32 v111, 0xffff0000, v108
	v_lshlrev_b32_e32 v108, 16, v109
	v_and_b32_e32 v109, 0xffff0000, v109
	v_pk_mul_f32 v[4:5], v[4:5], 0.5 op_sel_hi:[1,0]
	v_lshlrev_b32_e32 v112, 16, v42
	v_and_b32_e32 v113, 0xffff0000, v42
	v_lshlrev_b32_e32 v42, 16, v43
	v_and_b32_e32 v43, 0xffff0000, v43
	v_pk_add_f32 v[110:111], v[110:111], v[112:113]
	v_pk_add_f32 v[42:43], v[108:109], v[42:43]
	v_pk_mul_f32 v[4:5], v[4:5], v[110:111]
	v_pk_mul_f32 v[6:7], v[6:7], v[42:43]
	v_pk_fma_f32 v[42:43], v[0:1], s[42:43], v[4:5] op_sel_hi:[1,0,1]
	v_pk_fma_f32 v[112:113], v[2:3], s[42:43], v[6:7] op_sel_hi:[1,0,1]
	v_mov_b32_e32 v2, v42
	v_pk_mov_b32 v[0:1], v[42:43], v[112:113] op_sel:[1,0]
	v_mov_b32_e32 v3, v113
	v_pk_add_f32 v[0:1], v[0:1], v[2:3]
	s_nop 0
	v_pk_add_f32 v[130:131], v[0:1], v[0:1] op_sel:[0,1] op_sel_hi:[1,0]
	v_mov_b64_e32 v[0:1], v[202:203]
	v_mov_b64_e32 v[2:3], v[204:205]
	v_mov_b64_e32 v[4:5], v[190:191]
	v_mov_b64_e32 v[6:7], v[192:193]
	v_mov_b64_e32 v[108:109], v[230:231]
	v_pk_mul_f32 v[6:7], v[6:7], 0.5 op_sel_hi:[1,0]
	v_mov_b64_e32 v[104:105], v[236:237]
	v_lshlrev_b32_e32 v110, 16, v108
	v_and_b32_e32 v111, 0xffff0000, v108
	v_lshlrev_b32_e32 v108, 16, v109
	v_and_b32_e32 v109, 0xffff0000, v109
	v_pk_mul_f32 v[4:5], v[4:5], 0.5 op_sel_hi:[1,0]
	v_lshlrev_b32_e32 v132, 16, v104
	v_and_b32_e32 v133, 0xffff0000, v104
	v_lshlrev_b32_e32 v104, 16, v105
	v_and_b32_e32 v105, 0xffff0000, v105
	v_pk_add_f32 v[104:105], v[108:109], v[104:105]
	v_pk_add_f32 v[108:109], v[110:111], v[132:133]
	v_pk_mul_f32 v[6:7], v[6:7], v[104:105]
	v_pk_mul_f32 v[4:5], v[4:5], v[108:109]
	v_pk_fma_f32 v[110:111], v[2:3], s[42:43], v[6:7] op_sel_hi:[1,0,1]
	v_pk_fma_f32 v[108:109], v[0:1], s[42:43], v[4:5] op_sel_hi:[1,0,1]
	v_mov_b64_e32 v[0:1], v[224:225]
	v_mov_b64_e32 v[2:3], v[226:227]
	v_mov_b64_e32 v[4:5], v[194:195]
	v_mov_b64_e32 v[6:7], v[196:197]
	s_nop 0
	v_mov_b64_e32 v[16:17], v[232:233]
	v_add_f32_e32 v132, v108, v109
	v_mov_b64_e32 v[18:19], v[238:239]
	v_add_f32_e32 v134, v110, v111
	v_pk_mul_f32 v[6:7], v[6:7], 0.5 op_sel_hi:[1,0]
	v_lshlrev_b32_e32 v104, 16, v16
	v_and_b32_e32 v105, 0xffff0000, v16
	v_lshlrev_b32_e32 v16, 16, v17
	v_and_b32_e32 v17, 0xffff0000, v17
	v_lshlrev_b32_e32 v106, 16, v18
	v_and_b32_e32 v107, 0xffff0000, v18
	v_lshlrev_b32_e32 v18, 16, v19
	v_and_b32_e32 v19, 0xffff0000, v19
	v_pk_mul_f32 v[4:5], v[4:5], 0.5 op_sel_hi:[1,0]
	v_pk_add_f32 v[16:17], v[16:17], v[18:19]
	v_pk_add_f32 v[18:19], v[104:105], v[106:107]
	v_pk_mul_f32 v[6:7], v[6:7], v[16:17]
	v_pk_mul_f32 v[4:5], v[4:5], v[18:19]
	v_pk_fma_f32 v[106:107], v[2:3], s[42:43], v[6:7] op_sel_hi:[1,0,1]
	v_pk_fma_f32 v[104:105], v[0:1], s[42:43], v[4:5] op_sel_hi:[1,0,1]
	v_mov_b32_e32 v133, v106
	v_mov_b32_e32 v129, v104
	v_mov_b32_e32 v131, v105
	v_mov_b32_e32 v135, v107
	v_pk_add_f32 v[0:1], v[128:129], v[130:131]
	v_pk_add_f32 v[2:3], v[132:133], v[134:135]
	ds_bpermute_b32 v18, v67, v121
	v_pk_add_f32 v[0:1], v[0:1], v[2:3]
	s_waitcnt lgkmcnt(0)
	v_add_f32_e32 v18, v121, v18
	v_add_f32_e32 v65, v0, v1
	ds_bpermute_b32 v0, v67, v120
	ds_bpermute_b32 v19, v69, v18
	s_waitcnt lgkmcnt(1)
	v_add_f32_e32 v0, v120, v0
	ds_bpermute_b32 v1, v69, v0
	s_waitcnt lgkmcnt(1)
	v_add_f32_e32 v18, v18, v19
	ds_bpermute_b32 v19, v71, v18
	s_waitcnt lgkmcnt(1)
	v_add_f32_e32 v0, v0, v1
	ds_bpermute_b32 v1, v71, v0
	s_waitcnt lgkmcnt(1)
	v_add_f32_e32 v18, v18, v19
	ds_bpermute_b32 v19, v73, v18
	s_waitcnt lgkmcnt(1)
	v_add_f32_e32 v0, v0, v1
	ds_bpermute_b32 v1, v73, v0
	s_waitcnt lgkmcnt(1)
	v_add_f32_e32 v18, v18, v19
	ds_bpermute_b32 v19, v123, v18
	s_waitcnt lgkmcnt(1)
	v_add_f32_e32 v0, v0, v1
	ds_bpermute_b32 v1, v123, v0
	s_waitcnt lgkmcnt(1)
	v_add_f32_e32 v18, v18, v19
	ds_bpermute_b32 v19, v124, v18
	s_waitcnt lgkmcnt(1)
	v_add_f32_e32 v0, v0, v1
	ds_bpermute_b32 v1, v124, v0
	s_waitcnt lgkmcnt(1)
	v_add_f32_e32 v122, v18, v19
	v_fmamk_f32 v35, v122, 0xba800000, v35
	v_fmac_f32_e32 v34, 0xba800000, v122
	v_fmamk_f32 v37, v122, 0xba800000, v37
	s_waitcnt lgkmcnt(0)
	v_add_f32_e32 v16, v0, v1
	v_fmamk_f32 v9, v16, 0xba800000, v9
	v_fmac_f32_e32 v8, 0xba800000, v16
	v_fmamk_f32 v11, v16, 0xba800000, v11
	v_fmac_f32_e32 v10, 0xba800000, v16
	v_pk_mul_f32 v[0:1], v[10:11], v[10:11]
	v_pk_mul_f32 v[2:3], v[8:9], v[8:9]
	v_fmamk_f32 v13, v16, 0xba800000, v13
	v_pk_mov_b32 v[4:5], v[2:3], v[0:1] op_sel:[1,0]
	v_mov_b32_e32 v3, v1
	v_pk_add_f32 v[0:1], v[4:5], v[2:3]
	v_fmac_f32_e32 v12, 0xba800000, v16
	v_fmamk_f32 v15, v16, 0xba800000, v15
	v_fmac_f32_e32 v14, 0xba800000, v16
	v_pk_add_f32 v[0:1], v[0:1], v[0:1] op_sel_hi:[0,1]
	v_pk_mul_f32 v[2:3], v[14:15], v[14:15]
	v_pk_mul_f32 v[4:5], v[12:13], v[12:13]
	v_fmac_f32_e32 v20, 0xba800000, v16
	v_pk_mov_b32 v[6:7], v[4:5], v[2:3] op_sel:[1,0]
	v_mov_b32_e32 v5, v3
	v_fmamk_f32 v21, v16, 0xba800000, v21
	v_fmac_f32_e32 v22, 0xba800000, v16
	v_mul_f32_e32 v0, v20, v20
	v_pk_add_f32 v[2:3], v[6:7], v[4:5]
	v_fmamk_f32 v23, v16, 0xba800000, v23
	v_pk_fma_f32 v[4:5], v[20:21], v[20:21], v[0:1] op_sel_hi:[1,1,0]
	v_mul_f32_e32 v0, v22, v22
	v_pk_add_f32 v[2:3], v[2:3], v[2:3] op_sel_hi:[0,1]
	v_pk_fma_f32 v[6:7], v[22:23], v[22:23], v[0:1] op_sel_hi:[1,1,0]
	v_fmamk_f32 v27, v16, 0xba800000, v27
	v_fmac_f32_e32 v26, 0xba800000, v16
	v_fmamk_f32 v25, v16, 0xba800000, v25
	v_fmac_f32_e32 v24, 0xba800000, v16
	v_mul_f32_e32 v4, v24, v24
	v_mul_f32_e32 v6, v25, v25
	v_mul_f32_e32 v0, v26, v26
	v_mul_f32_e32 v2, v27, v27
	v_pk_add_f32 v[4:5], v[4:5], v[6:7]
	v_pk_add_f32 v[0:1], v[0:1], v[2:3]
	v_fmac_f32_e32 v36, 0xba800000, v122
	v_pk_add_f32 v[16:17], v[4:5], v[0:1]
	v_mov_b64_e32 v[0:1], v[154:155]
	v_mov_b64_e32 v[2:3], v[156:157]
	v_mov_b64_e32 v[4:5], v[158:159]
	v_mov_b64_e32 v[6:7], v[160:161]
	v_pk_mul_f32 v[18:19], v[36:37], v[36:37]
	v_pk_mul_f32 v[120:121], v[34:35], v[34:35]
	v_fmamk_f32 v39, v122, 0xba800000, v39
	v_pk_mov_b32 v[126:127], v[120:121], v[18:19] op_sel:[1,0]
	v_mov_b32_e32 v121, v19
	v_pk_add_f32 v[18:19], v[126:127], v[120:121]
	v_fmac_f32_e32 v38, 0xba800000, v122
	v_fmamk_f32 v61, v122, 0xba800000, v61
	v_fmac_f32_e32 v60, 0xba800000, v122
	v_pk_add_f32 v[18:19], v[18:19], v[18:19] op_sel_hi:[0,1]
	v_pk_mul_f32 v[120:121], v[60:61], v[60:61]
	v_pk_mul_f32 v[126:127], v[38:39], v[38:39]
	v_fmac_f32_e32 v28, 0xba800000, v122
	v_pk_mov_b32 v[128:129], v[126:127], v[120:121] op_sel:[1,0]
	v_mov_b32_e32 v127, v121
	v_fmamk_f32 v29, v122, 0xba800000, v29
	v_fmac_f32_e32 v30, 0xba800000, v122
	v_mul_f32_e32 v18, v28, v28
	v_pk_add_f32 v[120:121], v[128:129], v[126:127]
	v_fmamk_f32 v31, v122, 0xba800000, v31
	v_pk_fma_f32 v[126:127], v[28:29], v[28:29], v[18:19] op_sel_hi:[1,1,0]
	v_mul_f32_e32 v18, v30, v30
	v_pk_add_f32 v[120:121], v[120:121], v[120:121] op_sel_hi:[0,1]
	v_pk_fma_f32 v[128:129], v[30:31], v[30:31], v[18:19] op_sel_hi:[1,1,0]
	v_fmamk_f32 v119, v122, 0xba800000, v119
	v_fmac_f32_e32 v118, 0xba800000, v122
	v_fmamk_f32 v63, v122, 0xba800000, v63
	v_fmac_f32_e32 v62, 0xba800000, v122
	v_mul_f32_e32 v126, v62, v62
	v_mul_f32_e32 v128, v63, v63
	v_mul_f32_e32 v18, v118, v118
	v_mul_f32_e32 v120, v119, v119
	v_pk_add_f32 v[126:127], v[126:127], v[128:129]
	v_pk_add_f32 v[18:19], v[18:19], v[120:121]
	v_mov_b32_e32 v121, v16
	v_pk_add_f32 v[18:19], v[126:127], v[18:19]
	s_nop 0
	v_mov_b32_e32 v120, v18
	v_mov_b32_e32 v16, v19
	v_pk_add_f32 v[16:17], v[120:121], v[16:17]
	ds_bpermute_b32 v19, v67, v17
	ds_bpermute_b32 v18, v67, v16
	v_mov_b64_e32 v[120:121], s[4:5]
	s_mov_b32 s4, 0x3a800000
	s_waitcnt lgkmcnt(0)
	v_pk_add_f32 v[16:17], v[16:17], v[18:19]
	ds_bpermute_b32 v19, v69, v17
	ds_bpermute_b32 v18, v69, v16
	s_waitcnt lgkmcnt(0)
	v_pk_add_f32 v[16:17], v[16:17], v[18:19]
	ds_bpermute_b32 v19, v71, v17
	ds_bpermute_b32 v18, v71, v16
	s_waitcnt lgkmcnt(0)
	v_pk_add_f32 v[16:17], v[16:17], v[18:19]
	ds_bpermute_b32 v19, v73, v17
	ds_bpermute_b32 v18, v73, v16
	s_waitcnt lgkmcnt(0)
	v_pk_add_f32 v[16:17], v[16:17], v[18:19]
	ds_bpermute_b32 v19, v123, v17
	ds_bpermute_b32 v18, v123, v16
	s_waitcnt lgkmcnt(0)
	v_pk_add_f32 v[16:17], v[16:17], v[18:19]
	ds_bpermute_b32 v19, v124, v17
	ds_bpermute_b32 v18, v124, v16
	s_waitcnt lgkmcnt(0)
	v_pk_add_f32 v[16:17], v[16:17], v[18:19]
	s_nop 0
	v_pk_fma_f32 v[126:127], v[16:17], s[4:5], v[120:121] op_sel_hi:[1,0,0]
	s_nop 0
	v_mul_f32_e32 v16, 0x4b800000, v127
	v_cmp_gt_f32_e64 s[8:9], s68, v127
	v_cmp_gt_f32_e32 vcc, s68, v126
	s_nop 0
	v_cndmask_b32_e64 v16, v127, v16, s[8:9]
	v_rsq_f32_e32 v16, v16
	s_nop 0
	v_mul_f32_e32 v17, 0x45800000, v16
	v_cndmask_b32_e64 v122, v16, v17, s[8:9]
	v_pk_mul_f32 v[8:9], v[8:9], v[122:123] op_sel_hi:[1,0]
	v_pk_mul_f32 v[10:11], v[10:11], v[122:123] op_sel_hi:[1,0]
	v_pk_fma_f32 v[16:17], v[0:1], v[8:9], v[4:5]
	v_pk_fma_f32 v[18:19], v[2:3], v[10:11], v[6:7]
	flat_store_dwordx4 v[86:87], v[16:19]
	v_mov_b64_e32 v[0:1], v[162:163]
	v_mov_b64_e32 v[2:3], v[164:165]
	v_mov_b64_e32 v[4:5], v[166:167]
	v_mov_b64_e32 v[6:7], v[168:169]
	v_pk_mul_f32 v[8:9], v[14:15], v[122:123] op_sel_hi:[1,0]
	v_pk_mul_f32 v[10:11], v[12:13], v[122:123] op_sel_hi:[1,0]
	v_pk_fma_f32 v[14:15], v[2:3], v[8:9], v[6:7]
	v_pk_fma_f32 v[12:13], v[0:1], v[10:11], v[4:5]
	flat_store_dwordx4 v[86:87], v[12:15] offset:1024
	v_mov_b64_e32 v[0:1], v[170:171]
	v_mov_b64_e32 v[2:3], v[172:173]
	v_mov_b64_e32 v[4:5], v[174:175]
	v_mov_b64_e32 v[6:7], v[176:177]
	v_pk_mul_f32 v[8:9], v[22:23], v[122:123] op_sel_hi:[1,0]
	v_pk_mul_f32 v[10:11], v[20:21], v[122:123] op_sel_hi:[1,0]
	v_pk_mul_f32 v[22:23], v[24:25], v[122:123] op_sel_hi:[1,0]
	v_pk_mul_f32 v[20:21], v[26:27], v[122:123] op_sel_hi:[1,0]
	v_pk_fma_f32 v[4:5], v[0:1], v[10:11], v[4:5]
	v_pk_fma_f32 v[6:7], v[2:3], v[8:9], v[6:7]
	flat_store_dwordx4 v[86:87], v[4:7] offset:2048
	v_mov_b64_e32 v[0:1], v[178:179]
	v_mov_b64_e32 v[2:3], v[180:181]
	v_mov_b64_e32 v[8:9], v[182:183]
	v_mov_b64_e32 v[10:11], v[184:185]
	v_pk_fma_f32 v[0:1], v[0:1], v[22:23], v[8:9]
	v_mul_f32_e32 v8, 0x4b800000, v126
	v_cndmask_b32_e32 v8, v126, v8, vcc
	v_rsq_f32_e32 v8, v8
	v_pk_fma_f32 v[2:3], v[2:3], v[20:21], v[10:11]
	flat_store_dwordx4 v[86:87], v[0:3] offset:3072
	v_mul_f32_e32 v9, 0x45800000, v8
	v_cndmask_b32_e32 v122, v8, v9, vcc
	v_mov_b64_e32 v[8:9], v[154:155]
	v_mov_b64_e32 v[10:11], v[156:157]
	v_mov_b64_e32 v[20:21], v[158:159]
	v_mov_b64_e32 v[22:23], v[160:161]
	v_pk_mul_f32 v[24:25], v[36:37], v[122:123] op_sel_hi:[1,0]
	v_pk_mul_f32 v[26:27], v[34:35], v[122:123] op_sel_hi:[1,0]
	v_pk_mul_f32 v[34:35], v[60:61], v[122:123] op_sel_hi:[1,0]
	v_pk_mul_f32 v[36:37], v[38:39], v[122:123] op_sel_hi:[1,0]
	v_pk_mul_f32 v[38:39], v[118:119], v[122:123] op_sel_hi:[1,0]
	v_pk_mul_f32 v[60:61], v[62:63], v[122:123] op_sel_hi:[1,0]
	ds_bpermute_b32 v62, v67, v65
	s_waitcnt lgkmcnt(0)
	v_add_f32_e32 v62, v65, v62
	ds_bpermute_b32 v63, v69, v62
	s_waitcnt lgkmcnt(0)
	v_add_f32_e32 v62, v62, v63
	ds_bpermute_b32 v63, v71, v62
	s_waitcnt lgkmcnt(0)
	v_add_f32_e32 v62, v62, v63
	ds_bpermute_b32 v63, v73, v62
	s_waitcnt lgkmcnt(0)
	v_add_f32_e32 v62, v62, v63
	ds_bpermute_b32 v63, v123, v62
	s_waitcnt lgkmcnt(0)
	v_add_f32_e32 v62, v62, v63
	ds_bpermute_b32 v63, v124, v62
	s_waitcnt lgkmcnt(0)
	v_add_f32_e32 v65, v62, v63
	v_fmamk_f32 v115, v65, 0xba800000, v115
	v_fmac_f32_e32 v114, 0xba800000, v65
	v_fmamk_f32 v117, v65, 0xba800000, v117
	v_fmac_f32_e32 v116, 0xba800000, v65
	v_pk_mul_f32 v[62:63], v[116:117], v[116:117]
	v_pk_mul_f32 v[118:119], v[114:115], v[114:115]
	v_fmamk_f32 v43, v65, 0xba800000, v43
	v_pk_mov_b32 v[126:127], v[118:119], v[62:63] op_sel:[1,0]
	v_mov_b32_e32 v119, v63
	v_pk_add_f32 v[62:63], v[126:127], v[118:119]
	v_fmac_f32_e32 v42, 0xba800000, v65
	v_fmamk_f32 v113, v65, 0xba800000, v113
	v_fmac_f32_e32 v112, 0xba800000, v65
	v_pk_add_f32 v[62:63], v[62:63], v[62:63] op_sel_hi:[0,1]
	v_pk_mul_f32 v[118:119], v[112:113], v[112:113]
	v_pk_mul_f32 v[126:127], v[42:43], v[42:43]
	v_fmac_f32_e32 v108, 0xba800000, v65
	v_pk_mov_b32 v[128:129], v[126:127], v[118:119] op_sel:[1,0]
	v_mov_b32_e32 v127, v119
	v_fmamk_f32 v109, v65, 0xba800000, v109
	v_fmac_f32_e32 v110, 0xba800000, v65
	v_mul_f32_e32 v62, v108, v108
	v_pk_add_f32 v[118:119], v[128:129], v[126:127]
	v_fmamk_f32 v111, v65, 0xba800000, v111
	v_pk_fma_f32 v[126:127], v[108:109], v[108:109], v[62:63] op_sel_hi:[1,1,0]
	v_mul_f32_e32 v62, v110, v110
	v_pk_add_f32 v[118:119], v[118:119], v[118:119] op_sel_hi:[0,1]
	v_pk_fma_f32 v[128:129], v[110:111], v[110:111], v[62:63] op_sel_hi:[1,1,0]
	v_fmamk_f32 v107, v65, 0xba800000, v107
	v_fmac_f32_e32 v106, 0xba800000, v65
	v_fmamk_f32 v105, v65, 0xba800000, v105
	v_fmac_f32_e32 v104, 0xba800000, v65
	v_mul_f32_e32 v126, v104, v104
	v_mul_f32_e32 v128, v105, v105
	v_mul_f32_e32 v62, v106, v106
	v_mul_f32_e32 v118, v107, v107
	v_pk_add_f32 v[126:127], v[126:127], v[128:129]
	v_pk_fma_f32 v[8:9], v[8:9], v[26:27], v[20:21]
	v_pk_fma_f32 v[10:11], v[10:11], v[24:25], v[22:23]
	flat_store_dwordx4 v[32:33], v[8:11]
	v_mov_b64_e32 v[20:21], v[162:163]
	v_mov_b64_e32 v[22:23], v[164:165]
	v_mov_b64_e32 v[24:25], v[166:167]
	v_mov_b64_e32 v[26:27], v[168:169]
	v_pk_add_f32 v[62:63], v[62:63], v[118:119]
	v_pk_fma_f32 v[20:21], v[20:21], v[36:37], v[24:25]
	v_pk_fma_f32 v[22:23], v[22:23], v[34:35], v[26:27]
	flat_store_dwordx4 v[32:33], v[20:23] offset:1024
	v_pk_mul_f32 v[34:35], v[30:31], v[122:123] op_sel_hi:[1,0]
	v_pk_mul_f32 v[36:37], v[28:29], v[122:123] op_sel_hi:[1,0]
	v_mov_b64_e32 v[24:25], v[170:171]
	v_mov_b64_e32 v[26:27], v[172:173]
	v_mov_b64_e32 v[28:29], v[174:175]
	v_mov_b64_e32 v[30:31], v[176:177]
	v_pk_add_f32 v[62:63], v[126:127], v[62:63]
	v_pk_fma_f32 v[28:29], v[24:25], v[36:37], v[28:29]
	v_pk_fma_f32 v[30:31], v[26:27], v[34:35], v[30:31]
	flat_store_dwordx4 v[32:33], v[28:31] offset:2048
	v_mov_b64_e32 v[24:25], v[178:179]
	v_mov_b64_e32 v[26:27], v[180:181]
	v_mov_b64_e32 v[34:35], v[182:183]
	v_mov_b64_e32 v[36:37], v[184:185]
	v_mov_b32_e32 v118, v62
	v_pk_fma_f32 v[24:25], v[24:25], v[60:61], v[34:35]
	v_pk_fma_f32 v[26:27], v[26:27], v[38:39], v[36:37]
	flat_store_dwordx4 v[32:33], v[24:27] offset:3072
	ds_bpermute_b32 v32, v67, v125
	s_waitcnt lgkmcnt(0)
	v_add_f32_e32 v32, v125, v32
	ds_bpermute_b32 v33, v69, v32
	s_waitcnt lgkmcnt(0)
	v_add_f32_e32 v32, v32, v33
	ds_bpermute_b32 v33, v71, v32
	s_waitcnt lgkmcnt(0)
	v_add_f32_e32 v32, v32, v33
	ds_bpermute_b32 v33, v73, v32
	s_waitcnt lgkmcnt(0)
	v_add_f32_e32 v32, v32, v33
	ds_bpermute_b32 v33, v123, v32
	s_waitcnt lgkmcnt(0)
	v_add_f32_e32 v32, v32, v33
	ds_bpermute_b32 v33, v124, v32
	s_waitcnt lgkmcnt(0)
	v_add_f32_e32 v60, v32, v33
	v_fmamk_f32 v45, v60, 0xba800000, v45
	v_fmac_f32_e32 v44, 0xba800000, v60
	v_fmamk_f32 v51, v60, 0xba800000, v51
	v_fmac_f32_e32 v50, 0xba800000, v60
	v_pk_mul_f32 v[32:33], v[50:51], v[50:51]
	v_pk_mul_f32 v[34:35], v[44:45], v[44:45]
	v_fmamk_f32 v57, v60, 0xba800000, v57
	v_pk_mov_b32 v[36:37], v[34:35], v[32:33] op_sel:[1,0]
	v_mov_b32_e32 v35, v33
	v_pk_add_f32 v[32:33], v[36:37], v[34:35]
	v_fmac_f32_e32 v56, 0xba800000, v60
	v_fmamk_f32 v59, v60, 0xba800000, v59
	v_fmac_f32_e32 v58, 0xba800000, v60
	v_pk_add_f32 v[32:33], v[32:33], v[32:33] op_sel_hi:[0,1]
	v_pk_mul_f32 v[34:35], v[58:59], v[58:59]
	v_pk_mul_f32 v[36:37], v[56:57], v[56:57]
	v_fmac_f32_e32 v52, 0xba800000, v60
	v_pk_mov_b32 v[38:39], v[36:37], v[34:35] op_sel:[1,0]
	v_mov_b32_e32 v37, v35
	v_fmamk_f32 v53, v60, 0xba800000, v53
	v_fmac_f32_e32 v54, 0xba800000, v60
	v_mul_f32_e32 v32, v52, v52
	v_pk_add_f32 v[34:35], v[38:39], v[36:37]
	v_fmamk_f32 v55, v60, 0xba800000, v55
	v_pk_fma_f32 v[36:37], v[52:53], v[52:53], v[32:33] op_sel_hi:[1,1,0]
	v_mul_f32_e32 v32, v54, v54
	v_pk_add_f32 v[34:35], v[34:35], v[34:35] op_sel_hi:[0,1]
	v_pk_fma_f32 v[38:39], v[54:55], v[54:55], v[32:33] op_sel_hi:[1,1,0]
	v_fmamk_f32 v49, v60, 0xba800000, v49
	v_fmac_f32_e32 v48, 0xba800000, v60
	v_fmamk_f32 v47, v60, 0xba800000, v47
	v_fmac_f32_e32 v46, 0xba800000, v60
	v_mul_f32_e32 v36, v46, v46
	v_mul_f32_e32 v38, v47, v47
	v_mul_f32_e32 v32, v48, v48
	v_mul_f32_e32 v34, v49, v49
	v_pk_add_f32 v[36:37], v[36:37], v[38:39]
	v_pk_add_f32 v[32:33], v[32:33], v[34:35]
	s_nop 0
	v_pk_add_f32 v[60:61], v[36:37], v[32:33]
	v_mov_b64_e32 v[32:33], v[154:155]
	v_mov_b64_e32 v[34:35], v[156:157]
	v_mov_b64_e32 v[36:37], v[158:159]
	v_mov_b64_e32 v[38:39], v[160:161]
	v_mov_b32_e32 v119, v60
	v_mov_b32_e32 v60, v63
	v_pk_add_f32 v[60:61], v[118:119], v[60:61]
	ds_bpermute_b32 v63, v67, v61
	ds_bpermute_b32 v62, v67, v60
	s_waitcnt lgkmcnt(0)
	v_pk_add_f32 v[60:61], v[60:61], v[62:63]
	ds_bpermute_b32 v63, v69, v61
	ds_bpermute_b32 v62, v69, v60
	s_waitcnt lgkmcnt(0)
	v_pk_add_f32 v[60:61], v[60:61], v[62:63]
	ds_bpermute_b32 v63, v71, v61
	ds_bpermute_b32 v62, v71, v60
	s_waitcnt lgkmcnt(0)
	v_pk_add_f32 v[60:61], v[60:61], v[62:63]
	ds_bpermute_b32 v63, v73, v61
	ds_bpermute_b32 v62, v73, v60
	s_waitcnt lgkmcnt(0)
	v_pk_add_f32 v[60:61], v[60:61], v[62:63]
	ds_bpermute_b32 v63, v123, v61
	ds_bpermute_b32 v62, v123, v60
	s_waitcnt lgkmcnt(0)
	v_pk_add_f32 v[60:61], v[60:61], v[62:63]
	ds_bpermute_b32 v63, v124, v61
	ds_bpermute_b32 v62, v124, v60
	s_waitcnt lgkmcnt(0)
	v_pk_add_f32 v[60:61], v[60:61], v[62:63]
	s_nop 0
	v_pk_fma_f32 v[118:119], v[60:61], s[4:5], v[120:121] op_sel_hi:[1,0,0]
	s_nop 0
	v_mul_f32_e32 v60, 0x4b800000, v119
	v_cmp_gt_f32_e64 s[8:9], s68, v119
	v_cmp_gt_f32_e32 vcc, s68, v118
	s_nop 0
	v_cndmask_b32_e64 v60, v119, v60, s[8:9]
	v_rsq_f32_e32 v60, v60
	s_nop 0
	v_mul_f32_e32 v61, 0x45800000, v60
	v_cndmask_b32_e64 v120, v60, v61, s[8:9]
	v_pk_mul_f32 v[50:51], v[50:51], v[120:121] op_sel_hi:[1,0]
	v_pk_mul_f32 v[44:45], v[44:45], v[120:121] op_sel_hi:[1,0]
	v_pk_mul_f32 v[46:47], v[46:47], v[120:121] op_sel_hi:[1,0]
	v_pk_fma_f32 v[60:61], v[32:33], v[44:45], v[36:37]
	v_pk_fma_f32 v[62:63], v[34:35], v[50:51], v[38:39]
	flat_store_dwordx4 v[40:41], v[60:63]
	v_mov_b64_e32 v[32:33], v[162:163]
	v_mov_b64_e32 v[34:35], v[164:165]
	v_mov_b64_e32 v[36:37], v[166:167]
	v_mov_b64_e32 v[38:39], v[168:169]
	v_pk_mul_f32 v[44:45], v[58:59], v[120:121] op_sel_hi:[1,0]
	v_pk_mul_f32 v[50:51], v[56:57], v[120:121] op_sel_hi:[1,0]
	v_pk_fma_f32 v[58:59], v[34:35], v[44:45], v[38:39]
	v_pk_fma_f32 v[56:57], v[32:33], v[50:51], v[36:37]
	flat_store_dwordx4 v[40:41], v[56:59] offset:1024
	v_mov_b64_e32 v[32:33], v[170:171]
	v_mov_b64_e32 v[34:35], v[172:173]
	v_mov_b64_e32 v[36:37], v[174:175]
	v_mov_b64_e32 v[38:39], v[176:177]
	v_pk_mul_f32 v[44:45], v[54:55], v[120:121] op_sel_hi:[1,0]
	v_pk_mul_f32 v[50:51], v[52:53], v[120:121] op_sel_hi:[1,0]
	v_pk_fma_f32 v[54:55], v[34:35], v[44:45], v[38:39]
	v_pk_fma_f32 v[52:53], v[32:33], v[50:51], v[36:37]
	flat_store_dwordx4 v[40:41], v[52:55] offset:2048
	v_mov_b64_e32 v[32:33], v[178:179]
	v_mov_b64_e32 v[34:35], v[180:181]
	v_mov_b64_e32 v[36:37], v[182:183]
	v_mov_b64_e32 v[38:39], v[184:185]
	v_pk_mul_f32 v[44:45], v[48:49], v[120:121] op_sel_hi:[1,0]
	v_pk_fma_f32 v[48:49], v[32:33], v[46:47], v[36:37]
	v_mul_f32_e32 v32, 0x4b800000, v118
	v_cndmask_b32_e32 v32, v118, v32, vcc
	v_rsq_f32_e32 v32, v32
	v_pk_fma_f32 v[50:51], v[34:35], v[44:45], v[38:39]
	flat_store_dwordx4 v[40:41], v[48:51] offset:3072
	v_mul_f32_e32 v33, 0x45800000, v32
	v_cndmask_b32_e32 v118, v32, v33, vcc
	v_mov_b64_e32 v[32:33], v[154:155]
	v_mov_b64_e32 v[34:35], v[156:157]
	v_mov_b64_e32 v[36:37], v[158:159]
	v_mov_b64_e32 v[38:39], v[160:161]
	v_pk_mul_f32 v[40:41], v[116:117], v[118:119] op_sel_hi:[1,0]
	v_pk_mul_f32 v[44:45], v[114:115], v[118:119] op_sel_hi:[1,0]
	v_pk_mul_f32 v[112:113], v[112:113], v[118:119] op_sel_hi:[1,0]
	v_pk_mul_f32 v[110:111], v[110:111], v[118:119] op_sel_hi:[1,0]
	v_pk_mul_f32 v[108:109], v[108:109], v[118:119] op_sel_hi:[1,0]
	s_andn2_b64 vcc, exec, s[14:15]
	v_pk_fma_f32 v[44:45], v[32:33], v[44:45], v[36:37]
	v_pk_fma_f32 v[46:47], v[34:35], v[40:41], v[38:39]
	flat_store_dwordx4 v[102:103], v[44:47]
	v_mov_b64_e32 v[32:33], v[162:163]
	v_mov_b64_e32 v[34:35], v[164:165]
	v_mov_b64_e32 v[36:37], v[166:167]
	v_mov_b64_e32 v[38:39], v[168:169]
	v_pk_mul_f32 v[40:41], v[42:43], v[118:119] op_sel_hi:[1,0]
	v_pk_fma_f32 v[42:43], v[34:35], v[112:113], v[38:39]
	v_pk_fma_f32 v[40:41], v[32:33], v[40:41], v[36:37]
	flat_store_dwordx4 v[102:103], v[40:43] offset:1024
	v_mov_b64_e32 v[32:33], v[170:171]
	v_mov_b64_e32 v[34:35], v[172:173]
	v_mov_b64_e32 v[36:37], v[174:175]
	v_mov_b64_e32 v[38:39], v[176:177]
	v_pk_fma_f32 v[36:37], v[32:33], v[108:109], v[36:37]
	v_pk_fma_f32 v[38:39], v[34:35], v[110:111], v[38:39]
	flat_store_dwordx4 v[102:103], v[36:39] offset:2048
	v_pk_mul_f32 v[108:109], v[106:107], v[118:119] op_sel_hi:[1,0]
	v_pk_mul_f32 v[110:111], v[104:105], v[118:119] op_sel_hi:[1,0]
	v_mov_b64_e32 v[32:33], v[178:179]
	v_mov_b64_e32 v[34:35], v[180:181]
	v_mov_b64_e32 v[104:105], v[182:183]
	v_mov_b64_e32 v[106:107], v[184:185]
	v_pk_fma_f32 v[32:33], v[32:33], v[110:111], v[104:105]
	v_pk_fma_f32 v[34:35], v[34:35], v[108:109], v[106:107]
	flat_store_dwordx4 v[102:103], v[32:35] offset:3072
	s_cbranch_vccnz .LBB0_224
	v_lshl_add_u64 v[102:103], v[94:95], 0, s[2:3]
	v_mov_b64_e32 v[94:95], s[60:61]
	v_mad_u64_u32 v[104:105], s[4:5], v102, s7, v[94:95]
	v_mad_i32_i24 v105, v103, s7, v105
	v_lshl_add_u64 v[110:111], v[104:105], 0, s[30:31]
	v_lshlrev_b32_e32 v152, 2, v66
	v_lshl_add_u64 v[112:113], v[104:105], 0, v[152:153]
	v_lshl_add_u64 v[106:107], v[110:111], 0, v[152:153]
	global_load_dwordx4 v[186:189], v[112:113], off offset:1024
	global_load_dwordx4 v[190:193], v[112:113], off offset:2048
	global_load_dwordx4 v[194:197], v[112:113], off offset:3072
	flat_load_dwordx4 v[102:105], v[112:113]
	s_nop 0
	global_load_dwordx4 v[198:201], v[106:107], off offset:1024
	global_load_dwordx4 v[202:205], v[106:107], off offset:2048
	global_load_dwordx4 v[224:227], v[106:107], off offset:3072
	flat_load_dwordx4 v[106:109], v[106:107]
	s_waitcnt vmcnt(0) lgkmcnt(0)
	v_pk_add_f32 v[108:109], v[108:109], 1.0 op_sel_hi:[1,0]
	v_pk_add_f32 v[106:107], v[106:107], 1.0 op_sel_hi:[1,0]
	v_pk_fma_f32 v[18:19], v[18:19], v[108:109], v[104:105]
	v_pk_fma_f32 v[16:17], v[16:17], v[106:107], v[102:103]
	s_nop 0
	v_cvt_pk_bf16_f32 v16, v16, v17
	v_cvt_pk_bf16_f32 v17, v18, v19
	flat_store_dwordx2 v[84:85], v[16:17]
	v_lshlrev_b32_e32 v16, 2, v68
	v_mov_b32_e32 v17, v153
	v_lshl_add_u64 v[18:19], v[110:111], 0, v[16:17]
	v_mov_b64_e32 v[102:103], v[186:187]
	v_mov_b64_e32 v[104:105], v[188:189]
	v_mov_b64_e32 v[106:107], v[198:199]
	v_mov_b64_e32 v[108:109], v[200:201]
	v_pk_add_f32 v[18:19], v[108:109], 1.0 op_sel_hi:[1,0]
	v_pk_add_f32 v[106:107], v[106:107], 1.0 op_sel_hi:[1,0]
	v_pk_fma_f32 v[14:15], v[14:15], v[18:19], v[104:105]
	v_pk_fma_f32 v[12:13], v[12:13], v[106:107], v[102:103]
	s_nop 0
	v_cvt_pk_bf16_f32 v12, v12, v13
	v_cvt_pk_bf16_f32 v13, v14, v15
	flat_store_dwordx2 v[84:85], v[12:13] offset:512
	v_lshlrev_b32_e32 v12, 2, v70
	v_mov_b32_e32 v13, v153
	v_lshl_add_u64 v[14:15], v[110:111], 0, v[12:13]
	v_mov_b64_e32 v[102:103], v[190:191]
	v_mov_b64_e32 v[104:105], v[192:193]
	v_mov_b64_e32 v[106:107], v[202:203]
	v_mov_b64_e32 v[108:109], v[204:205]
	v_pk_add_f32 v[14:15], v[108:109], 1.0 op_sel_hi:[1,0]
	v_pk_add_f32 v[18:19], v[106:107], 1.0 op_sel_hi:[1,0]
	v_pk_fma_f32 v[6:7], v[6:7], v[14:15], v[104:105]
	v_pk_fma_f32 v[4:5], v[4:5], v[18:19], v[102:103]
	s_nop 0
	v_cvt_pk_bf16_f32 v4, v4, v5
	v_cvt_pk_bf16_f32 v5, v6, v7
	flat_store_dwordx2 v[84:85], v[4:5] offset:1024
	v_lshlrev_b32_e32 v4, 2, v72
	v_mov_b32_e32 v5, v153
	v_lshl_add_u64 v[6:7], v[110:111], 0, v[4:5]
	v_mov_b64_e32 v[102:103], v[194:195]
	v_mov_b64_e32 v[104:105], v[196:197]
	v_mov_b64_e32 v[106:107], v[224:225]
	v_mov_b64_e32 v[108:109], v[226:227]
	v_pk_add_f32 v[6:7], v[108:109], 1.0 op_sel_hi:[1,0]
	v_pk_add_f32 v[14:15], v[106:107], 1.0 op_sel_hi:[1,0]
	v_pk_fma_f32 v[2:3], v[2:3], v[6:7], v[104:105]
	v_pk_fma_f32 v[0:1], v[0:1], v[14:15], v[102:103]
	s_nop 0
	v_cvt_pk_bf16_f32 v0, v0, v1
	v_cvt_pk_bf16_f32 v1, v2, v3
	flat_store_dwordx2 v[84:85], v[0:1] offset:1536
	v_lshl_add_u64 v[0:1], v[92:93], 0, s[2:3]
	v_mad_u64_u32 v[2:3], s[4:5], v0, s7, v[94:95]
	v_mad_i32_i24 v3, v1, s7, v3
	v_lshl_add_u64 v[0:1], v[2:3], 0, s[30:31]
	v_lshl_add_u64 v[2:3], v[2:3], 0, v[152:153]
	v_lshl_add_u64 v[6:7], v[0:1], 0, v[152:153]
	global_load_dwordx4 v[186:189], v[2:3], off offset:1024
	global_load_dwordx4 v[190:193], v[2:3], off offset:2048
	global_load_dwordx4 v[194:197], v[2:3], off offset:3072
	flat_load_dwordx4 v[102:105], v[2:3]
	global_load_dwordx4 v[198:201], v[6:7], off offset:1024
	global_load_dwordx4 v[202:205], v[6:7], off offset:2048
	global_load_dwordx4 v[224:227], v[6:7], off offset:3072
	flat_load_dwordx4 v[106:109], v[6:7]
	s_waitcnt vmcnt(0) lgkmcnt(0)
	v_pk_add_f32 v[6:7], v[108:109], 1.0 op_sel_hi:[1,0]
	v_pk_add_f32 v[14:15], v[106:107], 1.0 op_sel_hi:[1,0]
	v_pk_fma_f32 v[6:7], v[10:11], v[6:7], v[104:105]
	v_pk_fma_f32 v[8:9], v[8:9], v[14:15], v[102:103]
	v_lshl_add_u64 v[10:11], v[82:83], 0, v[96:97]
	v_cvt_pk_bf16_f32 v8, v8, v9
	v_cvt_pk_bf16_f32 v9, v6, v7
	flat_store_dwordx2 v[10:11], v[8:9]
	v_lshl_add_u64 v[14:15], v[0:1], 0, v[16:17]
	v_mov_b64_e32 v[6:7], v[186:187]
	v_mov_b64_e32 v[8:9], v[188:189]
	v_mov_b64_e32 v[102:103], v[198:199]
	v_mov_b64_e32 v[104:105], v[200:201]
	v_pk_add_f32 v[14:15], v[104:105], 1.0 op_sel_hi:[1,0]
	v_pk_add_f32 v[18:19], v[102:103], 1.0 op_sel_hi:[1,0]
	v_pk_fma_f32 v[8:9], v[22:23], v[14:15], v[8:9]
	v_pk_fma_f32 v[6:7], v[20:21], v[18:19], v[6:7]
	v_lshl_add_u64 v[14:15], v[0:1], 0, v[12:13]
	v_cvt_pk_bf16_f32 v6, v6, v7
	v_cvt_pk_bf16_f32 v7, v8, v9
	flat_store_dwordx2 v[10:11], v[6:7] offset:512
	v_mov_b64_e32 v[6:7], v[190:191]
	v_mov_b64_e32 v[8:9], v[192:193]
	v_lshl_add_u64 v[0:1], v[0:1], 0, v[4:5]
	v_mov_b64_e32 v[18:19], v[202:203]
	v_mov_b64_e32 v[20:21], v[204:205]
	v_pk_add_f32 v[14:15], v[20:21], 1.0 op_sel_hi:[1,0]
	v_pk_add_f32 v[18:19], v[18:19], 1.0 op_sel_hi:[1,0]
	v_pk_fma_f32 v[8:9], v[30:31], v[14:15], v[8:9]
	v_pk_fma_f32 v[6:7], v[28:29], v[18:19], v[6:7]
	s_nop 0
	v_cvt_pk_bf16_f32 v6, v6, v7
	v_cvt_pk_bf16_f32 v7, v8, v9
	flat_store_dwordx2 v[10:11], v[6:7] offset:1024
	v_mov_b64_e32 v[6:7], v[194:195]
	v_mov_b64_e32 v[8:9], v[196:197]
	s_nop 0
	v_mov_b64_e32 v[0:1], v[224:225]
	v_mov_b64_e32 v[2:3], v[226:227]
	v_pk_add_f32 v[2:3], v[2:3], 1.0 op_sel_hi:[1,0]
	v_pk_add_f32 v[0:1], v[0:1], 1.0 op_sel_hi:[1,0]
	v_pk_fma_f32 v[2:3], v[26:27], v[2:3], v[8:9]
	v_pk_fma_f32 v[0:1], v[24:25], v[0:1], v[6:7]
	s_nop 0
	v_cvt_pk_bf16_f32 v0, v0, v1
	v_cvt_pk_bf16_f32 v1, v2, v3
	flat_store_dwordx2 v[10:11], v[0:1] offset:1536
	v_lshl_add_u64 v[0:1], v[90:91], 0, s[2:3]
	v_mad_u64_u32 v[2:3], s[4:5], v0, s7, v[94:95]
	v_mad_i32_i24 v3, v1, s7, v3
	v_lshl_add_u64 v[0:1], v[2:3], 0, s[30:31]
	v_lshl_add_u64 v[2:3], v[2:3], 0, v[152:153]
	v_lshl_add_u64 v[10:11], v[0:1], 0, v[152:153]
	global_load_dwordx4 v[186:189], v[2:3], off offset:1024
	global_load_dwordx4 v[190:193], v[2:3], off offset:2048
	global_load_dwordx4 v[194:197], v[2:3], off offset:3072
	flat_load_dwordx4 v[6:9], v[2:3]
	global_load_dwordx4 v[198:201], v[10:11], off offset:1024
	global_load_dwordx4 v[202:205], v[10:11], off offset:2048
	global_load_dwordx4 v[224:227], v[10:11], off offset:3072
	flat_load_dwordx4 v[18:21], v[10:11]
	s_waitcnt vmcnt(0) lgkmcnt(0)
	v_pk_add_f32 v[10:11], v[20:21], 1.0 op_sel_hi:[1,0]
	v_pk_add_f32 v[14:15], v[18:19], 1.0 op_sel_hi:[1,0]
	v_pk_fma_f32 v[8:9], v[62:63], v[10:11], v[8:9]
	v_pk_fma_f32 v[6:7], v[60:61], v[14:15], v[6:7]
	v_lshl_add_u64 v[10:11], v[82:83], 0, v[100:101]
	v_cvt_pk_bf16_f32 v6, v6, v7
	v_cvt_pk_bf16_f32 v7, v8, v9
	flat_store_dwordx2 v[10:11], v[6:7]
	v_lshl_add_u64 v[14:15], v[0:1], 0, v[16:17]
	v_mov_b64_e32 v[6:7], v[186:187]
	v_mov_b64_e32 v[8:9], v[188:189]
	v_mov_b64_e32 v[18:19], v[198:199]
	v_mov_b64_e32 v[20:21], v[200:201]
	v_pk_add_f32 v[14:15], v[20:21], 1.0 op_sel_hi:[1,0]
	v_pk_add_f32 v[18:19], v[18:19], 1.0 op_sel_hi:[1,0]
	v_pk_fma_f32 v[8:9], v[58:59], v[14:15], v[8:9]
	v_pk_fma_f32 v[6:7], v[56:57], v[18:19], v[6:7]
	v_lshl_add_u64 v[14:15], v[0:1], 0, v[12:13]
	v_cvt_pk_bf16_f32 v6, v6, v7
	v_cvt_pk_bf16_f32 v7, v8, v9
	flat_store_dwordx2 v[10:11], v[6:7] offset:512
	v_mov_b64_e32 v[6:7], v[190:191]
	v_mov_b64_e32 v[8:9], v[192:193]
	v_lshl_add_u64 v[0:1], v[0:1], 0, v[4:5]
	v_mov_b64_e32 v[18:19], v[202:203]
	v_mov_b64_e32 v[20:21], v[204:205]
	v_pk_add_f32 v[14:15], v[20:21], 1.0 op_sel_hi:[1,0]
	v_pk_add_f32 v[18:19], v[18:19], 1.0 op_sel_hi:[1,0]
	v_pk_fma_f32 v[8:9], v[54:55], v[14:15], v[8:9]
	v_pk_fma_f32 v[6:7], v[52:53], v[18:19], v[6:7]
	s_nop 0
	v_cvt_pk_bf16_f32 v6, v6, v7
	v_cvt_pk_bf16_f32 v7, v8, v9
	flat_store_dwordx2 v[10:11], v[6:7] offset:1024
	v_mov_b64_e32 v[6:7], v[194:195]
	v_mov_b64_e32 v[8:9], v[196:197]
	s_nop 0
	v_mov_b64_e32 v[0:1], v[224:225]
	v_mov_b64_e32 v[2:3], v[226:227]
	v_pk_add_f32 v[2:3], v[2:3], 1.0 op_sel_hi:[1,0]
	v_pk_add_f32 v[0:1], v[0:1], 1.0 op_sel_hi:[1,0]
	v_pk_fma_f32 v[2:3], v[50:51], v[2:3], v[8:9]
	v_pk_fma_f32 v[0:1], v[48:49], v[0:1], v[6:7]
	s_nop 0
	v_cvt_pk_bf16_f32 v0, v0, v1
	v_cvt_pk_bf16_f32 v1, v2, v3
	flat_store_dwordx2 v[10:11], v[0:1] offset:1536
	v_lshl_add_u64 v[0:1], v[88:89], 0, s[2:3]
	v_mad_u64_u32 v[2:3], s[4:5], v0, s7, v[94:95]
	v_mad_i32_i24 v3, v1, s7, v3
	v_lshl_add_u64 v[0:1], v[2:3], 0, s[30:31]
	v_lshl_add_u64 v[2:3], v[2:3], 0, v[152:153]
	v_lshl_add_u64 v[10:11], v[0:1], 0, v[152:153]
	global_load_dwordx4 v[186:189], v[2:3], off offset:1024
	global_load_dwordx4 v[190:193], v[2:3], off offset:2048
	global_load_dwordx4 v[194:197], v[2:3], off offset:3072
	flat_load_dwordx4 v[6:9], v[2:3]
	global_load_dwordx4 v[198:201], v[10:11], off offset:1024
	global_load_dwordx4 v[202:205], v[10:11], off offset:2048
	global_load_dwordx4 v[224:227], v[10:11], off offset:3072
	flat_load_dwordx4 v[18:21], v[10:11]
	s_waitcnt vmcnt(0) lgkmcnt(0)
	v_pk_add_f32 v[10:11], v[20:21], 1.0 op_sel_hi:[1,0]
	v_pk_add_f32 v[14:15], v[18:19], 1.0 op_sel_hi:[1,0]
	v_pk_fma_f32 v[8:9], v[46:47], v[10:11], v[8:9]
	v_pk_fma_f32 v[6:7], v[44:45], v[14:15], v[6:7]
	v_lshl_add_u64 v[18:19], v[82:83], 0, v[98:99]
	v_cvt_pk_bf16_f32 v6, v6, v7
	v_cvt_pk_bf16_f32 v7, v8, v9
	flat_store_dwordx2 v[18:19], v[6:7]
	v_lshl_add_u64 v[10:11], v[0:1], 0, v[16:17]
	v_mov_b64_e32 v[6:7], v[186:187]
	v_mov_b64_e32 v[8:9], v[188:189]
	v_mov_b64_e32 v[14:15], v[198:199]
	v_mov_b64_e32 v[16:17], v[200:201]
	v_pk_add_f32 v[10:11], v[16:17], 1.0 op_sel_hi:[1,0]
	v_pk_add_f32 v[14:15], v[14:15], 1.0 op_sel_hi:[1,0]
	v_pk_fma_f32 v[8:9], v[42:43], v[10:11], v[8:9]
	v_pk_fma_f32 v[6:7], v[40:41], v[14:15], v[6:7]
	v_lshl_add_u64 v[10:11], v[0:1], 0, v[12:13]
	v_cvt_pk_bf16_f32 v6, v6, v7
	v_cvt_pk_bf16_f32 v7, v8, v9
	flat_store_dwordx2 v[18:19], v[6:7] offset:512
	v_mov_b64_e32 v[6:7], v[190:191]
	v_mov_b64_e32 v[8:9], v[192:193]
	v_lshl_add_u64 v[0:1], v[0:1], 0, v[4:5]
	v_mov_b64_e32 v[10:11], v[202:203]
	v_mov_b64_e32 v[12:13], v[204:205]
	v_pk_add_f32 v[12:13], v[12:13], 1.0 op_sel_hi:[1,0]
	v_pk_add_f32 v[10:11], v[10:11], 1.0 op_sel_hi:[1,0]
	v_pk_fma_f32 v[8:9], v[38:39], v[12:13], v[8:9]
	v_pk_fma_f32 v[6:7], v[36:37], v[10:11], v[6:7]
	s_nop 0
	v_cvt_pk_bf16_f32 v6, v6, v7
	v_cvt_pk_bf16_f32 v7, v8, v9
	flat_store_dwordx2 v[18:19], v[6:7] offset:1024
	v_mov_b64_e32 v[6:7], v[194:195]
	v_mov_b64_e32 v[8:9], v[196:197]
	s_nop 0
	v_mov_b64_e32 v[0:1], v[224:225]
	v_mov_b64_e32 v[2:3], v[226:227]
	v_pk_add_f32 v[2:3], v[2:3], 1.0 op_sel_hi:[1,0]
	v_pk_add_f32 v[0:1], v[0:1], 1.0 op_sel_hi:[1,0]
	v_pk_fma_f32 v[2:3], v[34:35], v[2:3], v[8:9]
	v_pk_fma_f32 v[0:1], v[32:33], v[0:1], v[6:7]
	s_nop 0
	v_cvt_pk_bf16_f32 v0, v0, v1
	v_cvt_pk_bf16_f32 v1, v2, v3
	flat_store_dwordx2 v[18:19], v[0:1] offset:1536
	s_branch .LBB0_224
